# GEMM 256x128 mainloops: next-tile ds_write pass moved from the serialized tail into the MFMA stream (lgkmcnt ladder re-derived)
# speedup vs baseline: 1.0936x; 1.0009x over previous
.LBB0_208:
	s_add_i32 s27, s5, 64
	s_min_u32 s30, s27, 0x3e0
	s_lshl_b32 s30, s30, 1
	v_lshl_add_u64 v[180:181], v[154:155], 0, s[30:31]
	v_lshl_add_u64 v[184:185], v[158:159], 0, s[30:31]
	v_lshl_add_u64 v[188:189], v[160:161], 0, s[30:31]
	v_lshl_add_u64 v[192:193], v[162:163], 0, s[30:31]
	v_lshl_add_u64 v[196:197], v[156:157], 0, s[30:31]
	v_lshl_add_u64 v[200:201], v[164:165], 0, s[30:31]
	global_load_dwordx4 v[180:183], v[180:181], off
	ds_read_b128 v[204:207], v178 offset:32768
	global_load_dwordx4 v[184:187], v[184:185], off
	ds_read_b128 v[208:211], v178 offset:33792
	global_load_dwordx4 v[188:191], v[188:189], off
	ds_read_b128 v[212:215], v178 offset:34816
	global_load_dwordx4 v[192:195], v[192:193], off
	ds_read_b128 v[216:219], v178 offset:35840
	global_load_dwordx4 v[196:199], v[196:197], off
	ds_read_b128 v[222:225], v176
	global_load_dwordx4 v[200:203], v[200:201], off
	ds_read_b128 v[226:229], v176 offset:1024
	ds_read_b128 v[230:233], v176 offset:2048
	ds_read_b128 v[234:237], v176 offset:3072
	ds_read_b128 v[238:241], v176 offset:4096
	ds_read_b128 v[242:245], v176 offset:5120
	ds_read_b128 v[246:249], v176 offset:6144
	ds_read_b128 v[250:253], v176 offset:7168
	s_setprio 1
	s_waitcnt lgkmcnt(7)
	v_mfma_f32_16x16x32_bf16 v[124:127], v[222:225], v[204:207], v[124:127]
	v_mfma_f32_16x16x32_bf16 v[120:123], v[222:225], v[208:211], v[120:123]
	v_mfma_f32_16x16x32_bf16 v[60:63], v[222:225], v[212:215], v[60:63]
	v_mfma_f32_16x16x32_bf16 v[56:59], v[222:225], v[216:219], v[56:59]
	s_waitcnt vmcnt(11)
	ds_write_b128 v152, v[128:131] offset:16384
	s_waitcnt lgkmcnt(7)
	v_mfma_f32_16x16x32_bf16 v[116:119], v[226:229], v[204:207], v[116:119]
	v_mfma_f32_16x16x32_bf16 v[112:115], v[226:229], v[208:211], v[112:115]
	v_mfma_f32_16x16x32_bf16 v[52:55], v[226:229], v[212:215], v[52:55]
	v_mfma_f32_16x16x32_bf16 v[48:51], v[226:229], v[216:219], v[48:51]
	s_waitcnt vmcnt(9)
	ds_write_b128 v152, v[136:139] offset:20480
	s_waitcnt lgkmcnt(7)
	v_mfma_f32_16x16x32_bf16 v[108:111], v[230:233], v[204:207], v[108:111]
	v_mfma_f32_16x16x32_bf16 v[104:107], v[230:233], v[208:211], v[104:107]
	v_mfma_f32_16x16x32_bf16 v[44:47], v[230:233], v[212:215], v[44:47]
	v_mfma_f32_16x16x32_bf16 v[40:43], v[230:233], v[216:219], v[40:43]
	s_waitcnt vmcnt(8)
	ds_write_b128 v152, v[140:143] offset:24576
	s_waitcnt lgkmcnt(7)
	v_mfma_f32_16x16x32_bf16 v[100:103], v[234:237], v[204:207], v[100:103]
	v_mfma_f32_16x16x32_bf16 v[96:99], v[234:237], v[208:211], v[96:99]
	v_mfma_f32_16x16x32_bf16 v[36:39], v[234:237], v[212:215], v[36:39]
	v_mfma_f32_16x16x32_bf16 v[32:35], v[234:237], v[216:219], v[32:35]
	s_waitcnt vmcnt(7)
	ds_write_b128 v152, v[144:147] offset:28672
	s_waitcnt lgkmcnt(7)
	v_mfma_f32_16x16x32_bf16 v[92:95], v[238:241], v[204:207], v[92:95]
	v_mfma_f32_16x16x32_bf16 v[88:91], v[238:241], v[208:211], v[88:91]
	v_mfma_f32_16x16x32_bf16 v[28:31], v[238:241], v[212:215], v[28:31]
	v_mfma_f32_16x16x32_bf16 v[24:27], v[238:241], v[216:219], v[24:27]
	s_waitcnt vmcnt(7)
	ds_write_b128 v152, v[132:135] offset:40960
	s_waitcnt lgkmcnt(7)
	v_mfma_f32_16x16x32_bf16 v[84:87], v[242:245], v[204:207], v[84:87]
	v_mfma_f32_16x16x32_bf16 v[80:83], v[242:245], v[208:211], v[80:83]
	v_mfma_f32_16x16x32_bf16 v[20:23], v[242:245], v[212:215], v[20:23]
	v_mfma_f32_16x16x32_bf16 v[16:19], v[242:245], v[216:219], v[16:19]
	s_waitcnt vmcnt(6)
	ds_write_b128 v152, v[148:151] offset:45056
	s_waitcnt lgkmcnt(7)
	v_mfma_f32_16x16x32_bf16 v[76:79], v[246:249], v[204:207], v[76:79]
	v_mfma_f32_16x16x32_bf16 v[72:75], v[246:249], v[208:211], v[72:75]
	v_mfma_f32_16x16x32_bf16 v[12:15], v[246:249], v[212:215], v[12:15]
	v_mfma_f32_16x16x32_bf16 v[8:11], v[246:249], v[216:219], v[8:11]
	s_waitcnt lgkmcnt(6)
	v_mfma_f32_16x16x32_bf16 v[68:71], v[250:253], v[204:207], v[68:71]
	v_mfma_f32_16x16x32_bf16 v[64:67], v[250:253], v[208:211], v[64:67]
	v_mfma_f32_16x16x32_bf16 v[4:7], v[250:253], v[212:215], v[4:7]
	v_mfma_f32_16x16x32_bf16 v[0:3], v[250:253], v[216:219], v[0:3]
	s_setprio 0
	s_min_u32 s5, s5, 0x380
	s_lshl_b32 s30, s5, 1
	s_mov_b32 s53, s31
	s_add_i32 s52, s30, 0xc0
	v_lshl_add_u64 v[128:129], v[154:155], 0, s[30:31]
	v_lshl_add_u64 v[132:133], v[156:157], 0, s[30:31]
	v_lshl_add_u64 v[136:137], v[158:159], 0, s[52:53]
	v_lshl_add_u64 v[140:141], v[160:161], 0, s[52:53]
	v_lshl_add_u64 v[144:145], v[162:163], 0, s[52:53]
	v_lshl_add_u64 v[148:149], v[164:165], 0, s[52:53]
	s_waitcnt lgkmcnt(0)
	s_barrier
	global_load_dwordx4 v[128:131], v[128:129], off offset:192
	ds_read_b128 v[204:207], v175 offset:40960
	global_load_dwordx4 v[132:135], v[132:133], off offset:192
	ds_read_b128 v[208:211], v175 offset:41984
	global_load_dwordx4 v[136:139], v[136:137], off
	ds_read_b128 v[212:215], v175 offset:43008
	global_load_dwordx4 v[140:143], v[140:141], off
	ds_read_b128 v[216:219], v175 offset:44032
	global_load_dwordx4 v[144:147], v[144:145], off
	ds_read_b128 v[222:225], v177
	global_load_dwordx4 v[148:151], v[148:149], off
	ds_read_b128 v[226:229], v177 offset:1024
	ds_read_b128 v[230:233], v177 offset:2048
	ds_read_b128 v[234:237], v177 offset:3072
	ds_read_b128 v[238:241], v177 offset:4096
	ds_read_b128 v[242:245], v177 offset:5120
	ds_read_b128 v[246:249], v177 offset:6144
	ds_read_b128 v[250:253], v177 offset:7168
	s_setprio 1
	s_waitcnt lgkmcnt(7)
	v_mfma_f32_16x16x32_bf16 v[124:127], v[222:225], v[204:207], v[124:127]
	v_mfma_f32_16x16x32_bf16 v[120:123], v[222:225], v[208:211], v[120:123]
	v_mfma_f32_16x16x32_bf16 v[60:63], v[222:225], v[212:215], v[60:63]
	v_mfma_f32_16x16x32_bf16 v[56:59], v[222:225], v[216:219], v[56:59]
	s_waitcnt vmcnt(11)
	ds_write_b128 v152, v[180:183]
	s_waitcnt lgkmcnt(7)
	v_mfma_f32_16x16x32_bf16 v[116:119], v[226:229], v[204:207], v[116:119]
	v_mfma_f32_16x16x32_bf16 v[112:115], v[226:229], v[208:211], v[112:115]
	v_mfma_f32_16x16x32_bf16 v[52:55], v[226:229], v[212:215], v[52:55]
	v_mfma_f32_16x16x32_bf16 v[48:51], v[226:229], v[216:219], v[48:51]
	s_waitcnt vmcnt(10)
	ds_write_b128 v152, v[184:187] offset:4096
	s_waitcnt lgkmcnt(7)
	v_mfma_f32_16x16x32_bf16 v[108:111], v[230:233], v[204:207], v[108:111]
	v_mfma_f32_16x16x32_bf16 v[104:107], v[230:233], v[208:211], v[104:107]
	v_mfma_f32_16x16x32_bf16 v[44:47], v[230:233], v[212:215], v[44:47]
	v_mfma_f32_16x16x32_bf16 v[40:43], v[230:233], v[216:219], v[40:43]
	s_waitcnt vmcnt(9)
	ds_write_b128 v152, v[188:191] offset:8192
	s_waitcnt lgkmcnt(7)
	v_mfma_f32_16x16x32_bf16 v[100:103], v[234:237], v[204:207], v[100:103]
	v_mfma_f32_16x16x32_bf16 v[96:99], v[234:237], v[208:211], v[96:99]
	v_mfma_f32_16x16x32_bf16 v[36:39], v[234:237], v[212:215], v[36:39]
	v_mfma_f32_16x16x32_bf16 v[32:35], v[234:237], v[216:219], v[32:35]
	s_waitcnt vmcnt(8)
	ds_write_b128 v152, v[192:195] offset:12288
	s_waitcnt lgkmcnt(7)
	v_mfma_f32_16x16x32_bf16 v[92:95], v[238:241], v[204:207], v[92:95]
	v_mfma_f32_16x16x32_bf16 v[88:91], v[238:241], v[208:211], v[88:91]
	v_mfma_f32_16x16x32_bf16 v[28:31], v[238:241], v[212:215], v[28:31]
	v_mfma_f32_16x16x32_bf16 v[24:27], v[238:241], v[216:219], v[24:27]
	s_waitcnt vmcnt(7)
	ds_write_b128 v152, v[196:199] offset:32768
	s_waitcnt lgkmcnt(7)
	v_mfma_f32_16x16x32_bf16 v[84:87], v[242:245], v[204:207], v[84:87]
	v_mfma_f32_16x16x32_bf16 v[80:83], v[242:245], v[208:211], v[80:83]
	v_mfma_f32_16x16x32_bf16 v[20:23], v[242:245], v[212:215], v[20:23]
	v_mfma_f32_16x16x32_bf16 v[16:19], v[242:245], v[216:219], v[16:19]
	s_waitcnt vmcnt(6)
	ds_write_b128 v152, v[200:203] offset:36864
	s_waitcnt lgkmcnt(7)
	v_mfma_f32_16x16x32_bf16 v[76:79], v[246:249], v[204:207], v[76:79]
	v_mfma_f32_16x16x32_bf16 v[72:75], v[246:249], v[208:211], v[72:75]
	v_mfma_f32_16x16x32_bf16 v[12:15], v[246:249], v[212:215], v[12:15]
	v_mfma_f32_16x16x32_bf16 v[8:11], v[246:249], v[216:219], v[8:11]
	s_waitcnt lgkmcnt(6)
	v_mfma_f32_16x16x32_bf16 v[68:71], v[250:253], v[204:207], v[68:71]
	v_mfma_f32_16x16x32_bf16 v[64:67], v[250:253], v[208:211], v[64:67]
	v_mfma_f32_16x16x32_bf16 v[4:7], v[250:253], v[212:215], v[4:7]
	v_mfma_f32_16x16x32_bf16 v[0:3], v[250:253], v[216:219], v[0:3]
	s_setprio 0
	s_add_i32 s1, s1, 2
	s_cmp_lt_u32 s1, 30
	s_mov_b32 s5, s27
	s_waitcnt lgkmcnt(0)
	s_barrier
	s_cbranch_scc1 .LBB0_208
	s_waitcnt vmcnt(5)
	v_mov_b32_e32 v128, v220
	s_cmp_gt_i32 s26, 15
	v_and_b32_e32 v158, 15, v128
	v_and_b32_e32 v160, 64, v128
	v_and_b32_e32 v129, 0xffffff80, v128
	v_lshrrev_b32_e32 v128, 2, v128
	v_add_u32_e32 v130, s4, v129
	v_and_b32_e32 v159, 12, v128
	s_waitcnt vmcnt(3)
	v_or_b32_e32 v136, v130, v159
	v_ashrrev_i32_e32 v128, 14, v130
	s_waitcnt vmcnt(0)
	v_or_b32_e32 v150, 16, v136
	v_or_b32_e32 v148, 32, v136
	v_or_b32_e32 v146, 48, v136
	v_or_b32_e32 v142, 64, v136
	v_or_b32_e32 v140, 0x50, v136
	v_or_b32_e32 v138, 0x60, v136
	v_or_b32_e32 v134, 0x70, v136
	s_mov_b64 s[4:5], -1
	v_ashrrev_i32_e32 v137, 31, v136
	v_lshlrev_b32_e32 v132, 1, v159
	v_mov_b32_e32 v250, s0
	v_and_b32_e32 v250, 0x80, v250
	v_add_u32_e32 v250, v250, v160
	v_mul_u32_u24_e32 v250, 30, v250
	v_lshrrev_b32_e32 v251, 3, v158
	v_mul_u32_u24_e32 v251, 0xf0, v251
	v_add_u32_e32 v250, v250, v251
	v_lshrrev_b32_e32 v251, 2, v159
	v_mul_u32_u24_e32 v251, 0x7c0, v251
	v_sub_u32_e32 v250, v250, v251
	v_ashrrev_i32_e32 v251, 31, v250
	v_and_b32_e32 v252, 8, v159
	v_lshlrev_b32_e32 v252, 5, v252
	v_and_b32_e32 v253, 4, v159
	v_lshl_or_b32 v252, v253, 1, v252
	v_lshl_or_b32 v252, v158, 4, v252
	v_mov_b32_e32 v253, 0
	v_ashrrev_i32_e32 v129, 31, v128
	v_ashrrev_i32_e32 v151, 31, v150
	v_ashrrev_i32_e32 v149, 31, v148
	v_ashrrev_i32_e32 v147, 31, v146
	v_ashrrev_i32_e32 v143, 31, v142
	v_ashrrev_i32_e32 v141, 31, v140
	v_ashrrev_i32_e32 v139, 31, v138
	v_ashrrev_i32_e32 v135, 31, v134
	s_cbranch_scc0 .LBB0_211
	v_lshl_add_u64 v[144:145], v[136:137], 2, s[8:9]
	global_load_dwordx4 v[162:165], v[144:145], off
	s_add_i32 s1, s0, 0xfffff800
	s_and_b32 s5, s0, 0x180
	s_ashr_i32 s4, s1, 9
	v_or_b32_e32 v154, s5, v160
	s_ashr_i32 s5, s4, 31
	v_lshlrev_b64 v[144:145], 9, v[128:129]
	s_lshl_b64 s[4:5], s[4:5], 7
	v_lshrrev_b32_e32 v152, 7, v130
	v_lshl_add_u64 v[130:131], v[144:145], 0, s[4:5]
	v_and_or_b32 v130, v152, s38, v130
	v_lshlrev_b64 v[130:131], 16, v[130:131]
	v_mov_b32_e32 v133, v153
	v_lshl_or_b32 v130, v154, 7, v130
	v_lshl_add_u64 v[178:179], s[12:13], 0, v[252:253]
	v_mov_b32_e32 v145, v131
	v_mov_b32_e32 v181, v131
	v_lshlrev_b64 v[156:157], 1, v[130:131]
	v_or_b32_e32 v144, 0x800, v130
	v_or_b32_e32 v180, 0x1000, v130
	v_or_b32_e32 v130, 0x1800, v130
	v_lshl_add_u64 v[182:183], v[178:179], 0, v[156:157]
	v_lshlrev_b64 v[154:155], 1, v[144:145]
	v_lshlrev_b64 v[144:145], 1, v[180:181]
	v_lshlrev_b64 v[130:131], 1, v[130:131]
	v_lshl_add_u64 v[176:177], v[150:151], 2, s[8:9]
	v_lshl_add_u64 v[180:181], v[178:179], 0, v[154:155]
	v_lshl_add_u64 v[184:185], v[178:179], 0, v[144:145]
	v_lshl_add_u64 v[178:179], v[178:179], 0, v[130:131]
	s_waitcnt vmcnt(0)
	v_mul_f32_e32 v133, v124, v162
	v_mul_f32_e32 v152, v125, v163
	v_mul_f32_e32 v161, v126, v164
	v_mul_f32_e32 v175, v127, v165
	v_mul_f32_e32 v186, v120, v162
	v_mul_f32_e32 v187, v121, v163
	v_mul_f32_e32 v188, v122, v164
	v_mul_f32_e32 v189, v123, v165
	v_mul_f32_e32 v190, v60, v162
	v_mul_f32_e32 v191, v61, v163
	v_mul_f32_e32 v194, v56, v162
	v_mul_f32_e32 v195, v57, v163
	v_cvt_pk_bf16_f32 v162, v133, v152
	v_cvt_pk_bf16_f32 v163, v161, v175
	v_mul_f32_e32 v192, v62, v164
	v_mul_f32_e32 v193, v63, v165
	v_mul_f32_e32 v196, v58, v164
	v_mul_f32_e32 v197, v59, v165
	v_cvt_pk_bf16_f32 v164, v186, v187
	v_cvt_pk_bf16_f32 v165, v188, v189
	v_cvt_pk_bf16_f32 v186, v190, v191
	v_cvt_pk_bf16_f32 v187, v192, v193
	v_cvt_pk_bf16_f32 v188, v194, v195
	v_cvt_pk_bf16_f32 v189, v196, v197
	global_store_dwordx2 v[182:183], v[162:163], off
	global_store_dwordx2 v[180:181], v[164:165], off
	global_store_dwordx2 v[184:185], v[186:187], off
	global_store_dwordx2 v[178:179], v[188:189], off
	global_load_dwordx4 v[162:165], v[176:177], off
	v_bitop3_b32 v133, v136, 28, 16 bitop3:0xc8
	v_lshlrev_b32_e32 v152, 1, v133
	v_lshl_add_u64 v[178:179], s[12:13], 0, v[252:253]
	v_lshl_add_u64 v[180:181], v[178:179], 0, v[156:157]
	v_lshl_add_u64 v[176:177], v[148:149], 2, s[8:9]
	v_lshl_add_u64 v[182:183], v[178:179], 0, v[154:155]
	v_lshl_add_u64 v[184:185], v[178:179], 0, v[144:145]
	v_lshl_add_u64 v[178:179], v[178:179], 0, v[130:131]
	s_waitcnt vmcnt(0)
	v_mul_f32_e32 v133, v116, v162
	v_mul_f32_e32 v152, v117, v163
	v_mul_f32_e32 v161, v118, v164
	v_mul_f32_e32 v175, v119, v165
	v_mul_f32_e32 v186, v112, v162
	v_mul_f32_e32 v187, v113, v163
	v_mul_f32_e32 v188, v114, v164
	v_mul_f32_e32 v189, v115, v165
	v_mul_f32_e32 v190, v52, v162
	v_mul_f32_e32 v191, v53, v163
	v_mul_f32_e32 v194, v48, v162
	v_mul_f32_e32 v195, v49, v163
	v_cvt_pk_bf16_f32 v162, v133, v152
	v_cvt_pk_bf16_f32 v163, v161, v175
	v_mul_f32_e32 v192, v54, v164
	v_mul_f32_e32 v193, v55, v165
	v_mul_f32_e32 v196, v50, v164
	v_mul_f32_e32 v197, v51, v165
	v_cvt_pk_bf16_f32 v164, v186, v187
	v_cvt_pk_bf16_f32 v165, v188, v189
	v_cvt_pk_bf16_f32 v186, v190, v191
	v_cvt_pk_bf16_f32 v187, v192, v193
	v_cvt_pk_bf16_f32 v188, v194, v195
	v_cvt_pk_bf16_f32 v189, v196, v197
	global_store_dwordx2 v[180:181], v[162:163], off offset:512
	global_store_dwordx2 v[182:183], v[164:165], off offset:512
	global_store_dwordx2 v[184:185], v[186:187], off offset:512
	global_store_dwordx2 v[178:179], v[188:189], off offset:512
	global_load_dwordx4 v[162:165], v[176:177], off
	v_bitop3_b32 v133, v136, 44, 32 bitop3:0xc8
	v_lshlrev_b32_e32 v152, 1, v133
	v_lshl_add_u64 v[178:179], s[12:13], 0, v[252:253]
	v_lshl_add_u64 v[180:181], v[178:179], 0, v[156:157]
	v_lshl_add_u64 v[176:177], v[146:147], 2, s[8:9]
	v_lshl_add_u64 v[182:183], v[178:179], 0, v[154:155]
	v_lshl_add_u64 v[184:185], v[178:179], 0, v[144:145]
	v_lshl_add_u64 v[178:179], v[178:179], 0, v[130:131]
	s_waitcnt vmcnt(0)
	v_mul_f32_e32 v133, v108, v162
	v_mul_f32_e32 v152, v109, v163
	v_mul_f32_e32 v161, v110, v164
	v_mul_f32_e32 v175, v111, v165
	v_mul_f32_e32 v186, v104, v162
	v_mul_f32_e32 v187, v105, v163
	v_mul_f32_e32 v188, v106, v164
	v_mul_f32_e32 v189, v107, v165
	v_mul_f32_e32 v190, v44, v162
	v_mul_f32_e32 v191, v45, v163
	v_mul_f32_e32 v194, v40, v162
	v_mul_f32_e32 v195, v41, v163
	v_cvt_pk_bf16_f32 v162, v133, v152
	v_cvt_pk_bf16_f32 v163, v161, v175
	v_mul_f32_e32 v192, v46, v164
	v_mul_f32_e32 v193, v47, v165
	v_mul_f32_e32 v196, v42, v164
	v_mul_f32_e32 v197, v43, v165
	v_cvt_pk_bf16_f32 v164, v186, v187
	v_cvt_pk_bf16_f32 v165, v188, v189
	v_cvt_pk_bf16_f32 v186, v190, v191
	v_cvt_pk_bf16_f32 v187, v192, v193
	v_cvt_pk_bf16_f32 v188, v194, v195
	v_cvt_pk_bf16_f32 v189, v196, v197
	global_store_dwordx2 v[180:181], v[162:163], off offset:1024
	global_store_dwordx2 v[182:183], v[164:165], off offset:1024
	global_store_dwordx2 v[184:185], v[186:187], off offset:1024
	global_store_dwordx2 v[178:179], v[188:189], off offset:1024
	global_load_dwordx4 v[162:165], v[176:177], off
	v_bitop3_b32 v133, v136, 60, 48 bitop3:0xc8
	v_lshlrev_b32_e32 v152, 1, v133
	v_lshl_add_u64 v[178:179], s[12:13], 0, v[252:253]
	v_lshl_add_u64 v[180:181], v[178:179], 0, v[156:157]
	v_lshl_add_u64 v[176:177], v[142:143], 2, s[8:9]
	v_lshl_add_u64 v[182:183], v[178:179], 0, v[154:155]
	v_lshl_add_u64 v[184:185], v[178:179], 0, v[144:145]
	v_lshl_add_u64 v[178:179], v[178:179], 0, v[130:131]
	s_waitcnt vmcnt(0)
	v_mul_f32_e32 v133, v100, v162
	v_mul_f32_e32 v152, v101, v163
	v_mul_f32_e32 v161, v102, v164
	v_mul_f32_e32 v175, v103, v165
	v_mul_f32_e32 v186, v96, v162
	v_mul_f32_e32 v187, v97, v163
	v_mul_f32_e32 v188, v98, v164
	v_mul_f32_e32 v189, v99, v165
	v_mul_f32_e32 v190, v36, v162
	v_mul_f32_e32 v191, v37, v163
	v_mul_f32_e32 v194, v32, v162
	v_mul_f32_e32 v195, v33, v163
	v_cvt_pk_bf16_f32 v162, v133, v152
	v_cvt_pk_bf16_f32 v163, v161, v175
	v_mul_f32_e32 v192, v38, v164
	v_mul_f32_e32 v193, v39, v165
	v_mul_f32_e32 v196, v34, v164
	v_mul_f32_e32 v197, v35, v165
	v_cvt_pk_bf16_f32 v164, v186, v187
	v_cvt_pk_bf16_f32 v165, v188, v189
	v_cvt_pk_bf16_f32 v186, v190, v191
	v_cvt_pk_bf16_f32 v187, v192, v193
	v_cvt_pk_bf16_f32 v188, v194, v195
	v_cvt_pk_bf16_f32 v189, v196, v197
	global_store_dwordx2 v[180:181], v[162:163], off offset:1536
	global_store_dwordx2 v[182:183], v[164:165], off offset:1536
	global_store_dwordx2 v[184:185], v[186:187], off offset:1536
	global_store_dwordx2 v[178:179], v[188:189], off offset:1536
	global_load_dwordx4 v[162:165], v[176:177], off
	v_bitop3_b32 v133, v136, s39, 64 bitop3:0xc8
	v_lshlrev_b32_e32 v152, 1, v133
	v_lshl_add_u64 v[178:179], s[12:13], 0, v[252:253]
	v_lshl_add_u64 v[180:181], v[178:179], 0, v[156:157]
	v_lshl_add_u64 v[176:177], v[140:141], 2, s[8:9]
	v_lshl_add_u64 v[182:183], v[178:179], 0, v[154:155]
	v_lshl_add_u64 v[184:185], v[178:179], 0, v[144:145]
	v_lshl_add_u64 v[178:179], v[178:179], 0, v[130:131]
	s_waitcnt vmcnt(0)
	v_mul_f32_e32 v133, v92, v162
	v_mul_f32_e32 v152, v93, v163
	v_mul_f32_e32 v161, v94, v164
	v_mul_f32_e32 v175, v95, v165
	v_mul_f32_e32 v186, v88, v162
	v_mul_f32_e32 v187, v89, v163
	v_mul_f32_e32 v188, v90, v164
	v_mul_f32_e32 v189, v91, v165
	v_mul_f32_e32 v190, v28, v162
	v_mul_f32_e32 v191, v29, v163
	v_mul_f32_e32 v194, v24, v162
	v_mul_f32_e32 v195, v25, v163
	v_cvt_pk_bf16_f32 v162, v133, v152
	v_cvt_pk_bf16_f32 v163, v161, v175
	v_mul_f32_e32 v192, v30, v164
	v_mul_f32_e32 v193, v31, v165
	v_mul_f32_e32 v196, v26, v164
	v_mul_f32_e32 v197, v27, v165
	v_cvt_pk_bf16_f32 v164, v186, v187
	v_cvt_pk_bf16_f32 v165, v188, v189
	v_cvt_pk_bf16_f32 v186, v190, v191
	v_cvt_pk_bf16_f32 v187, v192, v193
	v_cvt_pk_bf16_f32 v188, v194, v195
	v_cvt_pk_bf16_f32 v189, v196, v197
	global_store_dwordx2 v[180:181], v[162:163], off offset:2048
	global_store_dwordx2 v[182:183], v[164:165], off offset:2048
	global_store_dwordx2 v[184:185], v[186:187], off offset:2048
	global_store_dwordx2 v[178:179], v[188:189], off offset:2048
	global_load_dwordx4 v[162:165], v[176:177], off
	v_bitop3_b32 v133, v136, s40, v166 bitop3:0xc8
	v_lshlrev_b32_e32 v152, 1, v133
	v_lshl_add_u64 v[178:179], s[12:13], 0, v[252:253]
	v_lshl_add_u64 v[180:181], v[178:179], 0, v[156:157]
	v_lshl_add_u64 v[176:177], v[138:139], 2, s[8:9]
	v_lshl_add_u64 v[182:183], v[178:179], 0, v[154:155]
	v_lshl_add_u64 v[184:185], v[178:179], 0, v[144:145]
	v_lshl_add_u64 v[178:179], v[178:179], 0, v[130:131]
	s_waitcnt vmcnt(0)
	v_mul_f32_e32 v133, v84, v162
	v_mul_f32_e32 v152, v85, v163
	v_mul_f32_e32 v161, v86, v164
	v_mul_f32_e32 v175, v87, v165
	v_mul_f32_e32 v186, v80, v162
	v_mul_f32_e32 v187, v81, v163
	v_mul_f32_e32 v188, v82, v164
	v_mul_f32_e32 v189, v83, v165
	v_mul_f32_e32 v190, v20, v162
	v_mul_f32_e32 v191, v21, v163
	v_mul_f32_e32 v194, v16, v162
	v_mul_f32_e32 v195, v17, v163
	v_cvt_pk_bf16_f32 v162, v133, v152
	v_cvt_pk_bf16_f32 v163, v161, v175
	v_mul_f32_e32 v192, v22, v164
	v_mul_f32_e32 v193, v23, v165
	v_mul_f32_e32 v196, v18, v164
	v_mul_f32_e32 v197, v19, v165
	v_cvt_pk_bf16_f32 v164, v186, v187
	v_cvt_pk_bf16_f32 v165, v188, v189
	v_cvt_pk_bf16_f32 v186, v190, v191
	v_cvt_pk_bf16_f32 v187, v192, v193
	v_cvt_pk_bf16_f32 v188, v194, v195
	v_cvt_pk_bf16_f32 v189, v196, v197
	global_store_dwordx2 v[180:181], v[162:163], off offset:2560
	global_store_dwordx2 v[182:183], v[164:165], off offset:2560
	global_store_dwordx2 v[184:185], v[186:187], off offset:2560
	global_store_dwordx2 v[178:179], v[188:189], off offset:2560
	global_load_dwordx4 v[162:165], v[176:177], off
	v_bitop3_b32 v133, v136, s41, v167 bitop3:0xc8
	v_lshlrev_b32_e32 v152, 1, v133
	v_lshl_add_u64 v[178:179], s[12:13], 0, v[252:253]
	v_lshl_add_u64 v[180:181], v[178:179], 0, v[156:157]
	v_lshl_add_u64 v[176:177], v[134:135], 2, s[8:9]
	v_lshl_add_u64 v[182:183], v[178:179], 0, v[154:155]
	v_lshl_add_u64 v[184:185], v[178:179], 0, v[144:145]
	v_lshl_add_u64 v[178:179], v[178:179], 0, v[130:131]
	s_waitcnt vmcnt(0)
	v_mul_f32_e32 v133, v76, v162
	v_mul_f32_e32 v152, v77, v163
	v_mul_f32_e32 v161, v78, v164
	v_mul_f32_e32 v175, v79, v165
	v_mul_f32_e32 v186, v72, v162
	v_mul_f32_e32 v187, v73, v163
	v_mul_f32_e32 v188, v74, v164
	v_mul_f32_e32 v189, v75, v165
	v_mul_f32_e32 v190, v12, v162
	v_mul_f32_e32 v191, v13, v163
	v_mul_f32_e32 v194, v8, v162
	v_mul_f32_e32 v195, v9, v163
	v_cvt_pk_bf16_f32 v162, v133, v152
	v_cvt_pk_bf16_f32 v163, v161, v175
	v_mul_f32_e32 v192, v14, v164
	v_mul_f32_e32 v193, v15, v165
	v_mul_f32_e32 v196, v10, v164
	v_mul_f32_e32 v197, v11, v165
	v_cvt_pk_bf16_f32 v164, v186, v187
	v_cvt_pk_bf16_f32 v165, v188, v189
	v_cvt_pk_bf16_f32 v186, v190, v191
	v_cvt_pk_bf16_f32 v187, v192, v193
	v_cvt_pk_bf16_f32 v188, v194, v195
	v_cvt_pk_bf16_f32 v189, v196, v197
	global_store_dwordx2 v[180:181], v[162:163], off offset:3072
	global_store_dwordx2 v[182:183], v[164:165], off offset:3072
	global_store_dwordx2 v[184:185], v[186:187], off offset:3072
	global_store_dwordx2 v[178:179], v[188:189], off offset:3072
	global_load_dwordx4 v[162:165], v[176:177], off
	v_bitop3_b32 v133, v136, s42, v168 bitop3:0xc8
	v_lshlrev_b32_e32 v152, 1, v133
	v_lshl_add_u64 v[176:177], s[12:13], 0, v[252:253]
	v_lshl_add_u64 v[156:157], v[176:177], 0, v[156:157]
	v_lshl_add_u64 v[154:155], v[176:177], 0, v[154:155]
	v_lshl_add_u64 v[144:145], v[176:177], 0, v[144:145]
	v_lshl_add_u64 v[130:131], v[176:177], 0, v[130:131]
	s_waitcnt vmcnt(0)
	v_mul_f32_e32 v133, v68, v162
	v_mul_f32_e32 v152, v69, v163
	v_mul_f32_e32 v161, v70, v164
	v_mul_f32_e32 v175, v71, v165
	v_mul_f32_e32 v176, v64, v162
	v_mul_f32_e32 v177, v65, v163
	v_mul_f32_e32 v178, v66, v164
	v_mul_f32_e32 v179, v67, v165
	v_mul_f32_e32 v180, v4, v162
	v_mul_f32_e32 v181, v5, v163
	v_mul_f32_e32 v184, v0, v162
	v_mul_f32_e32 v185, v1, v163
	v_cvt_pk_bf16_f32 v162, v133, v152
	v_cvt_pk_bf16_f32 v163, v161, v175
	v_mul_f32_e32 v182, v6, v164
	v_mul_f32_e32 v183, v7, v165
	v_mul_f32_e32 v186, v2, v164
	v_mul_f32_e32 v187, v3, v165
	v_cvt_pk_bf16_f32 v164, v176, v177
	v_cvt_pk_bf16_f32 v165, v178, v179
	v_cvt_pk_bf16_f32 v176, v180, v181
	v_cvt_pk_bf16_f32 v177, v182, v183
	v_cvt_pk_bf16_f32 v178, v184, v185
	v_cvt_pk_bf16_f32 v179, v186, v187
	global_store_dwordx2 v[156:157], v[162:163], off offset:3584
	global_store_dwordx2 v[154:155], v[164:165], off offset:3584
	global_store_dwordx2 v[144:145], v[176:177], off offset:3584
	global_store_dwordx2 v[130:131], v[178:179], off offset:3584
	s_cbranch_execnz .LBB0_206
	s_branch .LBB0_212

.LBB0_503:
	s_add_i32 s37, s36, 64
	s_min_u32 s14, s37, 0x3e0
	s_lshl_b32 s14, s14, 1
	v_lshl_add_u64 v[170:171], v[154:155], 0, s[14:15]
	v_lshl_add_u64 v[174:175], v[158:159], 0, s[14:15]
	v_lshl_add_u64 v[178:179], v[160:161], 0, s[14:15]
	v_lshl_add_u64 v[182:183], v[162:163], 0, s[14:15]
	v_lshl_add_u64 v[186:187], v[156:157], 0, s[14:15]
	v_lshl_add_u64 v[190:191], v[164:165], 0, s[14:15]
	global_load_dwordx4 v[170:173], v[170:171], off
	ds_read_b128 v[196:199], v169 offset:32768
	global_load_dwordx4 v[174:177], v[174:175], off
	ds_read_b128 v[200:203], v169 offset:33792
	global_load_dwordx4 v[178:181], v[178:179], off
	ds_read_b128 v[204:207], v169 offset:34816
	global_load_dwordx4 v[182:185], v[182:183], off
	ds_read_b128 v[208:211], v169 offset:35840
	global_load_dwordx4 v[186:189], v[186:187], off
	ds_read_b128 v[212:215], v167
	global_load_dwordx4 v[190:193], v[190:191], off
	ds_read_b128 v[216:219], v167 offset:1024
	ds_read_b128 v[222:225], v167 offset:2048
	ds_read_b128 v[226:229], v167 offset:3072
	ds_read_b128 v[230:233], v167 offset:4096
	ds_read_b128 v[234:237], v167 offset:5120
	ds_read_b128 v[238:241], v167 offset:6144
	ds_read_b128 v[242:245], v167 offset:7168
	s_setprio 1
	s_waitcnt lgkmcnt(7)
	v_mfma_f32_16x16x32_bf16 v[148:151], v[196:199], v[212:215], v[148:151]
	v_mfma_f32_16x16x32_bf16 v[136:139], v[200:203], v[212:215], v[136:139]
	v_mfma_f32_16x16x32_bf16 v[132:135], v[204:207], v[212:215], v[132:135]
	v_mfma_f32_16x16x32_bf16 v[128:131], v[208:211], v[212:215], v[128:131]
	s_waitcnt vmcnt(11)
	ds_write_b128 v152, v[44:47] offset:16384
	s_waitcnt lgkmcnt(7)
	v_mfma_f32_16x16x32_bf16 v[124:127], v[196:199], v[216:219], v[124:127]
	v_mfma_f32_16x16x32_bf16 v[120:123], v[200:203], v[216:219], v[120:123]
	v_mfma_f32_16x16x32_bf16 v[116:119], v[204:207], v[216:219], v[116:119]
	v_mfma_f32_16x16x32_bf16 v[112:115], v[208:211], v[216:219], v[112:115]
	s_waitcnt vmcnt(9)
	ds_write_b128 v152, v[60:63] offset:20480
	s_waitcnt lgkmcnt(7)
	v_mfma_f32_16x16x32_bf16 v[108:111], v[196:199], v[222:225], v[108:111]
	v_mfma_f32_16x16x32_bf16 v[104:107], v[200:203], v[222:225], v[104:107]
	v_mfma_f32_16x16x32_bf16 v[100:103], v[204:207], v[222:225], v[100:103]
	v_mfma_f32_16x16x32_bf16 v[96:99], v[208:211], v[222:225], v[96:99]
	s_waitcnt vmcnt(8)
	ds_write_b128 v152, v[68:71] offset:24576
	s_waitcnt lgkmcnt(7)
	v_mfma_f32_16x16x32_bf16 v[92:95], v[196:199], v[226:229], v[92:95]
	v_mfma_f32_16x16x32_bf16 v[88:91], v[200:203], v[226:229], v[88:91]
	v_mfma_f32_16x16x32_bf16 v[84:87], v[204:207], v[226:229], v[84:87]
	v_mfma_f32_16x16x32_bf16 v[80:83], v[208:211], v[226:229], v[80:83]
	s_waitcnt vmcnt(7)
	ds_write_b128 v152, v[140:143] offset:28672
	s_waitcnt lgkmcnt(7)
	v_mfma_f32_16x16x32_bf16 v[76:79], v[196:199], v[230:233], v[76:79]
	v_mfma_f32_16x16x32_bf16 v[72:75], v[200:203], v[230:233], v[72:75]
	v_mfma_f32_16x16x32_bf16 v[64:67], v[204:207], v[230:233], v[64:67]
	v_mfma_f32_16x16x32_bf16 v[56:59], v[208:211], v[230:233], v[56:59]
	s_waitcnt vmcnt(7)
	ds_write_b128 v152, v[52:55] offset:40960
	s_waitcnt lgkmcnt(7)
	v_mfma_f32_16x16x32_bf16 v[48:51], v[196:199], v[234:237], v[48:51]
	v_mfma_f32_16x16x32_bf16 v[40:43], v[200:203], v[234:237], v[40:43]
	v_mfma_f32_16x16x32_bf16 v[36:39], v[204:207], v[234:237], v[36:39]
	v_mfma_f32_16x16x32_bf16 v[32:35], v[208:211], v[234:237], v[32:35]
	s_waitcnt vmcnt(6)
	ds_write_b128 v152, v[144:147] offset:45056
	s_waitcnt lgkmcnt(7)
	v_mfma_f32_16x16x32_bf16 v[28:31], v[196:199], v[238:241], v[28:31]
	v_mfma_f32_16x16x32_bf16 v[24:27], v[200:203], v[238:241], v[24:27]
	v_mfma_f32_16x16x32_bf16 v[20:23], v[204:207], v[238:241], v[20:23]
	v_mfma_f32_16x16x32_bf16 v[16:19], v[208:211], v[238:241], v[16:19]
	s_waitcnt lgkmcnt(6)
	v_mfma_f32_16x16x32_bf16 v[12:15], v[196:199], v[242:245], v[12:15]
	v_mfma_f32_16x16x32_bf16 v[8:11], v[200:203], v[242:245], v[8:11]
	v_mfma_f32_16x16x32_bf16 v[4:7], v[204:207], v[242:245], v[4:7]
	v_mfma_f32_16x16x32_bf16 v[0:3], v[208:211], v[242:245], v[0:3]
	s_setprio 0
	s_min_u32 s14, s36, 0x380
	s_lshl_b32 s14, s14, 1
	s_mov_b32 s39, s15
	s_add_i32 s38, s14, 0xc0
	v_lshl_add_u64 v[44:45], v[154:155], 0, s[14:15]
	v_lshl_add_u64 v[52:53], v[156:157], 0, s[14:15]
	v_lshl_add_u64 v[60:61], v[158:159], 0, s[38:39]
	v_lshl_add_u64 v[68:69], v[160:161], 0, s[38:39]
	v_lshl_add_u64 v[140:141], v[162:163], 0, s[38:39]
	v_lshl_add_u64 v[144:145], v[164:165], 0, s[38:39]
	s_waitcnt lgkmcnt(0)
	s_barrier
	global_load_dwordx4 v[44:47], v[44:45], off offset:192
	ds_read_b128 v[196:199], v166 offset:40960
	global_load_dwordx4 v[52:55], v[52:53], off offset:192
	ds_read_b128 v[200:203], v166 offset:41984
	global_load_dwordx4 v[60:63], v[60:61], off
	ds_read_b128 v[204:207], v166 offset:43008
	global_load_dwordx4 v[68:71], v[68:69], off
	ds_read_b128 v[208:211], v166 offset:44032
	global_load_dwordx4 v[140:143], v[140:141], off
	ds_read_b128 v[212:215], v168
	global_load_dwordx4 v[144:147], v[144:145], off
	ds_read_b128 v[216:219], v168 offset:1024
	ds_read_b128 v[222:225], v168 offset:2048
	ds_read_b128 v[226:229], v168 offset:3072
	ds_read_b128 v[230:233], v168 offset:4096
	ds_read_b128 v[234:237], v168 offset:5120
	ds_read_b128 v[238:241], v168 offset:6144
	ds_read_b128 v[242:245], v168 offset:7168
	s_setprio 1
	s_waitcnt lgkmcnt(7)
	v_mfma_f32_16x16x32_bf16 v[148:151], v[196:199], v[212:215], v[148:151]
	v_mfma_f32_16x16x32_bf16 v[136:139], v[200:203], v[212:215], v[136:139]
	v_mfma_f32_16x16x32_bf16 v[132:135], v[204:207], v[212:215], v[132:135]
	v_mfma_f32_16x16x32_bf16 v[128:131], v[208:211], v[212:215], v[128:131]
	s_waitcnt vmcnt(11)
	ds_write_b128 v152, v[170:173]
	s_waitcnt lgkmcnt(7)
	v_mfma_f32_16x16x32_bf16 v[124:127], v[196:199], v[216:219], v[124:127]
	v_mfma_f32_16x16x32_bf16 v[120:123], v[200:203], v[216:219], v[120:123]
	v_mfma_f32_16x16x32_bf16 v[116:119], v[204:207], v[216:219], v[116:119]
	v_mfma_f32_16x16x32_bf16 v[112:115], v[208:211], v[216:219], v[112:115]
	s_waitcnt vmcnt(10)
	ds_write_b128 v152, v[174:177] offset:4096
	s_waitcnt lgkmcnt(7)
	v_mfma_f32_16x16x32_bf16 v[108:111], v[196:199], v[222:225], v[108:111]
	v_mfma_f32_16x16x32_bf16 v[104:107], v[200:203], v[222:225], v[104:107]
	v_mfma_f32_16x16x32_bf16 v[100:103], v[204:207], v[222:225], v[100:103]
	v_mfma_f32_16x16x32_bf16 v[96:99], v[208:211], v[222:225], v[96:99]
	s_waitcnt vmcnt(9)
	ds_write_b128 v152, v[178:181] offset:8192
	s_waitcnt lgkmcnt(7)
	v_mfma_f32_16x16x32_bf16 v[92:95], v[196:199], v[226:229], v[92:95]
	v_mfma_f32_16x16x32_bf16 v[88:91], v[200:203], v[226:229], v[88:91]
	v_mfma_f32_16x16x32_bf16 v[84:87], v[204:207], v[226:229], v[84:87]
	v_mfma_f32_16x16x32_bf16 v[80:83], v[208:211], v[226:229], v[80:83]
	s_waitcnt vmcnt(8)
	ds_write_b128 v152, v[182:185] offset:12288
	s_waitcnt lgkmcnt(7)
	v_mfma_f32_16x16x32_bf16 v[76:79], v[196:199], v[230:233], v[76:79]
	v_mfma_f32_16x16x32_bf16 v[72:75], v[200:203], v[230:233], v[72:75]
	v_mfma_f32_16x16x32_bf16 v[64:67], v[204:207], v[230:233], v[64:67]
	v_mfma_f32_16x16x32_bf16 v[56:59], v[208:211], v[230:233], v[56:59]
	s_waitcnt vmcnt(7)
	ds_write_b128 v152, v[186:189] offset:32768
	s_waitcnt lgkmcnt(7)
	v_mfma_f32_16x16x32_bf16 v[48:51], v[196:199], v[234:237], v[48:51]
	v_mfma_f32_16x16x32_bf16 v[40:43], v[200:203], v[234:237], v[40:43]
	v_mfma_f32_16x16x32_bf16 v[36:39], v[204:207], v[234:237], v[36:39]
	v_mfma_f32_16x16x32_bf16 v[32:35], v[208:211], v[234:237], v[32:35]
	s_waitcnt vmcnt(6)
	ds_write_b128 v152, v[190:193] offset:36864
	s_waitcnt lgkmcnt(7)
	v_mfma_f32_16x16x32_bf16 v[28:31], v[196:199], v[238:241], v[28:31]
	v_mfma_f32_16x16x32_bf16 v[24:27], v[200:203], v[238:241], v[24:27]
	v_mfma_f32_16x16x32_bf16 v[20:23], v[204:207], v[238:241], v[20:23]
	v_mfma_f32_16x16x32_bf16 v[16:19], v[208:211], v[238:241], v[16:19]
	s_waitcnt lgkmcnt(6)
	v_mfma_f32_16x16x32_bf16 v[12:15], v[196:199], v[242:245], v[12:15]
	v_mfma_f32_16x16x32_bf16 v[8:11], v[200:203], v[242:245], v[8:11]
	v_mfma_f32_16x16x32_bf16 v[4:7], v[204:207], v[242:245], v[4:7]
	v_mfma_f32_16x16x32_bf16 v[0:3], v[208:211], v[242:245], v[0:3]
	s_setprio 0
	s_add_i32 s29, s29, 2
	s_cmp_lt_u32 s29, 30
	s_mov_b32 s36, s37
	s_waitcnt lgkmcnt(0)
	s_barrier
	s_cbranch_scc1 .LBB0_503
	s_waitcnt vmcnt(1)
	v_mov_b32_e32 v142, v220
	v_readlane_b32 s36, v254, 6
	v_and_b32_e32 v45, 0xffffff80, v142
	v_add_u32_e32 v143, s28, v45
	v_lshrrev_b32_e32 v45, 2, v142
	v_and_b32_e32 v44, 64, v142
	v_and_b32_e32 v45, 12, v45
	s_ashr_i32 s28, s33, 2
	v_or3_b32 v140, v44, v45, s35
	s_ashr_i32 s29, s28, 31
	v_ashrrev_i32_e32 v141, 31, v140
	v_readlane_b32 s44, v254, 14
	v_readlane_b32 s45, v254, 15
	s_waitcnt vmcnt(0)
	v_and_or_b32 v144, v142, 15, v143
	s_lshl_b64 s[28:29], s[28:29], 3
	v_lshl_add_u64 v[44:45], v[140:141], 2, s[44:45]
	s_add_u32 s28, s5, s28
	v_lshlrev_b64 v[140:141], 1, v[140:141]
	v_ashrrev_i32_e32 v145, 31, v144
	s_addc_u32 s29, s26, s29
	v_lshl_add_u64 v[142:143], s[70:71], 0, v[140:141]
	v_lshl_add_u64 v[146:147], v[144:145], 2, s[6:7]
	v_lshlrev_b64 v[154:155], 5, v[144:145]
	v_lshlrev_b64 v[190:191], 12, v[144:145]
	global_load_dwordx4 v[68:71], v[44:45], off
	global_load_dwordx4 v[60:63], v[44:45], off offset:64
	global_load_dwordx4 v[52:55], v[44:45], off offset:128
	s_nop 0
	global_load_dwordx4 v[44:47], v[44:45], off offset:192
	v_lshl_add_u64 v[154:155], s[28:29], 0, v[154:155]
	global_load_dword v202, v[146:147], off
	global_load_dwordx2 v[184:185], v[154:155], off
	v_lshl_add_u64 v[146:147], v[142:143], 0, v[190:191]
	global_load_dwordx2 v[196:197], v[146:147], off
	global_load_dwordx2 v[198:199], v[146:147], off offset:32
	global_load_dwordx2 v[200:201], v[146:147], off offset:64
	global_load_dwordx2 v[192:193], v[146:147], off offset:96
	v_or_b32_e32 v146, 16, v144
	v_ashrrev_i32_e32 v147, 31, v146
	v_lshlrev_b64 v[188:189], 12, v[146:147]
	v_lshl_add_u64 v[154:155], v[146:147], 2, s[6:7]
	v_lshlrev_b64 v[156:157], 5, v[146:147]
	v_lshl_add_u64 v[146:147], v[142:143], 0, v[188:189]
	v_lshl_add_u64 v[156:157], s[28:29], 0, v[156:157]
	global_load_dword v195, v[154:155], off
	global_load_dwordx2 v[172:173], v[156:157], off
	global_load_dwordx2 v[186:187], v[146:147], off
	global_load_dwordx2 v[182:183], v[146:147], off offset:32
	global_load_dwordx2 v[180:181], v[146:147], off offset:64
	global_load_dwordx2 v[178:179], v[146:147], off offset:96
	v_or_b32_e32 v146, 32, v144
	v_ashrrev_i32_e32 v147, 31, v146
	v_lshl_add_u64 v[154:155], v[146:147], 2, s[6:7]
	v_lshlrev_b64 v[156:157], 5, v[146:147]
	v_lshl_add_u64 v[156:157], s[28:29], 0, v[156:157]
	global_load_dword v152, v[154:155], off
	global_load_dwordx2 v[160:161], v[156:157], off
	v_or_b32_e32 v154, 48, v144
	v_lshlrev_b64 v[176:177], 12, v[146:147]
	v_ashrrev_i32_e32 v155, 31, v154
	v_lshl_add_u64 v[146:147], v[142:143], 0, v[176:177]
	v_lshlrev_b64 v[156:157], 5, v[154:155]
	v_lshlrev_b64 v[164:165], 12, v[154:155]
	global_load_dwordx2 v[174:175], v[146:147], off
	global_load_dwordx2 v[170:171], v[146:147], off offset:32
	global_load_dwordx2 v[168:169], v[146:147], off offset:64
	global_load_dwordx2 v[166:167], v[146:147], off offset:96
	v_lshl_add_u64 v[146:147], v[154:155], 2, s[6:7]
	v_lshl_add_u64 v[156:157], s[28:29], 0, v[156:157]
	v_lshl_add_u64 v[154:155], v[142:143], 0, v[164:165]
	global_load_dword v145, v[146:147], off
	s_nop 0
	global_load_dwordx2 v[146:147], v[156:157], off
	global_load_dwordx2 v[162:163], v[154:155], off
	global_load_dwordx2 v[158:159], v[154:155], off offset:32
	s_nop 0
	global_load_dwordx2 v[156:157], v[154:155], off offset:64
	s_nop 0
	global_load_dwordx2 v[154:155], v[154:155], off offset:96
	v_readlane_b32 s37, v254, 7
	v_readlane_b32 s38, v254, 8
	v_readlane_b32 s39, v254, 9
	v_readlane_b32 s40, v254, 10
	v_readlane_b32 s41, v254, 11
	v_readlane_b32 s42, v254, 12
	v_readlane_b32 s43, v254, 13
	v_readlane_b32 s46, v254, 16
	v_readlane_b32 s47, v254, 17
	v_readlane_b32 s48, v254, 18
	v_readlane_b32 s49, v254, 19
	v_readlane_b32 s50, v254, 20
	v_readlane_b32 s51, v254, 21
	v_lshl_add_u64 v[140:141], s[8:9], 0, v[140:141]
	s_waitcnt vmcnt(23)
	v_mul_f32_e32 v148, v148, v202
	v_mul_f32_e32 v205, 0xbfb8aa3b, v148
	v_exp_f32_e32 v205, v205
	v_mul_f32_e32 v149, v149, v202
	v_mul_f32_e32 v206, 0xbfb8aa3b, v149
	v_exp_f32_e32 v206, v206
	v_add_f32_e32 v205, 1.0, v205
	v_rcp_f32_e32 v205, v205
	s_waitcnt vmcnt(21)
	v_lshlrev_b32_e32 v203, 16, v196
	v_mul_f32_e32 v150, v150, v202
	v_sub_f32_e32 v203, v203, v184
	v_mul_f32_e32 v148, v148, v205
	v_add_f32_e32 v205, 1.0, v206
	v_rcp_f32_e32 v205, v205
	v_mul_f32_e32 v148, v148, v203
	v_mul_f32_e32 v203, 0xbfb8aa3b, v150
	v_exp_f32_e32 v203, v203
	v_and_b32_e32 v196, 0xffff0000, v196
	v_mul_f32_e32 v151, v151, v202
	v_mul_f32_e32 v149, v149, v205
	v_sub_f32_e32 v196, v196, v184
	v_mul_f32_e32 v149, v149, v196
	v_add_f32_e32 v196, 1.0, v203
	v_mul_f32_e32 v203, 0xbfb8aa3b, v151
	v_exp_f32_e32 v203, v203
	v_rcp_f32_e32 v196, v196
	v_lshlrev_b32_e32 v204, 16, v197
	v_and_b32_e32 v197, 0xffff0000, v197
	v_add_f32_e32 v203, 1.0, v203
	v_rcp_f32_e32 v203, v203
	v_mul_f32_e32 v150, v150, v196
	v_sub_f32_e32 v196, v204, v184
	v_mul_f32_e32 v150, v150, v196
	v_mul_f32_e32 v151, v151, v203
	v_sub_f32_e32 v196, v197, v184
	v_mul_f32_e32 v151, v151, v196
	v_mul_f32_e32 v148, v185, v148
	v_mul_f32_e32 v149, v185, v149
	v_mul_f32_e32 v151, v185, v151
	v_mul_f32_e32 v148, v68, v148
	v_mul_f32_e32 v149, v69, v149
	v_mul_f32_e32 v150, v185, v150
	v_mul_f32_e32 v151, v71, v151
	v_mul_f32_e32 v136, v136, v202
	v_mul_f32_e32 v150, v70, v150
	v_cvt_pk_bf16_f32 v148, v148, v149
	v_cvt_pk_bf16_f32 v149, v150, v151
	v_mul_f32_e32 v151, 0xbfb8aa3b, v136
	v_exp_f32_e32 v151, v151
	v_mul_f32_e32 v137, v137, v202
	v_mul_f32_e32 v197, 0xbfb8aa3b, v137
	v_exp_f32_e32 v197, v197
	v_add_f32_e32 v151, 1.0, v151
	v_rcp_f32_e32 v151, v151
	v_lshl_add_u64 v[190:191], v[140:141], 0, v[190:191]
	global_store_dwordx2 v[190:191], v[148:149], off
	s_waitcnt vmcnt(21)
	v_lshlrev_b32_e32 v148, 16, v198
	v_mul_f32_e32 v136, v136, v151
	v_add_f32_e32 v151, 1.0, v197
	v_rcp_f32_e32 v151, v151
	v_and_b32_e32 v149, 0xffff0000, v198
	v_mul_f32_e32 v138, v138, v202
	v_sub_f32_e32 v148, v148, v184
	v_mul_f32_e32 v139, v139, v202
	v_mul_f32_e32 v136, v136, v148
	v_mul_f32_e32 v137, v137, v151
	v_mul_f32_e32 v148, 0xbfb8aa3b, v138
	v_sub_f32_e32 v149, v149, v184
	v_exp_f32_e32 v148, v148
	v_mul_f32_e32 v137, v137, v149
	v_mul_f32_e32 v149, 0xbfb8aa3b, v139
	v_exp_f32_e32 v149, v149
	v_add_f32_e32 v148, 1.0, v148
	v_rcp_f32_e32 v148, v148
	v_lshlrev_b32_e32 v150, 16, v199
	v_add_f32_e32 v149, 1.0, v149
	v_rcp_f32_e32 v149, v149
	v_and_b32_e32 v196, 0xffff0000, v199
	v_mul_f32_e32 v138, v138, v148
	v_sub_f32_e32 v148, v150, v184
	v_mul_f32_e32 v138, v138, v148
	v_mul_f32_e32 v139, v139, v149
	v_sub_f32_e32 v148, v196, v184
	v_mul_f32_e32 v139, v139, v148
	v_mul_f32_e32 v136, v185, v136
	v_mul_f32_e32 v137, v185, v137
	v_mul_f32_e32 v139, v185, v139
	v_mul_f32_e32 v136, v60, v136
	v_mul_f32_e32 v137, v61, v137
	v_mul_f32_e32 v138, v185, v138
	v_mul_f32_e32 v139, v63, v139
	v_mul_f32_e32 v132, v132, v202
	v_mul_f32_e32 v138, v62, v138
	v_cvt_pk_bf16_f32 v136, v136, v137
	v_cvt_pk_bf16_f32 v137, v138, v139
	v_mul_f32_e32 v139, 0xbfb8aa3b, v132
	v_exp_f32_e32 v139, v139
	v_mul_f32_e32 v133, v133, v202
	v_mul_f32_e32 v149, 0xbfb8aa3b, v133
	v_exp_f32_e32 v149, v149
	v_add_f32_e32 v139, 1.0, v139
	v_rcp_f32_e32 v139, v139
	global_store_dwordx2 v[190:191], v[136:137], off offset:32
	s_waitcnt vmcnt(21)
	v_lshlrev_b32_e32 v136, 16, v200
	v_and_b32_e32 v137, 0xffff0000, v200
	v_mul_f32_e32 v132, v132, v139
	v_add_f32_e32 v139, 1.0, v149
	v_rcp_f32_e32 v139, v139
	v_mul_f32_e32 v134, v134, v202
	v_sub_f32_e32 v136, v136, v184
	v_mul_f32_e32 v135, v135, v202
	v_mul_f32_e32 v132, v132, v136
	v_mul_f32_e32 v133, v133, v139
	v_mul_f32_e32 v136, 0xbfb8aa3b, v134
	v_sub_f32_e32 v137, v137, v184
	v_exp_f32_e32 v136, v136
	v_mul_f32_e32 v133, v133, v137
	v_mul_f32_e32 v137, 0xbfb8aa3b, v135
	v_exp_f32_e32 v137, v137
	v_add_f32_e32 v136, 1.0, v136
	v_rcp_f32_e32 v136, v136
	v_lshlrev_b32_e32 v138, 16, v201
	v_add_f32_e32 v137, 1.0, v137
	v_rcp_f32_e32 v137, v137
	v_and_b32_e32 v148, 0xffff0000, v201
	v_mul_f32_e32 v134, v134, v136
	v_sub_f32_e32 v136, v138, v184
	v_mul_f32_e32 v134, v134, v136
	v_mul_f32_e32 v135, v135, v137
	v_sub_f32_e32 v136, v148, v184
	v_mul_f32_e32 v135, v135, v136
	v_mul_f32_e32 v132, v185, v132
	v_mul_f32_e32 v133, v185, v133
	v_mul_f32_e32 v135, v185, v135
	v_mul_f32_e32 v132, v52, v132
	v_mul_f32_e32 v133, v53, v133
	v_mul_f32_e32 v134, v185, v134
	v_mul_f32_e32 v135, v55, v135
	v_mul_f32_e32 v128, v128, v202
	v_mul_f32_e32 v134, v54, v134
	v_cvt_pk_bf16_f32 v132, v132, v133
	v_cvt_pk_bf16_f32 v133, v134, v135
	v_mul_f32_e32 v135, 0xbfb8aa3b, v128
	v_exp_f32_e32 v135, v135
	v_mul_f32_e32 v129, v129, v202
	v_mul_f32_e32 v137, 0xbfb8aa3b, v129
	v_exp_f32_e32 v137, v137
	v_add_f32_e32 v135, 1.0, v135
	v_rcp_f32_e32 v135, v135
	global_store_dwordx2 v[190:191], v[132:133], off offset:64
	s_waitcnt vmcnt(21)
	v_and_b32_e32 v133, 0xffff0000, v192
	v_mul_f32_e32 v131, v131, v202
	v_mul_f32_e32 v128, v128, v135
	v_add_f32_e32 v135, 1.0, v137
	v_rcp_f32_e32 v135, v135
	v_sub_f32_e32 v133, v133, v184
	v_lshlrev_b32_e32 v132, 16, v192
	v_mul_f32_e32 v130, v130, v202
	v_mul_f32_e32 v129, v129, v135
	v_mul_f32_e32 v129, v129, v133
	v_mul_f32_e32 v133, 0xbfb8aa3b, v131
	v_exp_f32_e32 v133, v133
	v_sub_f32_e32 v132, v132, v184
	v_mul_f32_e32 v128, v128, v132
	v_mul_f32_e32 v132, 0xbfb8aa3b, v130
	v_add_f32_e32 v133, 1.0, v133
	v_rcp_f32_e32 v133, v133
	s_waitcnt vmcnt(20)
	v_mul_f32_e32 v124, v124, v195
	v_exp_f32_e32 v132, v132
	v_mul_f32_e32 v125, v125, v195
	v_mul_f32_e32 v131, v131, v133
	v_mul_f32_e32 v133, 0xbfb8aa3b, v124
	v_exp_f32_e32 v133, v133
	v_add_f32_e32 v132, 1.0, v132
	v_rcp_f32_e32 v132, v132
	v_mul_f32_e32 v135, 0xbfb8aa3b, v125
	v_add_f32_e32 v133, 1.0, v133
	v_rcp_f32_e32 v133, v133
	v_exp_f32_e32 v135, v135
	v_lshlrev_b32_e32 v134, 16, v193
	v_and_b32_e32 v136, 0xffff0000, v193
	v_mul_f32_e32 v130, v130, v132
	v_sub_f32_e32 v132, v134, v184
	v_mul_f32_e32 v130, v130, v132
	v_sub_f32_e32 v132, v136, v184
	v_mul_f32_e32 v124, v124, v133
	v_add_f32_e32 v133, 1.0, v135
	v_mul_f32_e32 v128, v185, v128
	v_mul_f32_e32 v129, v185, v129
	v_mul_f32_e32 v130, v185, v130
	v_mul_f32_e32 v131, v131, v132
	v_rcp_f32_e32 v133, v133
	v_mul_f32_e32 v128, v44, v128
	v_mul_f32_e32 v129, v45, v129
	v_mul_f32_e32 v130, v46, v130
	v_mul_f32_e32 v131, v185, v131
	v_mul_f32_e32 v131, v47, v131
	v_cvt_pk_bf16_f32 v128, v128, v129
	v_cvt_pk_bf16_f32 v129, v130, v131
	s_waitcnt vmcnt(18)
	v_lshlrev_b32_e32 v130, 16, v186
	v_and_b32_e32 v131, 0xffff0000, v186
	v_mul_f32_e32 v126, v126, v195
	v_sub_f32_e32 v130, v130, v172
	v_mul_f32_e32 v127, v127, v195
	v_mul_f32_e32 v124, v124, v130
	v_mul_f32_e32 v125, v125, v133
	v_mul_f32_e32 v130, 0xbfb8aa3b, v126
	v_sub_f32_e32 v131, v131, v172
	v_exp_f32_e32 v130, v130
	v_mul_f32_e32 v125, v125, v131
	v_mul_f32_e32 v131, 0xbfb8aa3b, v127
	v_exp_f32_e32 v131, v131
	v_add_f32_e32 v130, 1.0, v130
	v_rcp_f32_e32 v130, v130
	v_lshlrev_b32_e32 v132, 16, v187
	v_add_f32_e32 v131, 1.0, v131
	v_rcp_f32_e32 v131, v131
	v_and_b32_e32 v134, 0xffff0000, v187
	v_mul_f32_e32 v126, v126, v130
	v_sub_f32_e32 v130, v132, v172
	v_mul_f32_e32 v126, v126, v130
	v_mul_f32_e32 v127, v127, v131
	v_sub_f32_e32 v130, v134, v172
	v_mul_f32_e32 v127, v127, v130
	v_mul_f32_e32 v124, v173, v124
	v_mul_f32_e32 v125, v173, v125
	v_mul_f32_e32 v127, v173, v127
	v_mul_f32_e32 v124, v68, v124
	v_mul_f32_e32 v125, v69, v125
	v_mul_f32_e32 v126, v173, v126
	v_mul_f32_e32 v127, v71, v127
	v_mul_f32_e32 v120, v120, v195
	v_mul_f32_e32 v126, v70, v126
	v_cvt_pk_bf16_f32 v124, v124, v125
	v_cvt_pk_bf16_f32 v125, v126, v127
	v_mul_f32_e32 v127, 0xbfb8aa3b, v120
	v_exp_f32_e32 v127, v127
	v_mul_f32_e32 v121, v121, v195
	v_mul_f32_e32 v131, 0xbfb8aa3b, v121
	v_exp_f32_e32 v131, v131
	v_add_f32_e32 v127, 1.0, v127
	v_rcp_f32_e32 v127, v127
	global_store_dwordx2 v[190:191], v[128:129], off offset:96
	v_lshl_add_u64 v[128:129], v[140:141], 0, v[188:189]
	global_store_dwordx2 v[128:129], v[124:125], off
	v_mul_f32_e32 v120, v120, v127
	v_add_f32_e32 v127, 1.0, v131
	v_rcp_f32_e32 v127, v127
	s_waitcnt vmcnt(19)
	v_lshlrev_b32_e32 v124, 16, v182
	v_and_b32_e32 v125, 0xffff0000, v182
	v_mul_f32_e32 v122, v122, v195
	v_sub_f32_e32 v124, v124, v172
	v_mul_f32_e32 v123, v123, v195
	v_mul_f32_e32 v120, v120, v124
	v_mul_f32_e32 v121, v121, v127
	v_mul_f32_e32 v124, 0xbfb8aa3b, v122
	v_sub_f32_e32 v125, v125, v172
	v_exp_f32_e32 v124, v124
	v_mul_f32_e32 v121, v121, v125
	v_mul_f32_e32 v125, 0xbfb8aa3b, v123
	v_exp_f32_e32 v125, v125
	v_add_f32_e32 v124, 1.0, v124
	v_rcp_f32_e32 v124, v124
	v_lshlrev_b32_e32 v126, 16, v183
	v_add_f32_e32 v125, 1.0, v125
	v_rcp_f32_e32 v125, v125
	v_and_b32_e32 v130, 0xffff0000, v183
	v_mul_f32_e32 v122, v122, v124
	v_sub_f32_e32 v124, v126, v172
	v_mul_f32_e32 v122, v122, v124
	v_mul_f32_e32 v123, v123, v125
	v_sub_f32_e32 v124, v130, v172
	v_mul_f32_e32 v123, v123, v124
	v_mul_f32_e32 v120, v173, v120
	v_mul_f32_e32 v121, v173, v121
	v_mul_f32_e32 v123, v173, v123
	v_mul_f32_e32 v120, v60, v120
	v_mul_f32_e32 v121, v61, v121
	v_mul_f32_e32 v122, v173, v122
	v_mul_f32_e32 v123, v63, v123
	v_mul_f32_e32 v116, v116, v195
	v_mul_f32_e32 v122, v62, v122
	v_cvt_pk_bf16_f32 v120, v120, v121
	v_cvt_pk_bf16_f32 v121, v122, v123
	v_mul_f32_e32 v123, 0xbfb8aa3b, v116
	v_exp_f32_e32 v123, v123
	v_mul_f32_e32 v117, v117, v195
	v_mul_f32_e32 v125, 0xbfb8aa3b, v117
	v_exp_f32_e32 v125, v125
	v_add_f32_e32 v123, 1.0, v123
	v_rcp_f32_e32 v123, v123
	global_store_dwordx2 v[128:129], v[120:121], off offset:32
	s_waitcnt vmcnt(19)
	v_lshlrev_b32_e32 v120, 16, v180
	v_and_b32_e32 v121, 0xffff0000, v180
	v_mul_f32_e32 v116, v116, v123
	v_add_f32_e32 v123, 1.0, v125
	v_rcp_f32_e32 v123, v123
	v_mul_f32_e32 v118, v118, v195
	v_sub_f32_e32 v120, v120, v172
	v_mul_f32_e32 v119, v119, v195
	v_mul_f32_e32 v116, v116, v120
	v_mul_f32_e32 v117, v117, v123
	v_mul_f32_e32 v120, 0xbfb8aa3b, v118
	v_sub_f32_e32 v121, v121, v172
	v_exp_f32_e32 v120, v120
	v_mul_f32_e32 v117, v117, v121
	v_mul_f32_e32 v121, 0xbfb8aa3b, v119
	v_exp_f32_e32 v121, v121
	v_add_f32_e32 v120, 1.0, v120
	v_rcp_f32_e32 v120, v120
	v_lshlrev_b32_e32 v122, 16, v181
	v_add_f32_e32 v121, 1.0, v121
	v_rcp_f32_e32 v121, v121
	v_and_b32_e32 v124, 0xffff0000, v181
	v_mul_f32_e32 v118, v118, v120
	v_sub_f32_e32 v120, v122, v172
	v_mul_f32_e32 v118, v118, v120
	v_mul_f32_e32 v119, v119, v121
	v_sub_f32_e32 v120, v124, v172
	v_mul_f32_e32 v119, v119, v120
	v_mul_f32_e32 v116, v173, v116
	v_mul_f32_e32 v117, v173, v117
	v_mul_f32_e32 v119, v173, v119
	v_mul_f32_e32 v116, v52, v116
	v_mul_f32_e32 v117, v53, v117
	v_mul_f32_e32 v118, v173, v118
	v_mul_f32_e32 v119, v55, v119
	v_mul_f32_e32 v112, v112, v195
	v_mul_f32_e32 v118, v54, v118
	v_cvt_pk_bf16_f32 v116, v116, v117
	v_cvt_pk_bf16_f32 v117, v118, v119
	v_mul_f32_e32 v119, 0xbfb8aa3b, v112
	v_exp_f32_e32 v119, v119
	v_mul_f32_e32 v113, v113, v195
	v_mul_f32_e32 v121, 0xbfb8aa3b, v113
	v_exp_f32_e32 v121, v121
	v_add_f32_e32 v119, 1.0, v119
	v_rcp_f32_e32 v119, v119
	global_store_dwordx2 v[128:129], v[116:117], off offset:64
	s_waitcnt vmcnt(19)
	v_and_b32_e32 v117, 0xffff0000, v178
	v_mul_f32_e32 v115, v115, v195
	v_mul_f32_e32 v112, v112, v119
	v_add_f32_e32 v119, 1.0, v121
	v_rcp_f32_e32 v119, v119
	v_sub_f32_e32 v117, v117, v172
	v_lshlrev_b32_e32 v116, 16, v178
	v_mul_f32_e32 v114, v114, v195
	v_mul_f32_e32 v113, v113, v119
	v_mul_f32_e32 v113, v113, v117
	v_mul_f32_e32 v117, 0xbfb8aa3b, v115
	v_exp_f32_e32 v117, v117
	v_sub_f32_e32 v116, v116, v172
	v_mul_f32_e32 v112, v112, v116
	v_mul_f32_e32 v116, 0xbfb8aa3b, v114
	v_add_f32_e32 v117, 1.0, v117
	v_rcp_f32_e32 v117, v117
	s_waitcnt vmcnt(18)
	v_mul_f32_e32 v108, v108, v152
	v_exp_f32_e32 v116, v116
	v_mul_f32_e32 v109, v109, v152
	v_mul_f32_e32 v115, v115, v117
	v_mul_f32_e32 v117, 0xbfb8aa3b, v108
	v_exp_f32_e32 v117, v117
	v_add_f32_e32 v116, 1.0, v116
	v_rcp_f32_e32 v116, v116
	v_mul_f32_e32 v119, 0xbfb8aa3b, v109
	v_add_f32_e32 v117, 1.0, v117
	v_rcp_f32_e32 v117, v117
	v_exp_f32_e32 v119, v119
	v_lshlrev_b32_e32 v118, 16, v179
	v_and_b32_e32 v120, 0xffff0000, v179
	v_mul_f32_e32 v114, v114, v116
	v_sub_f32_e32 v116, v118, v172
	v_mul_f32_e32 v114, v114, v116
	v_sub_f32_e32 v116, v120, v172
	v_mul_f32_e32 v108, v108, v117
	v_add_f32_e32 v117, 1.0, v119
	v_mul_f32_e32 v112, v173, v112
	v_mul_f32_e32 v113, v173, v113
	v_mul_f32_e32 v114, v173, v114
	v_mul_f32_e32 v115, v115, v116
	v_rcp_f32_e32 v117, v117
	v_mul_f32_e32 v112, v44, v112
	v_mul_f32_e32 v113, v45, v113
	v_mul_f32_e32 v114, v46, v114
	v_mul_f32_e32 v115, v173, v115
	v_mul_f32_e32 v115, v47, v115
	v_cvt_pk_bf16_f32 v112, v112, v113
	v_cvt_pk_bf16_f32 v113, v114, v115
	s_waitcnt vmcnt(16)
	v_lshlrev_b32_e32 v114, 16, v174
	v_and_b32_e32 v115, 0xffff0000, v174
	v_mul_f32_e32 v110, v110, v152
	v_sub_f32_e32 v114, v114, v160
	v_mul_f32_e32 v111, v111, v152
	v_mul_f32_e32 v108, v108, v114
	v_mul_f32_e32 v109, v109, v117
	v_mul_f32_e32 v114, 0xbfb8aa3b, v110
	v_sub_f32_e32 v115, v115, v160
	v_exp_f32_e32 v114, v114
	v_mul_f32_e32 v109, v109, v115
	v_mul_f32_e32 v115, 0xbfb8aa3b, v111
	v_exp_f32_e32 v115, v115
	v_add_f32_e32 v114, 1.0, v114
	v_rcp_f32_e32 v114, v114
	v_lshlrev_b32_e32 v116, 16, v175
	v_add_f32_e32 v115, 1.0, v115
	v_rcp_f32_e32 v115, v115
	v_and_b32_e32 v118, 0xffff0000, v175
	v_mul_f32_e32 v110, v110, v114
	v_sub_f32_e32 v114, v116, v160
	v_mul_f32_e32 v110, v110, v114
	v_mul_f32_e32 v111, v111, v115
	v_sub_f32_e32 v114, v118, v160
	v_mul_f32_e32 v111, v111, v114
	v_mul_f32_e32 v108, v161, v108
	v_mul_f32_e32 v109, v161, v109
	v_mul_f32_e32 v111, v161, v111
	v_mul_f32_e32 v108, v68, v108
	v_mul_f32_e32 v109, v69, v109
	v_mul_f32_e32 v110, v161, v110
	v_mul_f32_e32 v111, v71, v111
	v_mul_f32_e32 v104, v104, v152
	v_mul_f32_e32 v110, v70, v110
	v_cvt_pk_bf16_f32 v108, v108, v109
	v_cvt_pk_bf16_f32 v109, v110, v111
	v_mul_f32_e32 v111, 0xbfb8aa3b, v104
	v_exp_f32_e32 v111, v111
	v_mul_f32_e32 v105, v105, v152
	v_mul_f32_e32 v115, 0xbfb8aa3b, v105
	v_exp_f32_e32 v115, v115
	v_add_f32_e32 v111, 1.0, v111
	v_rcp_f32_e32 v111, v111
	global_store_dwordx2 v[128:129], v[112:113], off offset:96
	v_lshl_add_u64 v[112:113], v[140:141], 0, v[176:177]
	global_store_dwordx2 v[112:113], v[108:109], off
	v_mul_f32_e32 v104, v104, v111
	v_add_f32_e32 v111, 1.0, v115
	v_rcp_f32_e32 v111, v111
	s_waitcnt vmcnt(17)
	v_lshlrev_b32_e32 v108, 16, v170
	v_and_b32_e32 v109, 0xffff0000, v170
	v_mul_f32_e32 v106, v106, v152
	v_sub_f32_e32 v108, v108, v160
	v_mul_f32_e32 v107, v107, v152
	v_mul_f32_e32 v104, v104, v108
	v_mul_f32_e32 v105, v105, v111
	v_mul_f32_e32 v108, 0xbfb8aa3b, v106
	v_sub_f32_e32 v109, v109, v160
	v_exp_f32_e32 v108, v108
	v_mul_f32_e32 v105, v105, v109
	v_mul_f32_e32 v109, 0xbfb8aa3b, v107
	v_exp_f32_e32 v109, v109
	v_add_f32_e32 v108, 1.0, v108
	v_rcp_f32_e32 v108, v108
	v_lshlrev_b32_e32 v110, 16, v171
	v_add_f32_e32 v109, 1.0, v109
	v_rcp_f32_e32 v109, v109
	v_and_b32_e32 v114, 0xffff0000, v171
	v_mul_f32_e32 v106, v106, v108
	v_sub_f32_e32 v108, v110, v160
	v_mul_f32_e32 v106, v106, v108
	v_mul_f32_e32 v107, v107, v109
	v_sub_f32_e32 v108, v114, v160
	v_mul_f32_e32 v107, v107, v108
	v_mul_f32_e32 v104, v161, v104
	v_mul_f32_e32 v105, v161, v105
	v_mul_f32_e32 v107, v161, v107
	v_mul_f32_e32 v104, v60, v104
	v_mul_f32_e32 v105, v61, v105
	v_mul_f32_e32 v106, v161, v106
	v_mul_f32_e32 v107, v63, v107
	v_mul_f32_e32 v100, v100, v152
	v_mul_f32_e32 v106, v62, v106
	v_cvt_pk_bf16_f32 v104, v104, v105
	v_cvt_pk_bf16_f32 v105, v106, v107
	v_mul_f32_e32 v107, 0xbfb8aa3b, v100
	v_exp_f32_e32 v107, v107
	v_mul_f32_e32 v101, v101, v152
	v_mul_f32_e32 v109, 0xbfb8aa3b, v101
	v_exp_f32_e32 v109, v109
	v_add_f32_e32 v107, 1.0, v107
	v_rcp_f32_e32 v107, v107
	global_store_dwordx2 v[112:113], v[104:105], off offset:32
	s_waitcnt vmcnt(17)
	v_lshlrev_b32_e32 v104, 16, v168
	v_and_b32_e32 v105, 0xffff0000, v168
	v_mul_f32_e32 v100, v100, v107
	v_add_f32_e32 v107, 1.0, v109
	v_rcp_f32_e32 v107, v107
	v_mul_f32_e32 v102, v102, v152
	v_sub_f32_e32 v104, v104, v160
	v_mul_f32_e32 v103, v103, v152
	v_mul_f32_e32 v100, v100, v104
	v_mul_f32_e32 v101, v101, v107
	v_mul_f32_e32 v104, 0xbfb8aa3b, v102
	v_sub_f32_e32 v105, v105, v160
	v_exp_f32_e32 v104, v104
	v_mul_f32_e32 v101, v101, v105
	v_mul_f32_e32 v105, 0xbfb8aa3b, v103
	v_exp_f32_e32 v105, v105
	v_add_f32_e32 v104, 1.0, v104
	v_rcp_f32_e32 v104, v104
	v_lshlrev_b32_e32 v106, 16, v169
	v_add_f32_e32 v105, 1.0, v105
	v_rcp_f32_e32 v105, v105
	v_and_b32_e32 v108, 0xffff0000, v169
	v_mul_f32_e32 v102, v102, v104
	v_sub_f32_e32 v104, v106, v160
	v_mul_f32_e32 v102, v102, v104
	v_mul_f32_e32 v103, v103, v105
	v_sub_f32_e32 v104, v108, v160
	v_mul_f32_e32 v103, v103, v104
	v_mul_f32_e32 v100, v161, v100
	v_mul_f32_e32 v101, v161, v101
	v_mul_f32_e32 v103, v161, v103
	v_mul_f32_e32 v100, v52, v100
	v_mul_f32_e32 v101, v53, v101
	v_mul_f32_e32 v102, v161, v102
	v_mul_f32_e32 v103, v55, v103
	v_mul_f32_e32 v96, v96, v152
	v_mul_f32_e32 v102, v54, v102
	v_cvt_pk_bf16_f32 v100, v100, v101
	v_cvt_pk_bf16_f32 v101, v102, v103
	v_mul_f32_e32 v103, 0xbfb8aa3b, v96
	v_exp_f32_e32 v103, v103
	v_mul_f32_e32 v97, v97, v152
	v_mul_f32_e32 v105, 0xbfb8aa3b, v97
	v_exp_f32_e32 v105, v105
	v_add_f32_e32 v103, 1.0, v103
	v_rcp_f32_e32 v103, v103
	global_store_dwordx2 v[112:113], v[100:101], off offset:64
	s_waitcnt vmcnt(17)
	v_and_b32_e32 v101, 0xffff0000, v166
	v_mul_f32_e32 v99, v99, v152
	v_mul_f32_e32 v96, v96, v103
	v_add_f32_e32 v103, 1.0, v105
	v_rcp_f32_e32 v103, v103
	v_sub_f32_e32 v101, v101, v160
	v_lshlrev_b32_e32 v100, 16, v166
	v_mul_f32_e32 v98, v98, v152
	v_mul_f32_e32 v97, v97, v103
	v_mul_f32_e32 v97, v97, v101
	v_mul_f32_e32 v101, 0xbfb8aa3b, v99
	v_exp_f32_e32 v101, v101
	v_sub_f32_e32 v100, v100, v160
	v_mul_f32_e32 v96, v96, v100
	v_mul_f32_e32 v100, 0xbfb8aa3b, v98
	v_add_f32_e32 v101, 1.0, v101
	v_rcp_f32_e32 v101, v101
	s_waitcnt vmcnt(16)
	v_mul_f32_e32 v92, v92, v145
	v_exp_f32_e32 v100, v100
	v_mul_f32_e32 v93, v93, v145
	v_mul_f32_e32 v99, v99, v101
	v_mul_f32_e32 v101, 0xbfb8aa3b, v92
	v_exp_f32_e32 v101, v101
	v_add_f32_e32 v100, 1.0, v100
	v_rcp_f32_e32 v100, v100
	v_mul_f32_e32 v103, 0xbfb8aa3b, v93
	v_add_f32_e32 v101, 1.0, v101
	v_rcp_f32_e32 v101, v101
	v_exp_f32_e32 v103, v103
	v_lshlrev_b32_e32 v102, 16, v167
	v_and_b32_e32 v104, 0xffff0000, v167
	v_mul_f32_e32 v98, v98, v100
	v_sub_f32_e32 v100, v102, v160
	v_mul_f32_e32 v98, v98, v100
	v_sub_f32_e32 v100, v104, v160
	v_mul_f32_e32 v92, v92, v101
	v_add_f32_e32 v101, 1.0, v103
	v_mul_f32_e32 v96, v161, v96
	v_mul_f32_e32 v97, v161, v97
	v_mul_f32_e32 v98, v161, v98
	v_mul_f32_e32 v99, v99, v100
	v_rcp_f32_e32 v101, v101
	v_mul_f32_e32 v96, v44, v96
	v_mul_f32_e32 v97, v45, v97
	v_mul_f32_e32 v98, v46, v98
	v_mul_f32_e32 v99, v161, v99
	v_mul_f32_e32 v99, v47, v99
	v_cvt_pk_bf16_f32 v96, v96, v97
	v_cvt_pk_bf16_f32 v97, v98, v99
	s_waitcnt vmcnt(14)
	v_lshlrev_b32_e32 v98, 16, v162
	v_and_b32_e32 v99, 0xffff0000, v162
	v_mul_f32_e32 v94, v94, v145
	v_sub_f32_e32 v98, v98, v146
	v_mul_f32_e32 v95, v95, v145
	v_mul_f32_e32 v92, v92, v98
	v_mul_f32_e32 v93, v93, v101
	v_mul_f32_e32 v98, 0xbfb8aa3b, v94
	v_sub_f32_e32 v99, v99, v146
	v_exp_f32_e32 v98, v98
	v_mul_f32_e32 v93, v93, v99
	v_mul_f32_e32 v99, 0xbfb8aa3b, v95
	v_exp_f32_e32 v99, v99
	v_add_f32_e32 v98, 1.0, v98
	v_rcp_f32_e32 v98, v98
	v_lshlrev_b32_e32 v100, 16, v163
	v_add_f32_e32 v99, 1.0, v99
	v_rcp_f32_e32 v99, v99
	v_and_b32_e32 v102, 0xffff0000, v163
	v_mul_f32_e32 v94, v94, v98
	v_sub_f32_e32 v98, v100, v146
	v_mul_f32_e32 v94, v94, v98
	v_mul_f32_e32 v95, v95, v99
	v_sub_f32_e32 v98, v102, v146
	v_mul_f32_e32 v95, v95, v98
	v_mul_f32_e32 v92, v147, v92
	v_mul_f32_e32 v93, v147, v93
	v_mul_f32_e32 v95, v147, v95
	v_mul_f32_e32 v92, v68, v92
	v_mul_f32_e32 v93, v69, v93
	v_mul_f32_e32 v94, v147, v94
	v_mul_f32_e32 v95, v71, v95
	v_mul_f32_e32 v88, v88, v145
	v_mul_f32_e32 v94, v70, v94
	v_cvt_pk_bf16_f32 v92, v92, v93
	v_cvt_pk_bf16_f32 v93, v94, v95
	v_mul_f32_e32 v95, 0xbfb8aa3b, v88
	v_exp_f32_e32 v95, v95
	v_mul_f32_e32 v89, v89, v145
	v_mul_f32_e32 v99, 0xbfb8aa3b, v89
	v_exp_f32_e32 v99, v99
	v_add_f32_e32 v95, 1.0, v95
	v_rcp_f32_e32 v95, v95
	global_store_dwordx2 v[112:113], v[96:97], off offset:96
	v_lshl_add_u64 v[96:97], v[140:141], 0, v[164:165]
	global_store_dwordx2 v[96:97], v[92:93], off
	v_mul_f32_e32 v88, v88, v95
	v_add_f32_e32 v95, 1.0, v99
	v_rcp_f32_e32 v95, v95
	s_waitcnt vmcnt(15)
	v_lshlrev_b32_e32 v92, 16, v158
	v_and_b32_e32 v93, 0xffff0000, v158
	v_mul_f32_e32 v90, v90, v145
	v_sub_f32_e32 v92, v92, v146
	v_mul_f32_e32 v91, v91, v145
	v_mul_f32_e32 v88, v88, v92
	v_mul_f32_e32 v89, v89, v95
	v_mul_f32_e32 v92, 0xbfb8aa3b, v90
	v_sub_f32_e32 v93, v93, v146
	v_exp_f32_e32 v92, v92
	v_mul_f32_e32 v89, v89, v93
	v_mul_f32_e32 v93, 0xbfb8aa3b, v91
	v_exp_f32_e32 v93, v93
	v_add_f32_e32 v92, 1.0, v92
	v_rcp_f32_e32 v92, v92
	v_lshlrev_b32_e32 v94, 16, v159
	v_add_f32_e32 v93, 1.0, v93
	v_rcp_f32_e32 v93, v93
	v_and_b32_e32 v98, 0xffff0000, v159
	v_mul_f32_e32 v90, v90, v92
	v_sub_f32_e32 v92, v94, v146
	v_mul_f32_e32 v90, v90, v92
	v_mul_f32_e32 v91, v91, v93
	v_sub_f32_e32 v92, v98, v146
	v_mul_f32_e32 v91, v91, v92
	v_mul_f32_e32 v88, v147, v88
	v_mul_f32_e32 v89, v147, v89
	v_mul_f32_e32 v91, v147, v91
	v_mul_f32_e32 v88, v60, v88
	v_mul_f32_e32 v89, v61, v89
	v_mul_f32_e32 v90, v147, v90
	v_mul_f32_e32 v91, v63, v91
	v_mul_f32_e32 v84, v84, v145
	v_mul_f32_e32 v90, v62, v90
	v_cvt_pk_bf16_f32 v88, v88, v89
	v_cvt_pk_bf16_f32 v89, v90, v91
	v_mul_f32_e32 v91, 0xbfb8aa3b, v84
	v_exp_f32_e32 v91, v91
	v_mul_f32_e32 v85, v85, v145
	v_mul_f32_e32 v93, 0xbfb8aa3b, v85
	v_exp_f32_e32 v93, v93
	v_add_f32_e32 v91, 1.0, v91
	v_rcp_f32_e32 v91, v91
	global_store_dwordx2 v[96:97], v[88:89], off offset:32
	s_waitcnt vmcnt(15)
	v_lshlrev_b32_e32 v88, 16, v156
	v_and_b32_e32 v89, 0xffff0000, v156
	v_mul_f32_e32 v84, v84, v91
	v_add_f32_e32 v91, 1.0, v93
	v_rcp_f32_e32 v91, v91
	v_mul_f32_e32 v86, v86, v145
	v_sub_f32_e32 v88, v88, v146
	v_mul_f32_e32 v87, v87, v145
	v_mul_f32_e32 v84, v84, v88
	v_mul_f32_e32 v85, v85, v91
	v_mul_f32_e32 v88, 0xbfb8aa3b, v86
	v_sub_f32_e32 v89, v89, v146
	v_exp_f32_e32 v88, v88
	v_mul_f32_e32 v85, v85, v89
	v_mul_f32_e32 v89, 0xbfb8aa3b, v87
	v_exp_f32_e32 v89, v89
	v_add_f32_e32 v88, 1.0, v88
	v_rcp_f32_e32 v88, v88
	v_lshlrev_b32_e32 v90, 16, v157
	v_add_f32_e32 v89, 1.0, v89
	v_rcp_f32_e32 v89, v89
	v_and_b32_e32 v92, 0xffff0000, v157
	v_mul_f32_e32 v86, v86, v88
	v_sub_f32_e32 v88, v90, v146
	v_mul_f32_e32 v86, v86, v88
	v_mul_f32_e32 v87, v87, v89
	v_sub_f32_e32 v88, v92, v146
	v_mul_f32_e32 v87, v87, v88
	v_mul_f32_e32 v84, v147, v84
	v_mul_f32_e32 v85, v147, v85
	v_mul_f32_e32 v87, v147, v87
	v_mul_f32_e32 v84, v52, v84
	v_mul_f32_e32 v85, v53, v85
	v_mul_f32_e32 v86, v147, v86
	v_mul_f32_e32 v87, v55, v87
	v_mul_f32_e32 v80, v80, v145
	v_mul_f32_e32 v86, v54, v86
	v_cvt_pk_bf16_f32 v84, v84, v85
	v_cvt_pk_bf16_f32 v85, v86, v87
	v_mul_f32_e32 v87, 0xbfb8aa3b, v80
	v_exp_f32_e32 v87, v87
	v_mul_f32_e32 v81, v81, v145
	v_mul_f32_e32 v89, 0xbfb8aa3b, v81
	v_exp_f32_e32 v89, v89
	v_add_f32_e32 v87, 1.0, v87
	v_rcp_f32_e32 v87, v87
	global_store_dwordx2 v[96:97], v[84:85], off offset:64
	s_waitcnt vmcnt(15)
	v_lshlrev_b32_e32 v84, 16, v154
	v_and_b32_e32 v85, 0xffff0000, v154
	v_mul_f32_e32 v80, v80, v87
	v_add_f32_e32 v87, 1.0, v89
	v_rcp_f32_e32 v87, v87
	v_mul_f32_e32 v82, v82, v145
	v_sub_f32_e32 v84, v84, v146
	v_mul_f32_e32 v83, v83, v145
	v_mul_f32_e32 v80, v80, v84
	v_mul_f32_e32 v81, v81, v87
	v_mul_f32_e32 v84, 0xbfb8aa3b, v82
	v_sub_f32_e32 v85, v85, v146
	v_exp_f32_e32 v84, v84
	v_mul_f32_e32 v81, v81, v85
	v_mul_f32_e32 v85, 0xbfb8aa3b, v83
	v_exp_f32_e32 v85, v85
	v_add_f32_e32 v84, 1.0, v84
	v_rcp_f32_e32 v84, v84
	v_lshlrev_b32_e32 v86, 16, v155
	v_add_f32_e32 v85, 1.0, v85
	v_rcp_f32_e32 v85, v85
	v_and_b32_e32 v88, 0xffff0000, v155
	v_mul_f32_e32 v82, v82, v84
	v_sub_f32_e32 v84, v86, v146
	v_mul_f32_e32 v82, v82, v84
	v_mul_f32_e32 v83, v83, v85
	v_sub_f32_e32 v84, v88, v146
	v_mul_f32_e32 v80, v147, v80
	v_mul_f32_e32 v81, v147, v81
	v_mul_f32_e32 v83, v83, v84
	v_mul_f32_e32 v80, v44, v80
	v_mul_f32_e32 v81, v45, v81
	v_mul_f32_e32 v82, v147, v82
	v_mul_f32_e32 v83, v147, v83
	v_mul_f32_e32 v82, v46, v82
	v_mul_f32_e32 v83, v47, v83
	v_cvt_pk_bf16_f32 v80, v80, v81
	v_cvt_pk_bf16_f32 v81, v82, v83
	global_store_dwordx2 v[96:97], v[80:81], off offset:96
	v_or_b32_e32 v80, 64, v144
	v_ashrrev_i32_e32 v81, 31, v80
	v_lshlrev_b64 v[118:119], 12, v[80:81]
	v_lshl_add_u64 v[82:83], v[80:81], 2, s[6:7]
	v_lshlrev_b64 v[84:85], 5, v[80:81]
	v_lshl_add_u64 v[80:81], v[142:143], 0, v[118:119]
	v_lshl_add_u64 v[84:85], s[28:29], 0, v[84:85]
	global_load_dword v125, v[82:83], off
	global_load_dwordx2 v[112:113], v[84:85], off
	global_load_dwordx2 v[126:127], v[80:81], off
	global_load_dwordx2 v[128:129], v[80:81], off offset:32
	global_load_dwordx2 v[130:131], v[80:81], off offset:64
	global_load_dwordx2 v[120:121], v[80:81], off offset:96
	v_or_b32_e32 v80, 0x50, v144
	v_ashrrev_i32_e32 v81, 31, v80
	v_lshlrev_b64 v[116:117], 12, v[80:81]
	v_lshl_add_u64 v[82:83], v[80:81], 2, s[6:7]
	v_lshlrev_b64 v[84:85], 5, v[80:81]
	v_lshl_add_u64 v[80:81], v[142:143], 0, v[116:117]
	v_lshl_add_u64 v[84:85], s[28:29], 0, v[84:85]
	global_load_dword v124, v[82:83], off
	global_load_dwordx2 v[100:101], v[84:85], off
	global_load_dwordx2 v[114:115], v[80:81], off
	global_load_dwordx2 v[110:111], v[80:81], off offset:32
	global_load_dwordx2 v[108:109], v[80:81], off offset:64
	global_load_dwordx2 v[106:107], v[80:81], off offset:96
	v_or_b32_e32 v80, 0x60, v144
	v_ashrrev_i32_e32 v81, 31, v80
	v_lshl_add_u64 v[82:83], v[80:81], 2, s[6:7]
	v_lshlrev_b64 v[84:85], 5, v[80:81]
	v_lshl_add_u64 v[84:85], s[28:29], 0, v[84:85]
	global_load_dword v123, v[82:83], off
	global_load_dwordx2 v[88:89], v[84:85], off
	v_or_b32_e32 v82, 0x70, v144
	v_lshlrev_b64 v[104:105], 12, v[80:81]
	v_ashrrev_i32_e32 v83, 31, v82
	v_lshl_add_u64 v[80:81], v[142:143], 0, v[104:105]
	v_lshlrev_b64 v[84:85], 5, v[82:83]
	v_lshlrev_b64 v[92:93], 12, v[82:83]
	global_load_dwordx2 v[102:103], v[80:81], off
	global_load_dwordx2 v[98:99], v[80:81], off offset:32
	global_load_dwordx2 v[96:97], v[80:81], off offset:64
	global_load_dwordx2 v[94:95], v[80:81], off offset:96
	v_lshl_add_u64 v[80:81], v[82:83], 2, s[6:7]
	v_lshl_add_u64 v[84:85], s[28:29], 0, v[84:85]
	v_lshl_add_u64 v[82:83], v[142:143], 0, v[92:93]
	global_load_dword v122, v[80:81], off
	s_nop 0
	global_load_dwordx2 v[80:81], v[84:85], off
	global_load_dwordx2 v[90:91], v[82:83], off
	global_load_dwordx2 v[86:87], v[82:83], off offset:32
	s_nop 0
	global_load_dwordx2 v[84:85], v[82:83], off offset:64
	s_nop 0
	global_load_dwordx2 v[82:83], v[82:83], off offset:96
	s_waitcnt vmcnt(23)
	v_mul_f32_e32 v76, v76, v125
	v_mul_f32_e32 v134, 0xbfb8aa3b, v76
	v_exp_f32_e32 v134, v134
	v_mul_f32_e32 v77, v77, v125
	v_mul_f32_e32 v135, 0xbfb8aa3b, v77
	v_exp_f32_e32 v135, v135
	v_add_f32_e32 v134, 1.0, v134
	v_rcp_f32_e32 v134, v134
	s_waitcnt vmcnt(21)
	v_lshlrev_b32_e32 v132, 16, v126
	v_mul_f32_e32 v78, v78, v125
	v_sub_f32_e32 v132, v132, v112
	v_mul_f32_e32 v76, v76, v134
	v_add_f32_e32 v134, 1.0, v135
	v_rcp_f32_e32 v134, v134
	v_mul_f32_e32 v76, v76, v132
	v_mul_f32_e32 v132, 0xbfb8aa3b, v78
	v_exp_f32_e32 v132, v132
	v_and_b32_e32 v126, 0xffff0000, v126
	v_mul_f32_e32 v79, v79, v125
	v_mul_f32_e32 v77, v77, v134
	v_sub_f32_e32 v126, v126, v112
	v_mul_f32_e32 v77, v77, v126
	v_add_f32_e32 v126, 1.0, v132
	v_mul_f32_e32 v132, 0xbfb8aa3b, v79
	v_exp_f32_e32 v132, v132
	v_rcp_f32_e32 v126, v126
	v_lshlrev_b32_e32 v133, 16, v127
	v_and_b32_e32 v127, 0xffff0000, v127
	v_add_f32_e32 v132, 1.0, v132
	v_rcp_f32_e32 v132, v132
	v_mul_f32_e32 v78, v78, v126
	v_sub_f32_e32 v126, v133, v112
	v_mul_f32_e32 v78, v78, v126
	v_mul_f32_e32 v79, v79, v132
	v_sub_f32_e32 v126, v127, v112
	v_mul_f32_e32 v79, v79, v126
	v_mul_f32_e32 v76, v113, v76
	v_mul_f32_e32 v77, v113, v77
	v_mul_f32_e32 v79, v113, v79
	v_mul_f32_e32 v76, v68, v76
	v_mul_f32_e32 v77, v69, v77
	v_mul_f32_e32 v78, v113, v78
	v_mul_f32_e32 v79, v71, v79
	v_mul_f32_e32 v72, v72, v125
	v_mul_f32_e32 v78, v70, v78
	v_cvt_pk_bf16_f32 v76, v76, v77
	v_cvt_pk_bf16_f32 v77, v78, v79
	v_mul_f32_e32 v79, 0xbfb8aa3b, v72
	v_exp_f32_e32 v79, v79
	v_mul_f32_e32 v73, v73, v125
	v_mul_f32_e32 v127, 0xbfb8aa3b, v73
	v_exp_f32_e32 v127, v127
	v_add_f32_e32 v79, 1.0, v79
	v_rcp_f32_e32 v79, v79
	v_lshl_add_u64 v[118:119], v[140:141], 0, v[118:119]
	global_store_dwordx2 v[118:119], v[76:77], off
	s_waitcnt vmcnt(21)
	v_lshlrev_b32_e32 v76, 16, v128
	v_mul_f32_e32 v72, v72, v79
	v_add_f32_e32 v79, 1.0, v127
	v_rcp_f32_e32 v79, v79
	v_and_b32_e32 v77, 0xffff0000, v128
	v_mul_f32_e32 v74, v74, v125
	v_sub_f32_e32 v76, v76, v112
	v_mul_f32_e32 v75, v75, v125
	v_mul_f32_e32 v72, v72, v76
	v_mul_f32_e32 v73, v73, v79
	v_mul_f32_e32 v76, 0xbfb8aa3b, v74
	v_sub_f32_e32 v77, v77, v112
	v_exp_f32_e32 v76, v76
	v_mul_f32_e32 v73, v73, v77
	v_mul_f32_e32 v77, 0xbfb8aa3b, v75
	v_exp_f32_e32 v77, v77
	v_add_f32_e32 v76, 1.0, v76
	v_rcp_f32_e32 v76, v76
	v_lshlrev_b32_e32 v78, 16, v129
	v_add_f32_e32 v77, 1.0, v77
	v_rcp_f32_e32 v77, v77
	v_and_b32_e32 v126, 0xffff0000, v129
	v_mul_f32_e32 v74, v74, v76
	v_sub_f32_e32 v76, v78, v112
	v_mul_f32_e32 v74, v74, v76
	v_mul_f32_e32 v75, v75, v77
	v_sub_f32_e32 v76, v126, v112
	v_mul_f32_e32 v75, v75, v76
	v_mul_f32_e32 v72, v113, v72
	v_mul_f32_e32 v73, v113, v73
	v_mul_f32_e32 v75, v113, v75
	v_mul_f32_e32 v72, v60, v72
	v_mul_f32_e32 v73, v61, v73
	v_mul_f32_e32 v74, v113, v74
	v_mul_f32_e32 v75, v63, v75
	v_mul_f32_e32 v64, v64, v125
	v_mul_f32_e32 v74, v62, v74
	v_cvt_pk_bf16_f32 v72, v72, v73
	v_cvt_pk_bf16_f32 v73, v74, v75
	v_mul_f32_e32 v75, 0xbfb8aa3b, v64
	v_exp_f32_e32 v75, v75
	v_mul_f32_e32 v65, v65, v125
	v_mul_f32_e32 v77, 0xbfb8aa3b, v65
	v_exp_f32_e32 v77, v77
	v_add_f32_e32 v75, 1.0, v75
	v_rcp_f32_e32 v75, v75
	global_store_dwordx2 v[118:119], v[72:73], off offset:32
	s_waitcnt vmcnt(21)
	v_lshlrev_b32_e32 v72, 16, v130
	v_and_b32_e32 v73, 0xffff0000, v130
	v_mul_f32_e32 v64, v64, v75
	v_add_f32_e32 v75, 1.0, v77
	v_rcp_f32_e32 v75, v75
	v_mul_f32_e32 v66, v66, v125
	v_sub_f32_e32 v72, v72, v112
	v_mul_f32_e32 v67, v67, v125
	v_mul_f32_e32 v64, v64, v72
	v_mul_f32_e32 v65, v65, v75
	v_mul_f32_e32 v72, 0xbfb8aa3b, v66
	v_sub_f32_e32 v73, v73, v112
	v_exp_f32_e32 v72, v72
	v_mul_f32_e32 v65, v65, v73
	v_mul_f32_e32 v73, 0xbfb8aa3b, v67
	v_exp_f32_e32 v73, v73
	v_add_f32_e32 v72, 1.0, v72
	v_rcp_f32_e32 v72, v72
	v_lshlrev_b32_e32 v74, 16, v131
	v_add_f32_e32 v73, 1.0, v73
	v_rcp_f32_e32 v73, v73
	v_and_b32_e32 v76, 0xffff0000, v131
	v_mul_f32_e32 v66, v66, v72
	v_sub_f32_e32 v72, v74, v112
	v_mul_f32_e32 v66, v66, v72
	v_mul_f32_e32 v67, v67, v73
	v_sub_f32_e32 v72, v76, v112
	v_mul_f32_e32 v67, v67, v72
	v_mul_f32_e32 v64, v113, v64
	v_mul_f32_e32 v65, v113, v65
	v_mul_f32_e32 v67, v113, v67
	v_mul_f32_e32 v64, v52, v64
	v_mul_f32_e32 v65, v53, v65
	v_mul_f32_e32 v66, v113, v66
	v_mul_f32_e32 v67, v55, v67
	v_mul_f32_e32 v56, v56, v125
	v_mul_f32_e32 v66, v54, v66
	v_cvt_pk_bf16_f32 v64, v64, v65
	v_cvt_pk_bf16_f32 v65, v66, v67
	v_mul_f32_e32 v67, 0xbfb8aa3b, v56
	v_exp_f32_e32 v67, v67
	v_mul_f32_e32 v57, v57, v125
	v_mul_f32_e32 v73, 0xbfb8aa3b, v57
	v_exp_f32_e32 v73, v73
	v_add_f32_e32 v67, 1.0, v67
	v_rcp_f32_e32 v67, v67
	global_store_dwordx2 v[118:119], v[64:65], off offset:64
	s_waitcnt vmcnt(21)
	v_and_b32_e32 v65, 0xffff0000, v120
	v_mul_f32_e32 v59, v59, v125
	v_mul_f32_e32 v56, v56, v67
	v_add_f32_e32 v67, 1.0, v73
	v_rcp_f32_e32 v67, v67
	v_sub_f32_e32 v65, v65, v112
	v_lshlrev_b32_e32 v64, 16, v120
	v_mul_f32_e32 v58, v58, v125
	v_mul_f32_e32 v57, v57, v67
	v_mul_f32_e32 v57, v57, v65
	v_mul_f32_e32 v65, 0xbfb8aa3b, v59
	v_exp_f32_e32 v65, v65
	v_sub_f32_e32 v64, v64, v112
	v_mul_f32_e32 v56, v56, v64
	v_mul_f32_e32 v64, 0xbfb8aa3b, v58
	v_add_f32_e32 v65, 1.0, v65
	v_rcp_f32_e32 v65, v65
	s_waitcnt vmcnt(20)
	v_mul_f32_e32 v48, v48, v124
	v_exp_f32_e32 v64, v64
	v_mul_f32_e32 v49, v49, v124
	v_mul_f32_e32 v59, v59, v65
	v_mul_f32_e32 v65, 0xbfb8aa3b, v48
	v_exp_f32_e32 v65, v65
	v_add_f32_e32 v64, 1.0, v64
	v_rcp_f32_e32 v64, v64
	v_mul_f32_e32 v67, 0xbfb8aa3b, v49
	v_add_f32_e32 v65, 1.0, v65
	v_rcp_f32_e32 v65, v65
	v_exp_f32_e32 v67, v67
	v_lshlrev_b32_e32 v66, 16, v121
	v_and_b32_e32 v72, 0xffff0000, v121
	v_mul_f32_e32 v58, v58, v64
	v_sub_f32_e32 v64, v66, v112
	v_mul_f32_e32 v58, v58, v64
	v_sub_f32_e32 v64, v72, v112
	v_mul_f32_e32 v48, v48, v65
	v_add_f32_e32 v65, 1.0, v67
	v_mul_f32_e32 v56, v113, v56
	v_mul_f32_e32 v57, v113, v57
	v_mul_f32_e32 v58, v113, v58
	v_mul_f32_e32 v59, v59, v64
	v_rcp_f32_e32 v65, v65
	v_mul_f32_e32 v56, v44, v56
	v_mul_f32_e32 v57, v45, v57
	v_mul_f32_e32 v58, v46, v58
	v_mul_f32_e32 v59, v113, v59
	v_mul_f32_e32 v59, v47, v59
	v_cvt_pk_bf16_f32 v56, v56, v57
	v_cvt_pk_bf16_f32 v57, v58, v59
	s_waitcnt vmcnt(18)
	v_lshlrev_b32_e32 v58, 16, v114
	v_and_b32_e32 v59, 0xffff0000, v114
	v_mul_f32_e32 v50, v50, v124
	v_sub_f32_e32 v58, v58, v100
	v_mul_f32_e32 v51, v51, v124
	v_mul_f32_e32 v48, v48, v58
	v_mul_f32_e32 v49, v49, v65
	v_mul_f32_e32 v58, 0xbfb8aa3b, v50
	v_sub_f32_e32 v59, v59, v100
	v_exp_f32_e32 v58, v58
	v_mul_f32_e32 v49, v49, v59
	v_mul_f32_e32 v59, 0xbfb8aa3b, v51
	v_exp_f32_e32 v59, v59
	v_add_f32_e32 v58, 1.0, v58
	v_rcp_f32_e32 v58, v58
	v_lshlrev_b32_e32 v64, 16, v115
	v_add_f32_e32 v59, 1.0, v59
	v_rcp_f32_e32 v59, v59
	v_and_b32_e32 v66, 0xffff0000, v115
	v_mul_f32_e32 v50, v50, v58
	v_sub_f32_e32 v58, v64, v100
	v_mul_f32_e32 v50, v50, v58
	v_mul_f32_e32 v51, v51, v59
	v_sub_f32_e32 v58, v66, v100
	v_mul_f32_e32 v51, v51, v58
	v_mul_f32_e32 v48, v101, v48
	v_mul_f32_e32 v49, v101, v49
	v_mul_f32_e32 v51, v101, v51
	v_mul_f32_e32 v48, v68, v48
	v_mul_f32_e32 v49, v69, v49
	v_mul_f32_e32 v50, v101, v50
	v_mul_f32_e32 v51, v71, v51
	v_mul_f32_e32 v40, v40, v124
	v_mul_f32_e32 v50, v70, v50
	v_cvt_pk_bf16_f32 v48, v48, v49
	v_cvt_pk_bf16_f32 v49, v50, v51
	v_mul_f32_e32 v51, 0xbfb8aa3b, v40
	v_exp_f32_e32 v51, v51
	v_mul_f32_e32 v41, v41, v124
	v_mul_f32_e32 v59, 0xbfb8aa3b, v41
	v_exp_f32_e32 v59, v59
	v_add_f32_e32 v51, 1.0, v51
	v_rcp_f32_e32 v51, v51
	global_store_dwordx2 v[118:119], v[56:57], off offset:96
	v_lshl_add_u64 v[56:57], v[140:141], 0, v[116:117]
	global_store_dwordx2 v[56:57], v[48:49], off
	v_mul_f32_e32 v40, v40, v51
	v_add_f32_e32 v51, 1.0, v59
	v_rcp_f32_e32 v51, v51
	s_waitcnt vmcnt(19)
	v_lshlrev_b32_e32 v48, 16, v110
	v_and_b32_e32 v49, 0xffff0000, v110
	v_mul_f32_e32 v42, v42, v124
	v_sub_f32_e32 v48, v48, v100
	v_mul_f32_e32 v43, v43, v124
	v_mul_f32_e32 v40, v40, v48
	v_mul_f32_e32 v41, v41, v51
	v_mul_f32_e32 v48, 0xbfb8aa3b, v42
	v_sub_f32_e32 v49, v49, v100
	v_exp_f32_e32 v48, v48
	v_mul_f32_e32 v41, v41, v49
	v_mul_f32_e32 v49, 0xbfb8aa3b, v43
	v_exp_f32_e32 v49, v49
	v_add_f32_e32 v48, 1.0, v48
	v_rcp_f32_e32 v48, v48
	v_lshlrev_b32_e32 v50, 16, v111
	v_add_f32_e32 v49, 1.0, v49
	v_rcp_f32_e32 v49, v49
	v_and_b32_e32 v58, 0xffff0000, v111
	v_mul_f32_e32 v42, v42, v48
	v_sub_f32_e32 v48, v50, v100
	v_mul_f32_e32 v42, v42, v48
	v_mul_f32_e32 v43, v43, v49
	v_sub_f32_e32 v48, v58, v100
	v_mul_f32_e32 v43, v43, v48
	v_mul_f32_e32 v40, v101, v40
	v_mul_f32_e32 v41, v101, v41
	v_mul_f32_e32 v43, v101, v43
	v_mul_f32_e32 v40, v60, v40
	v_mul_f32_e32 v41, v61, v41
	v_mul_f32_e32 v42, v101, v42
	v_mul_f32_e32 v43, v63, v43
	v_mul_f32_e32 v36, v36, v124
	v_mul_f32_e32 v42, v62, v42
	v_cvt_pk_bf16_f32 v40, v40, v41
	v_cvt_pk_bf16_f32 v41, v42, v43
	v_mul_f32_e32 v43, 0xbfb8aa3b, v36
	v_exp_f32_e32 v43, v43
	v_mul_f32_e32 v37, v37, v124
	v_mul_f32_e32 v49, 0xbfb8aa3b, v37
	v_exp_f32_e32 v49, v49
	v_add_f32_e32 v43, 1.0, v43
	v_rcp_f32_e32 v43, v43
	global_store_dwordx2 v[56:57], v[40:41], off offset:32
	s_waitcnt vmcnt(19)
	v_lshlrev_b32_e32 v40, 16, v108
	v_and_b32_e32 v41, 0xffff0000, v108
	v_mul_f32_e32 v36, v36, v43
	v_add_f32_e32 v43, 1.0, v49
	v_rcp_f32_e32 v43, v43
	v_mul_f32_e32 v38, v38, v124
	v_sub_f32_e32 v40, v40, v100
	v_mul_f32_e32 v39, v39, v124
	v_mul_f32_e32 v36, v36, v40
	v_mul_f32_e32 v37, v37, v43
	v_mul_f32_e32 v40, 0xbfb8aa3b, v38
	v_sub_f32_e32 v41, v41, v100
	v_exp_f32_e32 v40, v40
	v_mul_f32_e32 v37, v37, v41
	v_mul_f32_e32 v41, 0xbfb8aa3b, v39
	v_exp_f32_e32 v41, v41
	v_add_f32_e32 v40, 1.0, v40
	v_rcp_f32_e32 v40, v40
	v_lshlrev_b32_e32 v42, 16, v109
	v_add_f32_e32 v41, 1.0, v41
	v_rcp_f32_e32 v41, v41
	v_and_b32_e32 v48, 0xffff0000, v109
	v_mul_f32_e32 v38, v38, v40
	v_sub_f32_e32 v40, v42, v100
	v_mul_f32_e32 v38, v38, v40
	v_mul_f32_e32 v39, v39, v41
	v_sub_f32_e32 v40, v48, v100
	v_mul_f32_e32 v39, v39, v40
	v_mul_f32_e32 v36, v101, v36
	v_mul_f32_e32 v37, v101, v37
	v_mul_f32_e32 v39, v101, v39
	v_mul_f32_e32 v36, v52, v36
	v_mul_f32_e32 v37, v53, v37
	v_mul_f32_e32 v38, v101, v38
	v_mul_f32_e32 v39, v55, v39
	v_mul_f32_e32 v32, v32, v124
	v_mul_f32_e32 v38, v54, v38
	v_cvt_pk_bf16_f32 v36, v36, v37
	v_cvt_pk_bf16_f32 v37, v38, v39
	v_mul_f32_e32 v39, 0xbfb8aa3b, v32
	v_exp_f32_e32 v39, v39
	v_mul_f32_e32 v33, v33, v124
	v_mul_f32_e32 v41, 0xbfb8aa3b, v33
	v_exp_f32_e32 v41, v41
	v_add_f32_e32 v39, 1.0, v39
	v_rcp_f32_e32 v39, v39
	global_store_dwordx2 v[56:57], v[36:37], off offset:64
	s_waitcnt vmcnt(19)
	v_and_b32_e32 v37, 0xffff0000, v106
	v_mul_f32_e32 v35, v35, v124
	v_mul_f32_e32 v32, v32, v39
	v_add_f32_e32 v39, 1.0, v41
	v_rcp_f32_e32 v39, v39
	v_sub_f32_e32 v37, v37, v100
	v_lshlrev_b32_e32 v36, 16, v106
	v_mul_f32_e32 v34, v34, v124
	v_mul_f32_e32 v33, v33, v39
	v_mul_f32_e32 v33, v33, v37
	v_mul_f32_e32 v37, 0xbfb8aa3b, v35
	v_exp_f32_e32 v37, v37
	v_sub_f32_e32 v36, v36, v100
	v_mul_f32_e32 v32, v32, v36
	v_mul_f32_e32 v36, 0xbfb8aa3b, v34
	v_add_f32_e32 v37, 1.0, v37
	v_rcp_f32_e32 v37, v37
	s_waitcnt vmcnt(18)
	v_mul_f32_e32 v28, v28, v123
	v_exp_f32_e32 v36, v36
	v_mul_f32_e32 v29, v29, v123
	v_mul_f32_e32 v35, v35, v37
	v_mul_f32_e32 v37, 0xbfb8aa3b, v28
	v_exp_f32_e32 v37, v37
	v_add_f32_e32 v36, 1.0, v36
	v_rcp_f32_e32 v36, v36
	v_mul_f32_e32 v39, 0xbfb8aa3b, v29
	v_add_f32_e32 v37, 1.0, v37
	v_rcp_f32_e32 v37, v37
	v_exp_f32_e32 v39, v39
	v_lshlrev_b32_e32 v38, 16, v107
	v_and_b32_e32 v40, 0xffff0000, v107
	v_mul_f32_e32 v34, v34, v36
	v_sub_f32_e32 v36, v38, v100
	v_mul_f32_e32 v34, v34, v36
	v_sub_f32_e32 v36, v40, v100
	v_mul_f32_e32 v28, v28, v37
	v_add_f32_e32 v37, 1.0, v39
	v_mul_f32_e32 v32, v101, v32
	v_mul_f32_e32 v33, v101, v33
	v_mul_f32_e32 v34, v101, v34
	v_mul_f32_e32 v35, v35, v36
	v_rcp_f32_e32 v37, v37
	v_mul_f32_e32 v32, v44, v32
	v_mul_f32_e32 v33, v45, v33
	v_mul_f32_e32 v34, v46, v34
	v_mul_f32_e32 v35, v101, v35
	v_mul_f32_e32 v35, v47, v35
	v_cvt_pk_bf16_f32 v32, v32, v33
	v_cvt_pk_bf16_f32 v33, v34, v35
	s_waitcnt vmcnt(16)
	v_lshlrev_b32_e32 v34, 16, v102
	v_and_b32_e32 v35, 0xffff0000, v102
	v_mul_f32_e32 v30, v30, v123
	v_sub_f32_e32 v34, v34, v88
	v_mul_f32_e32 v31, v31, v123
	v_mul_f32_e32 v28, v28, v34
	v_mul_f32_e32 v29, v29, v37
	v_mul_f32_e32 v34, 0xbfb8aa3b, v30
	v_sub_f32_e32 v35, v35, v88
	v_exp_f32_e32 v34, v34
	v_mul_f32_e32 v29, v29, v35
	v_mul_f32_e32 v35, 0xbfb8aa3b, v31
	v_exp_f32_e32 v35, v35
	v_add_f32_e32 v34, 1.0, v34
	v_rcp_f32_e32 v34, v34
	v_lshlrev_b32_e32 v36, 16, v103
	v_add_f32_e32 v35, 1.0, v35
	v_rcp_f32_e32 v35, v35
	v_and_b32_e32 v38, 0xffff0000, v103
	v_mul_f32_e32 v30, v30, v34
	v_sub_f32_e32 v34, v36, v88
	v_mul_f32_e32 v30, v30, v34
	v_mul_f32_e32 v31, v31, v35
	v_sub_f32_e32 v34, v38, v88
	v_mul_f32_e32 v31, v31, v34
	v_mul_f32_e32 v28, v89, v28
	v_mul_f32_e32 v29, v89, v29
	v_mul_f32_e32 v31, v89, v31
	v_mul_f32_e32 v28, v68, v28
	v_mul_f32_e32 v29, v69, v29
	v_mul_f32_e32 v30, v89, v30
	v_mul_f32_e32 v31, v71, v31
	v_mul_f32_e32 v24, v24, v123
	v_mul_f32_e32 v30, v70, v30
	v_cvt_pk_bf16_f32 v28, v28, v29
	v_cvt_pk_bf16_f32 v29, v30, v31
	v_mul_f32_e32 v31, 0xbfb8aa3b, v24
	v_exp_f32_e32 v31, v31
	v_mul_f32_e32 v25, v25, v123
	v_mul_f32_e32 v35, 0xbfb8aa3b, v25
	v_exp_f32_e32 v35, v35
	v_add_f32_e32 v31, 1.0, v31
	v_rcp_f32_e32 v31, v31
	global_store_dwordx2 v[56:57], v[32:33], off offset:96
	v_lshl_add_u64 v[32:33], v[140:141], 0, v[104:105]
	global_store_dwordx2 v[32:33], v[28:29], off
	v_mul_f32_e32 v24, v24, v31
	v_add_f32_e32 v31, 1.0, v35
	v_rcp_f32_e32 v31, v31
	s_waitcnt vmcnt(17)
	v_lshlrev_b32_e32 v28, 16, v98
	v_and_b32_e32 v29, 0xffff0000, v98
	v_mul_f32_e32 v26, v26, v123
	v_sub_f32_e32 v28, v28, v88
	v_mul_f32_e32 v27, v27, v123
	v_mul_f32_e32 v24, v24, v28
	v_mul_f32_e32 v25, v25, v31
	v_mul_f32_e32 v28, 0xbfb8aa3b, v26
	v_sub_f32_e32 v29, v29, v88
	v_exp_f32_e32 v28, v28
	v_mul_f32_e32 v25, v25, v29
	v_mul_f32_e32 v29, 0xbfb8aa3b, v27
	v_exp_f32_e32 v29, v29
	v_add_f32_e32 v28, 1.0, v28
	v_rcp_f32_e32 v28, v28
	v_lshlrev_b32_e32 v30, 16, v99
	v_add_f32_e32 v29, 1.0, v29
	v_rcp_f32_e32 v29, v29
	v_and_b32_e32 v34, 0xffff0000, v99
	v_mul_f32_e32 v26, v26, v28
	v_sub_f32_e32 v28, v30, v88
	v_mul_f32_e32 v26, v26, v28
	v_mul_f32_e32 v27, v27, v29
	v_sub_f32_e32 v28, v34, v88
	v_mul_f32_e32 v27, v27, v28
	v_mul_f32_e32 v24, v89, v24
	v_mul_f32_e32 v25, v89, v25
	v_mul_f32_e32 v27, v89, v27
	v_mul_f32_e32 v24, v60, v24
	v_mul_f32_e32 v25, v61, v25
	v_mul_f32_e32 v26, v89, v26
	v_mul_f32_e32 v27, v63, v27
	v_mul_f32_e32 v20, v20, v123
	v_mul_f32_e32 v26, v62, v26
	v_cvt_pk_bf16_f32 v24, v24, v25
	v_cvt_pk_bf16_f32 v25, v26, v27
	v_mul_f32_e32 v27, 0xbfb8aa3b, v20
	v_exp_f32_e32 v27, v27
	v_mul_f32_e32 v21, v21, v123
	v_mul_f32_e32 v29, 0xbfb8aa3b, v21
	v_exp_f32_e32 v29, v29
	v_add_f32_e32 v27, 1.0, v27
	v_rcp_f32_e32 v27, v27
	global_store_dwordx2 v[32:33], v[24:25], off offset:32
	s_waitcnt vmcnt(17)
	v_lshlrev_b32_e32 v24, 16, v96
	v_and_b32_e32 v25, 0xffff0000, v96
	v_mul_f32_e32 v20, v20, v27
	v_add_f32_e32 v27, 1.0, v29
	v_rcp_f32_e32 v27, v27
	v_mul_f32_e32 v22, v22, v123
	v_sub_f32_e32 v24, v24, v88
	v_mul_f32_e32 v23, v23, v123
	v_mul_f32_e32 v20, v20, v24
	v_mul_f32_e32 v21, v21, v27
	v_mul_f32_e32 v24, 0xbfb8aa3b, v22
	v_sub_f32_e32 v25, v25, v88
	v_exp_f32_e32 v24, v24
	v_mul_f32_e32 v21, v21, v25
	v_mul_f32_e32 v25, 0xbfb8aa3b, v23
	v_exp_f32_e32 v25, v25
	v_add_f32_e32 v24, 1.0, v24
	v_rcp_f32_e32 v24, v24
	v_lshlrev_b32_e32 v26, 16, v97
	v_add_f32_e32 v25, 1.0, v25
	v_rcp_f32_e32 v25, v25
	v_and_b32_e32 v28, 0xffff0000, v97
	v_mul_f32_e32 v22, v22, v24
	v_sub_f32_e32 v24, v26, v88
	v_mul_f32_e32 v22, v22, v24
	v_mul_f32_e32 v23, v23, v25
	v_sub_f32_e32 v24, v28, v88
	v_mul_f32_e32 v23, v23, v24
	v_mul_f32_e32 v20, v89, v20
	v_mul_f32_e32 v21, v89, v21
	v_mul_f32_e32 v23, v89, v23
	v_mul_f32_e32 v20, v52, v20
	v_mul_f32_e32 v21, v53, v21
	v_mul_f32_e32 v22, v89, v22
	v_mul_f32_e32 v23, v55, v23
	v_mul_f32_e32 v16, v16, v123
	v_mul_f32_e32 v22, v54, v22
	v_cvt_pk_bf16_f32 v20, v20, v21
	v_cvt_pk_bf16_f32 v21, v22, v23
	v_mul_f32_e32 v23, 0xbfb8aa3b, v16
	v_exp_f32_e32 v23, v23
	v_mul_f32_e32 v17, v17, v123
	v_mul_f32_e32 v25, 0xbfb8aa3b, v17
	v_exp_f32_e32 v25, v25
	v_add_f32_e32 v23, 1.0, v23
	v_rcp_f32_e32 v23, v23
	global_store_dwordx2 v[32:33], v[20:21], off offset:64
	s_waitcnt vmcnt(17)
	v_and_b32_e32 v21, 0xffff0000, v94
	v_mul_f32_e32 v19, v19, v123
	v_mul_f32_e32 v16, v16, v23
	v_add_f32_e32 v23, 1.0, v25
	v_rcp_f32_e32 v23, v23
	v_sub_f32_e32 v21, v21, v88
	v_lshlrev_b32_e32 v20, 16, v94
	v_mul_f32_e32 v18, v18, v123
	v_mul_f32_e32 v17, v17, v23
	v_mul_f32_e32 v17, v17, v21
	v_mul_f32_e32 v21, 0xbfb8aa3b, v19
	v_exp_f32_e32 v21, v21
	v_sub_f32_e32 v20, v20, v88
	v_mul_f32_e32 v16, v16, v20
	v_mul_f32_e32 v20, 0xbfb8aa3b, v18
	v_add_f32_e32 v21, 1.0, v21
	v_rcp_f32_e32 v21, v21
	s_waitcnt vmcnt(16)
	v_mul_f32_e32 v12, v12, v122
	v_exp_f32_e32 v20, v20
	v_mul_f32_e32 v13, v13, v122
	v_mul_f32_e32 v19, v19, v21
	v_mul_f32_e32 v21, 0xbfb8aa3b, v12
	v_exp_f32_e32 v21, v21
	v_add_f32_e32 v20, 1.0, v20
	v_rcp_f32_e32 v20, v20
	v_mul_f32_e32 v23, 0xbfb8aa3b, v13
	v_add_f32_e32 v21, 1.0, v21
	v_rcp_f32_e32 v21, v21
	v_exp_f32_e32 v23, v23
	v_lshlrev_b32_e32 v22, 16, v95
	v_and_b32_e32 v24, 0xffff0000, v95
	v_mul_f32_e32 v18, v18, v20
	v_sub_f32_e32 v20, v22, v88
	v_mul_f32_e32 v18, v18, v20
	v_sub_f32_e32 v20, v24, v88
	v_mul_f32_e32 v12, v12, v21
	v_add_f32_e32 v21, 1.0, v23
	v_mul_f32_e32 v16, v89, v16
	v_mul_f32_e32 v17, v89, v17
	v_mul_f32_e32 v18, v89, v18
	v_mul_f32_e32 v19, v19, v20
	v_rcp_f32_e32 v21, v21
	v_mul_f32_e32 v16, v44, v16
	v_mul_f32_e32 v17, v45, v17
	v_mul_f32_e32 v18, v46, v18
	v_mul_f32_e32 v19, v89, v19
	v_mul_f32_e32 v19, v47, v19
	v_cvt_pk_bf16_f32 v16, v16, v17
	v_cvt_pk_bf16_f32 v17, v18, v19
	s_waitcnt vmcnt(14)
	v_lshlrev_b32_e32 v18, 16, v90
	v_and_b32_e32 v19, 0xffff0000, v90
	v_mul_f32_e32 v14, v14, v122
	v_sub_f32_e32 v18, v18, v80
	v_mul_f32_e32 v15, v15, v122
	v_mul_f32_e32 v12, v12, v18
	v_mul_f32_e32 v13, v13, v21
	v_mul_f32_e32 v18, 0xbfb8aa3b, v14
	v_sub_f32_e32 v19, v19, v80
	v_exp_f32_e32 v18, v18
	v_mul_f32_e32 v13, v13, v19
	v_mul_f32_e32 v19, 0xbfb8aa3b, v15
	v_exp_f32_e32 v19, v19
	v_add_f32_e32 v18, 1.0, v18
	v_rcp_f32_e32 v18, v18
	v_lshlrev_b32_e32 v20, 16, v91
	v_add_f32_e32 v19, 1.0, v19
	v_rcp_f32_e32 v19, v19
	v_and_b32_e32 v22, 0xffff0000, v91
	v_mul_f32_e32 v14, v14, v18
	v_sub_f32_e32 v18, v20, v80
	v_mul_f32_e32 v14, v14, v18
	v_mul_f32_e32 v15, v15, v19
	v_sub_f32_e32 v18, v22, v80
	v_mul_f32_e32 v15, v15, v18
	v_mul_f32_e32 v12, v81, v12
	v_mul_f32_e32 v13, v81, v13
	v_mul_f32_e32 v15, v81, v15
	v_mul_f32_e32 v12, v68, v12
	v_mul_f32_e32 v13, v69, v13
	v_mul_f32_e32 v14, v81, v14
	v_mul_f32_e32 v15, v71, v15
	v_mul_f32_e32 v8, v8, v122
	v_mul_f32_e32 v14, v70, v14
	v_cvt_pk_bf16_f32 v12, v12, v13
	v_cvt_pk_bf16_f32 v13, v14, v15
	v_mul_f32_e32 v15, 0xbfb8aa3b, v8
	v_exp_f32_e32 v15, v15
	v_mul_f32_e32 v9, v9, v122
	v_mul_f32_e32 v19, 0xbfb8aa3b, v9
	v_exp_f32_e32 v19, v19
	v_add_f32_e32 v15, 1.0, v15
	v_rcp_f32_e32 v15, v15
	global_store_dwordx2 v[32:33], v[16:17], off offset:96
	v_lshl_add_u64 v[16:17], v[140:141], 0, v[92:93]
	global_store_dwordx2 v[16:17], v[12:13], off
	v_mul_f32_e32 v8, v8, v15
	v_add_f32_e32 v15, 1.0, v19
	v_rcp_f32_e32 v15, v15
	s_waitcnt vmcnt(15)
	v_lshlrev_b32_e32 v12, 16, v86
	v_and_b32_e32 v13, 0xffff0000, v86
	v_mul_f32_e32 v10, v10, v122
	v_sub_f32_e32 v12, v12, v80
	v_mul_f32_e32 v11, v11, v122
	v_mul_f32_e32 v8, v8, v12
	v_mul_f32_e32 v9, v9, v15
	v_mul_f32_e32 v12, 0xbfb8aa3b, v10
	v_sub_f32_e32 v13, v13, v80
	v_exp_f32_e32 v12, v12
	v_mul_f32_e32 v9, v9, v13
	v_mul_f32_e32 v13, 0xbfb8aa3b, v11
	v_exp_f32_e32 v13, v13
	v_add_f32_e32 v12, 1.0, v12
	v_rcp_f32_e32 v12, v12
	v_lshlrev_b32_e32 v14, 16, v87
	v_add_f32_e32 v13, 1.0, v13
	v_rcp_f32_e32 v13, v13
	v_and_b32_e32 v18, 0xffff0000, v87
	v_mul_f32_e32 v10, v10, v12
	v_sub_f32_e32 v12, v14, v80
	v_mul_f32_e32 v10, v10, v12
	v_mul_f32_e32 v11, v11, v13
	v_sub_f32_e32 v12, v18, v80
	v_mul_f32_e32 v11, v11, v12
	v_mul_f32_e32 v8, v81, v8
	v_mul_f32_e32 v9, v81, v9
	v_mul_f32_e32 v11, v81, v11
	v_mul_f32_e32 v8, v60, v8
	v_mul_f32_e32 v9, v61, v9
	v_mul_f32_e32 v10, v81, v10
	v_mul_f32_e32 v11, v63, v11
	v_mul_f32_e32 v4, v4, v122
	v_mul_f32_e32 v10, v62, v10
	v_cvt_pk_bf16_f32 v8, v8, v9
	v_cvt_pk_bf16_f32 v9, v10, v11
	v_mul_f32_e32 v11, 0xbfb8aa3b, v4
	v_exp_f32_e32 v11, v11
	v_mul_f32_e32 v5, v5, v122
	v_mul_f32_e32 v13, 0xbfb8aa3b, v5
	v_exp_f32_e32 v13, v13
	v_add_f32_e32 v11, 1.0, v11
	v_rcp_f32_e32 v11, v11
	global_store_dwordx2 v[16:17], v[8:9], off offset:32
	s_waitcnt vmcnt(15)
	v_lshlrev_b32_e32 v8, 16, v84
	v_and_b32_e32 v9, 0xffff0000, v84
	v_mul_f32_e32 v4, v4, v11
	v_add_f32_e32 v11, 1.0, v13
	v_rcp_f32_e32 v11, v11
	v_mul_f32_e32 v6, v6, v122
	v_sub_f32_e32 v8, v8, v80
	v_mul_f32_e32 v7, v7, v122
	v_mul_f32_e32 v4, v4, v8
	v_mul_f32_e32 v5, v5, v11
	v_mul_f32_e32 v8, 0xbfb8aa3b, v6
	v_sub_f32_e32 v9, v9, v80
	v_exp_f32_e32 v8, v8
	v_mul_f32_e32 v5, v5, v9
	v_mul_f32_e32 v9, 0xbfb8aa3b, v7
	v_exp_f32_e32 v9, v9
	v_add_f32_e32 v8, 1.0, v8
	v_rcp_f32_e32 v8, v8
	v_lshlrev_b32_e32 v10, 16, v85
	v_add_f32_e32 v9, 1.0, v9
	v_rcp_f32_e32 v9, v9
	v_and_b32_e32 v12, 0xffff0000, v85
	v_mul_f32_e32 v6, v6, v8
	v_sub_f32_e32 v8, v10, v80
	v_mul_f32_e32 v6, v6, v8
	v_mul_f32_e32 v7, v7, v9
	v_sub_f32_e32 v8, v12, v80
	v_mul_f32_e32 v7, v7, v8
	v_mul_f32_e32 v4, v81, v4
	v_mul_f32_e32 v5, v81, v5
	v_mul_f32_e32 v7, v81, v7
	v_mul_f32_e32 v4, v52, v4
	v_mul_f32_e32 v5, v53, v5
	v_mul_f32_e32 v6, v81, v6
	v_mul_f32_e32 v7, v55, v7
	v_mul_f32_e32 v0, v0, v122
	v_mul_f32_e32 v6, v54, v6
	v_cvt_pk_bf16_f32 v4, v4, v5
	v_cvt_pk_bf16_f32 v5, v6, v7
	v_mul_f32_e32 v7, 0xbfb8aa3b, v0
	v_exp_f32_e32 v7, v7
	v_mul_f32_e32 v1, v1, v122
	v_mul_f32_e32 v9, 0xbfb8aa3b, v1
	v_exp_f32_e32 v9, v9
	v_add_f32_e32 v7, 1.0, v7
	v_rcp_f32_e32 v7, v7
	global_store_dwordx2 v[16:17], v[4:5], off offset:64
	s_waitcnt vmcnt(15)
	v_lshlrev_b32_e32 v4, 16, v82
	v_and_b32_e32 v5, 0xffff0000, v82
	v_mul_f32_e32 v0, v0, v7
	v_add_f32_e32 v7, 1.0, v9
	v_rcp_f32_e32 v7, v7
	v_mul_f32_e32 v2, v2, v122
	v_sub_f32_e32 v4, v4, v80
	v_mul_f32_e32 v3, v3, v122
	v_mul_f32_e32 v0, v0, v4
	v_mul_f32_e32 v1, v1, v7
	v_mul_f32_e32 v4, 0xbfb8aa3b, v2
	v_sub_f32_e32 v5, v5, v80
	v_exp_f32_e32 v4, v4
	v_mul_f32_e32 v1, v1, v5
	v_mul_f32_e32 v5, 0xbfb8aa3b, v3
	v_exp_f32_e32 v5, v5
	v_add_f32_e32 v4, 1.0, v4
	v_rcp_f32_e32 v4, v4
	v_lshlrev_b32_e32 v6, 16, v83
	v_add_f32_e32 v5, 1.0, v5
	v_rcp_f32_e32 v5, v5
	v_and_b32_e32 v8, 0xffff0000, v83
	v_mul_f32_e32 v2, v2, v4
	v_sub_f32_e32 v4, v6, v80
	v_mul_f32_e32 v2, v2, v4
	v_mul_f32_e32 v3, v3, v5
	v_sub_f32_e32 v4, v8, v80
	v_mul_f32_e32 v0, v81, v0
	v_mul_f32_e32 v1, v81, v1
	v_mul_f32_e32 v3, v3, v4
	v_mul_f32_e32 v0, v44, v0
	v_mul_f32_e32 v1, v45, v1
	v_mul_f32_e32 v2, v81, v2
	v_mul_f32_e32 v3, v81, v3
	v_mul_f32_e32 v2, v46, v2
	v_mul_f32_e32 v3, v47, v3
	v_cvt_pk_bf16_f32 v0, v0, v1
	v_cvt_pk_bf16_f32 v1, v2, v3
	global_store_dwordx2 v[16:17], v[0:1], off offset:96
	s_add_i32 s34, s34, s74
	s_cmpk_lt_i32 s34, 0x800
	s_cbranch_scc1 .LBB0_502

.LBB0_561:
	s_add_i32 s31, s29, 64
	s_min_u32 s22, s31, 0x7e0
	s_lshl_b32 s22, s22, 1
	v_lshl_add_u64 v[174:175], v[156:157], 0, s[22:23]
	global_load_dwordx4 v[178:181], v[174:175], off
	v_lshl_add_u64 v[174:175], v[158:159], 0, s[22:23]
	v_lshl_add_u64 v[170:171], v[152:153], 0, s[22:23]
	v_lshl_add_u64 v[186:187], v[160:161], 0, s[22:23]
	global_load_dwordx4 v[182:185], v[174:175], off
	v_lshl_add_u64 v[174:175], v[154:155], 0, s[22:23]
	v_lshl_add_u64 v[194:195], v[162:163], 0, s[22:23]
	global_load_dwordx4 v[170:173], v[170:171], off
	ds_read_b128 v[202:205], v168 offset:32768
	global_load_dwordx4 v[186:189], v[186:187], off
	ds_read_b128 v[206:209], v168 offset:33792
	global_load_dwordx4 v[190:193], v[174:175], off
	global_load_dwordx4 v[198:201], v[194:195], off
	ds_read_b128 v[210:213], v168 offset:34816
	ds_read_b128 v[214:217], v168 offset:35840
	ds_read_b128 v[222:225], v166
	ds_read_b128 v[226:229], v166 offset:1024
	ds_read_b128 v[230:233], v166 offset:2048
	ds_read_b128 v[234:237], v166 offset:3072
	ds_read_b128 v[238:241], v166 offset:4096
	ds_read_b128 v[242:245], v166 offset:5120
	ds_read_b128 v[246:249], v166 offset:6144
	ds_read_b128 v[250:253], v166 offset:7168
	s_setprio 1
	s_waitcnt lgkmcnt(7)
	v_mfma_f32_16x16x32_bf16 v[148:151], v[202:205], v[222:225], v[148:151]
	v_mfma_f32_16x16x32_bf16 v[144:147], v[206:209], v[222:225], v[144:147]
	v_mfma_f32_16x16x32_bf16 v[140:143], v[210:213], v[222:225], v[140:143]
	v_mfma_f32_16x16x32_bf16 v[136:139], v[214:217], v[222:225], v[136:139]
	s_waitcnt vmcnt(11)
	ds_write_b128 v164, v[112:115] offset:16384
	s_waitcnt lgkmcnt(7)
	v_mfma_f32_16x16x32_bf16 v[108:111], v[202:205], v[226:229], v[108:111]
	v_mfma_f32_16x16x32_bf16 v[104:107], v[206:209], v[226:229], v[104:107]
	v_mfma_f32_16x16x32_bf16 v[100:103], v[210:213], v[226:229], v[100:103]
	v_mfma_f32_16x16x32_bf16 v[96:99], v[214:217], v[226:229], v[96:99]
	s_waitcnt vmcnt(9)
	ds_write_b128 v164, v[120:123] offset:20480
	s_waitcnt lgkmcnt(7)
	v_mfma_f32_16x16x32_bf16 v[92:95], v[202:205], v[230:233], v[92:95]
	v_mfma_f32_16x16x32_bf16 v[88:91], v[206:209], v[230:233], v[88:91]
	v_mfma_f32_16x16x32_bf16 v[84:87], v[210:213], v[230:233], v[84:87]
	v_mfma_f32_16x16x32_bf16 v[80:83], v[214:217], v[230:233], v[80:83]
	s_waitcnt vmcnt(8)
	ds_write_b128 v164, v[124:127] offset:24576
	s_waitcnt lgkmcnt(7)
	v_mfma_f32_16x16x32_bf16 v[76:79], v[202:205], v[234:237], v[76:79]
	v_mfma_f32_16x16x32_bf16 v[72:75], v[206:209], v[234:237], v[72:75]
	v_mfma_f32_16x16x32_bf16 v[68:71], v[210:213], v[234:237], v[68:71]
	v_mfma_f32_16x16x32_bf16 v[64:67], v[214:217], v[234:237], v[64:67]
	s_waitcnt vmcnt(7)
	ds_write_b128 v164, v[128:131] offset:28672
	s_waitcnt lgkmcnt(7)
	v_mfma_f32_16x16x32_bf16 v[60:63], v[202:205], v[238:241], v[60:63]
	v_mfma_f32_16x16x32_bf16 v[56:59], v[206:209], v[238:241], v[56:59]
	v_mfma_f32_16x16x32_bf16 v[52:55], v[210:213], v[238:241], v[52:55]
	v_mfma_f32_16x16x32_bf16 v[48:51], v[214:217], v[238:241], v[48:51]
	s_waitcnt vmcnt(7)
	ds_write_b128 v164, v[116:119] offset:40960
	s_waitcnt lgkmcnt(7)
	v_mfma_f32_16x16x32_bf16 v[44:47], v[202:205], v[242:245], v[44:47]
	v_mfma_f32_16x16x32_bf16 v[40:43], v[206:209], v[242:245], v[40:43]
	v_mfma_f32_16x16x32_bf16 v[36:39], v[210:213], v[242:245], v[36:39]
	v_mfma_f32_16x16x32_bf16 v[32:35], v[214:217], v[242:245], v[32:35]
	s_waitcnt vmcnt(6)
	ds_write_b128 v164, v[132:135] offset:45056
	s_waitcnt lgkmcnt(7)
	v_mfma_f32_16x16x32_bf16 v[28:31], v[202:205], v[246:249], v[28:31]
	v_mfma_f32_16x16x32_bf16 v[24:27], v[206:209], v[246:249], v[24:27]
	v_mfma_f32_16x16x32_bf16 v[20:23], v[210:213], v[246:249], v[20:23]
	v_mfma_f32_16x16x32_bf16 v[16:19], v[214:217], v[246:249], v[16:19]
	s_waitcnt lgkmcnt(6)
	v_mfma_f32_16x16x32_bf16 v[12:15], v[202:205], v[250:253], v[12:15]
	v_mfma_f32_16x16x32_bf16 v[8:11], v[206:209], v[250:253], v[8:11]
	v_mfma_f32_16x16x32_bf16 v[4:7], v[210:213], v[250:253], v[4:7]
	v_mfma_f32_16x16x32_bf16 v[0:3], v[214:217], v[250:253], v[0:3]
	s_setprio 0
	s_min_u32 s22, s29, 0x780
	s_lshl_b32 s22, s22, 1
	s_mov_b32 s35, s23
	s_add_i32 s34, s22, 0xc0
	v_lshl_add_u64 v[112:113], v[152:153], 0, s[22:23]
	v_lshl_add_u64 v[116:117], v[154:155], 0, s[22:23]
	v_lshl_add_u64 v[120:121], v[156:157], 0, s[34:35]
	v_lshl_add_u64 v[124:125], v[158:159], 0, s[34:35]
	v_lshl_add_u64 v[128:129], v[160:161], 0, s[34:35]
	v_lshl_add_u64 v[132:133], v[162:163], 0, s[34:35]
	s_waitcnt lgkmcnt(0)
	s_barrier
	global_load_dwordx4 v[112:115], v[112:113], off offset:192
	ds_read_b128 v[202:205], v165 offset:40960
	global_load_dwordx4 v[116:119], v[116:117], off offset:192
	ds_read_b128 v[206:209], v165 offset:41984
	global_load_dwordx4 v[120:123], v[120:121], off
	ds_read_b128 v[210:213], v165 offset:43008
	global_load_dwordx4 v[124:127], v[124:125], off
	ds_read_b128 v[214:217], v165 offset:44032
	global_load_dwordx4 v[128:131], v[128:129], off
	ds_read_b128 v[222:225], v167
	global_load_dwordx4 v[132:135], v[132:133], off
	ds_read_b128 v[226:229], v167 offset:1024
	ds_read_b128 v[230:233], v167 offset:2048
	ds_read_b128 v[234:237], v167 offset:3072
	ds_read_b128 v[238:241], v167 offset:4096
	ds_read_b128 v[242:245], v167 offset:5120
	ds_read_b128 v[246:249], v167 offset:6144
	ds_read_b128 v[250:253], v167 offset:7168
	s_setprio 1
	s_waitcnt lgkmcnt(7)
	v_mfma_f32_16x16x32_bf16 v[148:151], v[202:205], v[222:225], v[148:151]
	v_mfma_f32_16x16x32_bf16 v[144:147], v[206:209], v[222:225], v[144:147]
	v_mfma_f32_16x16x32_bf16 v[140:143], v[210:213], v[222:225], v[140:143]
	v_mfma_f32_16x16x32_bf16 v[136:139], v[214:217], v[222:225], v[136:139]
	s_waitcnt vmcnt(9)
	ds_write_b128 v164, v[170:173]
	s_waitcnt lgkmcnt(7)
	v_mfma_f32_16x16x32_bf16 v[108:111], v[202:205], v[226:229], v[108:111]
	v_mfma_f32_16x16x32_bf16 v[104:107], v[206:209], v[226:229], v[104:107]
	v_mfma_f32_16x16x32_bf16 v[100:103], v[210:213], v[226:229], v[100:103]
	v_mfma_f32_16x16x32_bf16 v[96:99], v[214:217], v[226:229], v[96:99]
	ds_write_b128 v164, v[178:181] offset:4096
	s_waitcnt lgkmcnt(7)
	v_mfma_f32_16x16x32_bf16 v[92:95], v[202:205], v[230:233], v[92:95]
	v_mfma_f32_16x16x32_bf16 v[88:91], v[206:209], v[230:233], v[88:91]
	v_mfma_f32_16x16x32_bf16 v[84:87], v[210:213], v[230:233], v[84:87]
	v_mfma_f32_16x16x32_bf16 v[80:83], v[214:217], v[230:233], v[80:83]
	ds_write_b128 v164, v[182:185] offset:8192
	s_waitcnt lgkmcnt(7)
	v_mfma_f32_16x16x32_bf16 v[76:79], v[202:205], v[234:237], v[76:79]
	v_mfma_f32_16x16x32_bf16 v[72:75], v[206:209], v[234:237], v[72:75]
	v_mfma_f32_16x16x32_bf16 v[68:71], v[210:213], v[234:237], v[68:71]
	v_mfma_f32_16x16x32_bf16 v[64:67], v[214:217], v[234:237], v[64:67]
	s_waitcnt vmcnt(8)
	ds_write_b128 v164, v[186:189] offset:12288
	s_waitcnt lgkmcnt(7)
	v_mfma_f32_16x16x32_bf16 v[60:63], v[202:205], v[238:241], v[60:63]
	v_mfma_f32_16x16x32_bf16 v[56:59], v[206:209], v[238:241], v[56:59]
	v_mfma_f32_16x16x32_bf16 v[52:55], v[210:213], v[238:241], v[52:55]
	v_mfma_f32_16x16x32_bf16 v[48:51], v[214:217], v[238:241], v[48:51]
	s_waitcnt vmcnt(7)
	ds_write_b128 v164, v[190:193] offset:32768
	s_waitcnt lgkmcnt(7)
	v_mfma_f32_16x16x32_bf16 v[44:47], v[202:205], v[242:245], v[44:47]
	v_mfma_f32_16x16x32_bf16 v[40:43], v[206:209], v[242:245], v[40:43]
	v_mfma_f32_16x16x32_bf16 v[36:39], v[210:213], v[242:245], v[36:39]
	v_mfma_f32_16x16x32_bf16 v[32:35], v[214:217], v[242:245], v[32:35]
	s_waitcnt vmcnt(6)
	ds_write_b128 v164, v[198:201] offset:36864
	s_waitcnt lgkmcnt(7)
	v_mfma_f32_16x16x32_bf16 v[28:31], v[202:205], v[246:249], v[28:31]
	v_mfma_f32_16x16x32_bf16 v[24:27], v[206:209], v[246:249], v[24:27]
	v_mfma_f32_16x16x32_bf16 v[20:23], v[210:213], v[246:249], v[20:23]
	v_mfma_f32_16x16x32_bf16 v[16:19], v[214:217], v[246:249], v[16:19]
	s_waitcnt lgkmcnt(6)
	v_mfma_f32_16x16x32_bf16 v[12:15], v[202:205], v[250:253], v[12:15]
	v_mfma_f32_16x16x32_bf16 v[8:11], v[206:209], v[250:253], v[8:11]
	v_mfma_f32_16x16x32_bf16 v[4:7], v[210:213], v[250:253], v[4:7]
	v_mfma_f32_16x16x32_bf16 v[0:3], v[214:217], v[250:253], v[0:3]
	s_setprio 0
	s_add_i32 s25, s25, 2
	s_cmp_lt_u32 s25, 62
	s_mov_b32 s29, s31
	s_waitcnt lgkmcnt(0)
	s_barrier
	s_cbranch_scc1 .LBB0_561
	s_waitcnt vmcnt(5)
	v_mov_b32_e32 v112, v220
	v_readlane_b32 s36, v254, 6
	v_and_b32_e32 v114, 0xffffff80, v112
	v_bfe_u32 v176, v112, 4, 2
	v_add_u32_e32 v114, s28, v114
	v_and_b32_e32 v113, 64, v112
	v_and_or_b32 v180, v112, 15, v114
	v_lshlrev_b32_e32 v112, 2, v176
	v_or3_b32 v178, v112, v113, s24
	v_ashrrev_i32_e32 v179, 31, v178
	v_lshlrev_b64 v[214:215], 2, v[178:179]
	v_readlane_b32 s37, v254, 7
	v_ashrrev_i32_e32 v181, 31, v180
	v_or_b32_e32 v190, 16, v180
	v_lshl_add_u64 v[182:183], s[36:37], 0, v[214:215]
	v_lshlrev_b64 v[216:217], 12, v[180:181]
	v_ashrrev_i32_e32 v191, 31, v190
	v_or_b32_e32 v186, 32, v180
	v_lshl_add_u64 v[112:113], v[182:183], 0, v[216:217]
	v_lshlrev_b64 v[194:195], 12, v[190:191]
	v_ashrrev_i32_e32 v187, 31, v186
	v_or_b32_e32 v184, 48, v180
	global_load_dwordx4 v[198:201], v[112:113], off nt
	global_load_dwordx4 v[202:205], v[112:113], off offset:64 nt
	global_load_dwordx4 v[206:209], v[112:113], off offset:128 nt
	global_load_dwordx4 v[210:213], v[112:113], off offset:192 nt
	v_lshl_add_u64 v[112:113], v[182:183], 0, v[194:195]
	v_lshlrev_b64 v[192:193], 12, v[186:187]
	v_ashrrev_i32_e32 v185, 31, v184
	global_load_dwordx4 v[172:175], v[112:113], off nt
	global_load_dwordx4 v[168:171], v[112:113], off offset:64 nt
	global_load_dwordx4 v[164:167], v[112:113], off offset:128 nt
	global_load_dwordx4 v[160:163], v[112:113], off offset:192 nt
	v_lshl_add_u64 v[112:113], v[182:183], 0, v[192:193]
	v_lshlrev_b64 v[188:189], 12, v[184:185]
	global_load_dwordx4 v[156:159], v[112:113], off nt
	global_load_dwordx4 v[152:155], v[112:113], off offset:64 nt
	global_load_dwordx4 v[132:135], v[112:113], off offset:128 nt
	global_load_dwordx4 v[128:131], v[112:113], off offset:192 nt
	v_lshl_add_u64 v[112:113], v[182:183], 0, v[188:189]
	global_load_dwordx4 v[124:127], v[112:113], off nt
	global_load_dwordx4 v[120:123], v[112:113], off offset:64 nt
	global_load_dwordx4 v[116:119], v[112:113], off offset:128 nt
	s_nop 0
	global_load_dwordx4 v[112:115], v[112:113], off offset:192 nt
	v_cmp_eq_u32_e32 vcc, 0, v176
	v_readlane_b32 s38, v254, 8
	v_readlane_b32 s39, v254, 9
	v_readlane_b32 s40, v254, 10
	v_readlane_b32 s41, v254, 11
	v_readlane_b32 s42, v254, 12
	v_readlane_b32 s43, v254, 13
	v_readlane_b32 s44, v254, 14
	v_readlane_b32 s45, v254, 15
	v_readlane_b32 s46, v254, 16
	v_readlane_b32 s47, v254, 17
	v_readlane_b32 s48, v254, 18
	v_readlane_b32 s49, v254, 19
	v_readlane_b32 s50, v254, 20
	v_readlane_b32 s51, v254, 21
	v_lshl_add_u64 v[216:217], s[70:71], 0, v[216:217]
	s_waitcnt vmcnt(15)
	v_pk_add_f32 v[148:149], v[148:149], v[198:199]
	v_lshl_add_u64 v[214:215], v[216:217], 0, v[214:215]
	v_pk_add_f32 v[150:151], v[150:151], v[200:201]
	v_mul_f32_e32 v176, v149, v149
	global_store_dwordx4 v[214:215], v[148:151], off
	v_cvt_pk_bf16_f32 v198, v148, v149
	v_lshlrev_b64 v[200:201], 11, v[180:181]
	v_cvt_pk_bf16_f32 v199, v150, v151
	v_lshl_add_u64 v[200:201], s[6:7], 0, v[200:201]
	v_pk_fma_f32 v[148:149], v[148:149], v[148:149], v[176:177] op_sel_hi:[1,1,0]
	v_lshl_add_u64 v[200:201], v[178:179], 1, v[200:201]
	v_pk_fma_f32 v[148:149], v[150:151], v[150:151], v[148:149]
	v_mul_f32_e32 v150, v151, v151
	v_pk_add_f32 v[148:149], v[150:151], v[148:149] op_sel_hi:[0,1]
	s_waitcnt vmcnt(15)
	v_pk_add_f32 v[146:147], v[146:147], v[204:205]
	v_pk_add_f32 v[144:145], v[144:145], v[202:203]
	global_store_dwordx2 v[200:201], v[198:199], off
	v_cvt_pk_bf16_f32 v150, v144, v145
	global_store_dwordx4 v[214:215], v[144:147], off offset:64
	v_cvt_pk_bf16_f32 v151, v146, v147
	global_store_dwordx2 v[200:201], v[150:151], off offset:32
	v_mul_f32_e32 v150, v145, v145
	v_pk_fma_f32 v[144:145], v[144:145], v[144:145], v[150:151] op_sel_hi:[1,1,0]
	s_waitcnt vmcnt(17)
	v_pk_add_f32 v[142:143], v[142:143], v[208:209]
	v_pk_fma_f32 v[144:145], v[146:147], v[146:147], v[144:145]
	v_mul_f32_e32 v146, v147, v147
	v_pk_add_f32 v[144:145], v[146:147], v[144:145] op_sel_hi:[0,1]
	v_pk_add_f32 v[140:141], v[140:141], v[206:207]
	global_store_dwordx4 v[214:215], v[140:143], off offset:128
	v_cvt_pk_bf16_f32 v146, v140, v141
	v_cvt_pk_bf16_f32 v147, v142, v143
	global_store_dwordx2 v[200:201], v[146:147], off offset:64
	v_mul_f32_e32 v146, v141, v141
	v_pk_fma_f32 v[140:141], v[140:141], v[140:141], v[146:147] op_sel_hi:[1,1,0]
	s_waitcnt vmcnt(18)
	v_pk_add_f32 v[138:139], v[138:139], v[212:213]
	v_pk_fma_f32 v[140:141], v[142:143], v[142:143], v[140:141]
	v_mul_f32_e32 v142, v143, v143
	v_pk_add_f32 v[140:141], v[142:143], v[140:141] op_sel_hi:[0,1]
	v_pk_add_f32 v[136:137], v[136:137], v[210:211]
	global_store_dwordx4 v[214:215], v[136:139], off offset:192
	v_cvt_pk_bf16_f32 v142, v136, v137
	v_cvt_pk_bf16_f32 v143, v138, v139
	global_store_dwordx2 v[200:201], v[142:143], off offset:96
	v_mul_f32_e32 v142, v137, v137
	v_pk_fma_f32 v[136:137], v[136:137], v[136:137], v[142:143] op_sel_hi:[1,1,0]
	v_pk_add_f32 v[144:145], v[148:149], v[144:145]
	v_pk_fma_f32 v[136:137], v[138:139], v[138:139], v[136:137]
	v_mul_f32_e32 v138, v139, v139
	v_pk_add_f32 v[140:141], v[144:145], v[140:141]
	v_pk_add_f32 v[136:137], v[138:139], v[136:137] op_sel_hi:[0,1]
	v_pk_add_f32 v[136:137], v[140:141], v[136:137]
	s_nop 0
	v_mov_b32_e32 v137, v136
	s_nop 1
	v_permlane32_swap_b32_e32 v136, v137
	v_add_f32_e32 v136, v136, v137
	v_mov_b32_e32 v137, v136
	s_nop 1
	v_permlane16_swap_b32_e32 v136, v137
	s_and_saveexec_b64 s[24:25], vcc
	s_cbranch_execz .LBB0_564
	v_lshl_add_u64 v[138:139], v[180:181], 2, s[10:11]
	v_add_f32_e32 v136, v136, v137
	global_atomic_add_f32 v[138:139], v136, off

.LBB0_706:
	s_add_i32 s11, s10, 64
	s_min_u32 s13, s11, 0x3e0
	s_lshl_b32 s16, s13, 1
	v_lshl_add_u64 v[172:173], v[154:155], 0, s[16:17]
	v_lshl_add_u64 v[176:177], v[158:159], 0, s[16:17]
	v_lshl_add_u64 v[180:181], v[160:161], 0, s[16:17]
	v_lshl_add_u64 v[184:185], v[162:163], 0, s[16:17]
	v_lshl_add_u64 v[188:189], v[156:157], 0, s[16:17]
	v_lshl_add_u64 v[192:193], v[164:165], 0, s[16:17]
	global_load_dwordx4 v[172:175], v[172:173], off
	ds_read_b128 v[196:199], v171 offset:32768
	global_load_dwordx4 v[176:179], v[176:177], off
	ds_read_b128 v[200:203], v171 offset:33792
	global_load_dwordx4 v[180:183], v[180:181], off
	ds_read_b128 v[204:207], v171 offset:34816
	global_load_dwordx4 v[184:187], v[184:185], off
	ds_read_b128 v[208:211], v171 offset:35840
	global_load_dwordx4 v[188:191], v[188:189], off
	ds_read_b128 v[212:215], v169
	global_load_dwordx4 v[192:195], v[192:193], off
	ds_read_b128 v[216:219], v169 offset:1024
	ds_read_b128 v[222:225], v169 offset:2048
	ds_read_b128 v[226:229], v169 offset:3072
	ds_read_b128 v[230:233], v169 offset:4096
	ds_read_b128 v[234:237], v169 offset:5120
	ds_read_b128 v[238:241], v169 offset:6144
	ds_read_b128 v[242:245], v169 offset:7168
	s_setprio 1
	s_waitcnt lgkmcnt(7)
	v_mfma_f32_16x16x32_bf16 v[148:151], v[196:199], v[212:215], v[148:151]
	v_mfma_f32_16x16x32_bf16 v[144:147], v[200:203], v[212:215], v[144:147]
	v_mfma_f32_16x16x32_bf16 v[140:143], v[204:207], v[212:215], v[140:143]
	v_mfma_f32_16x16x32_bf16 v[136:139], v[208:211], v[212:215], v[136:139]
	s_waitcnt vmcnt(11)
	ds_write_b128 v152, v[112:115] offset:16384
	s_waitcnt lgkmcnt(7)
	v_mfma_f32_16x16x32_bf16 v[108:111], v[196:199], v[216:219], v[108:111]
	v_mfma_f32_16x16x32_bf16 v[104:107], v[200:203], v[216:219], v[104:107]
	v_mfma_f32_16x16x32_bf16 v[100:103], v[204:207], v[216:219], v[100:103]
	v_mfma_f32_16x16x32_bf16 v[96:99], v[208:211], v[216:219], v[96:99]
	s_waitcnt vmcnt(9)
	ds_write_b128 v152, v[120:123] offset:20480
	s_waitcnt lgkmcnt(7)
	v_mfma_f32_16x16x32_bf16 v[92:95], v[196:199], v[222:225], v[92:95]
	v_mfma_f32_16x16x32_bf16 v[88:91], v[200:203], v[222:225], v[88:91]
	v_mfma_f32_16x16x32_bf16 v[84:87], v[204:207], v[222:225], v[84:87]
	v_mfma_f32_16x16x32_bf16 v[80:83], v[208:211], v[222:225], v[80:83]
	s_waitcnt vmcnt(8)
	ds_write_b128 v152, v[124:127] offset:24576
	s_waitcnt lgkmcnt(7)
	v_mfma_f32_16x16x32_bf16 v[76:79], v[196:199], v[226:229], v[76:79]
	v_mfma_f32_16x16x32_bf16 v[72:75], v[200:203], v[226:229], v[72:75]
	v_mfma_f32_16x16x32_bf16 v[68:71], v[204:207], v[226:229], v[68:71]
	v_mfma_f32_16x16x32_bf16 v[64:67], v[208:211], v[226:229], v[64:67]
	s_waitcnt vmcnt(7)
	ds_write_b128 v152, v[128:131] offset:28672
	s_waitcnt lgkmcnt(7)
	v_mfma_f32_16x16x32_bf16 v[60:63], v[196:199], v[230:233], v[60:63]
	v_mfma_f32_16x16x32_bf16 v[56:59], v[200:203], v[230:233], v[56:59]
	v_mfma_f32_16x16x32_bf16 v[52:55], v[204:207], v[230:233], v[52:55]
	v_mfma_f32_16x16x32_bf16 v[48:51], v[208:211], v[230:233], v[48:51]
	s_waitcnt vmcnt(7)
	ds_write_b128 v152, v[116:119] offset:40960
	s_waitcnt lgkmcnt(7)
	v_mfma_f32_16x16x32_bf16 v[44:47], v[196:199], v[234:237], v[44:47]
	v_mfma_f32_16x16x32_bf16 v[40:43], v[200:203], v[234:237], v[40:43]
	v_mfma_f32_16x16x32_bf16 v[36:39], v[204:207], v[234:237], v[36:39]
	v_mfma_f32_16x16x32_bf16 v[32:35], v[208:211], v[234:237], v[32:35]
	s_waitcnt vmcnt(6)
	ds_write_b128 v152, v[132:135] offset:45056
	s_waitcnt lgkmcnt(7)
	v_mfma_f32_16x16x32_bf16 v[28:31], v[196:199], v[238:241], v[28:31]
	v_mfma_f32_16x16x32_bf16 v[24:27], v[200:203], v[238:241], v[24:27]
	v_mfma_f32_16x16x32_bf16 v[20:23], v[204:207], v[238:241], v[20:23]
	v_mfma_f32_16x16x32_bf16 v[16:19], v[208:211], v[238:241], v[16:19]
	s_waitcnt lgkmcnt(6)
	v_mfma_f32_16x16x32_bf16 v[12:15], v[196:199], v[242:245], v[12:15]
	v_mfma_f32_16x16x32_bf16 v[8:11], v[200:203], v[242:245], v[8:11]
	v_mfma_f32_16x16x32_bf16 v[4:7], v[204:207], v[242:245], v[4:7]
	v_mfma_f32_16x16x32_bf16 v[0:3], v[208:211], v[242:245], v[0:3]
	s_setprio 0
	s_min_u32 s10, s10, 0x380
	s_lshl_b32 s16, s10, 1
	s_mov_b32 s27, s17
	s_add_i32 s26, s16, 0xc0
	v_lshl_add_u64 v[112:113], v[154:155], 0, s[16:17]
	v_lshl_add_u64 v[116:117], v[156:157], 0, s[16:17]
	v_lshl_add_u64 v[120:121], v[158:159], 0, s[26:27]
	v_lshl_add_u64 v[124:125], v[160:161], 0, s[26:27]
	v_lshl_add_u64 v[128:129], v[162:163], 0, s[26:27]
	v_lshl_add_u64 v[132:133], v[164:165], 0, s[26:27]
	s_waitcnt lgkmcnt(0)
	s_barrier
	global_load_dwordx4 v[112:115], v[112:113], off offset:192
	ds_read_b128 v[196:199], v168 offset:40960
	global_load_dwordx4 v[116:119], v[116:117], off offset:192
	ds_read_b128 v[200:203], v168 offset:41984
	global_load_dwordx4 v[120:123], v[120:121], off
	ds_read_b128 v[204:207], v168 offset:43008
	global_load_dwordx4 v[124:127], v[124:125], off
	ds_read_b128 v[208:211], v168 offset:44032
	global_load_dwordx4 v[128:131], v[128:129], off
	ds_read_b128 v[212:215], v170
	global_load_dwordx4 v[132:135], v[132:133], off
	ds_read_b128 v[216:219], v170 offset:1024
	ds_read_b128 v[222:225], v170 offset:2048
	ds_read_b128 v[226:229], v170 offset:3072
	ds_read_b128 v[230:233], v170 offset:4096
	ds_read_b128 v[234:237], v170 offset:5120
	ds_read_b128 v[238:241], v170 offset:6144
	ds_read_b128 v[242:245], v170 offset:7168
	s_setprio 1
	s_waitcnt lgkmcnt(7)
	v_mfma_f32_16x16x32_bf16 v[148:151], v[196:199], v[212:215], v[148:151]
	v_mfma_f32_16x16x32_bf16 v[144:147], v[200:203], v[212:215], v[144:147]
	v_mfma_f32_16x16x32_bf16 v[140:143], v[204:207], v[212:215], v[140:143]
	v_mfma_f32_16x16x32_bf16 v[136:139], v[208:211], v[212:215], v[136:139]
	s_waitcnt vmcnt(11)
	ds_write_b128 v152, v[172:175]
	s_waitcnt lgkmcnt(7)
	v_mfma_f32_16x16x32_bf16 v[108:111], v[196:199], v[216:219], v[108:111]
	v_mfma_f32_16x16x32_bf16 v[104:107], v[200:203], v[216:219], v[104:107]
	v_mfma_f32_16x16x32_bf16 v[100:103], v[204:207], v[216:219], v[100:103]
	v_mfma_f32_16x16x32_bf16 v[96:99], v[208:211], v[216:219], v[96:99]
	s_waitcnt vmcnt(10)
	ds_write_b128 v152, v[176:179] offset:4096
	s_waitcnt lgkmcnt(7)
	v_mfma_f32_16x16x32_bf16 v[92:95], v[196:199], v[222:225], v[92:95]
	v_mfma_f32_16x16x32_bf16 v[88:91], v[200:203], v[222:225], v[88:91]
	v_mfma_f32_16x16x32_bf16 v[84:87], v[204:207], v[222:225], v[84:87]
	v_mfma_f32_16x16x32_bf16 v[80:83], v[208:211], v[222:225], v[80:83]
	s_waitcnt vmcnt(9)
	ds_write_b128 v152, v[180:183] offset:8192
	s_waitcnt lgkmcnt(7)
	v_mfma_f32_16x16x32_bf16 v[76:79], v[196:199], v[226:229], v[76:79]
	v_mfma_f32_16x16x32_bf16 v[72:75], v[200:203], v[226:229], v[72:75]
	v_mfma_f32_16x16x32_bf16 v[68:71], v[204:207], v[226:229], v[68:71]
	v_mfma_f32_16x16x32_bf16 v[64:67], v[208:211], v[226:229], v[64:67]
	s_waitcnt vmcnt(8)
	ds_write_b128 v152, v[184:187] offset:12288
	s_waitcnt lgkmcnt(7)
	v_mfma_f32_16x16x32_bf16 v[60:63], v[196:199], v[230:233], v[60:63]
	v_mfma_f32_16x16x32_bf16 v[56:59], v[200:203], v[230:233], v[56:59]
	v_mfma_f32_16x16x32_bf16 v[52:55], v[204:207], v[230:233], v[52:55]
	v_mfma_f32_16x16x32_bf16 v[48:51], v[208:211], v[230:233], v[48:51]
	s_waitcnt vmcnt(7)
	ds_write_b128 v152, v[188:191] offset:32768
	s_waitcnt lgkmcnt(7)
	v_mfma_f32_16x16x32_bf16 v[44:47], v[196:199], v[234:237], v[44:47]
	v_mfma_f32_16x16x32_bf16 v[40:43], v[200:203], v[234:237], v[40:43]
	v_mfma_f32_16x16x32_bf16 v[36:39], v[204:207], v[234:237], v[36:39]
	v_mfma_f32_16x16x32_bf16 v[32:35], v[208:211], v[234:237], v[32:35]
	s_waitcnt vmcnt(6)
	ds_write_b128 v152, v[192:195] offset:36864
	s_waitcnt lgkmcnt(7)
	v_mfma_f32_16x16x32_bf16 v[28:31], v[196:199], v[238:241], v[28:31]
	v_mfma_f32_16x16x32_bf16 v[24:27], v[200:203], v[238:241], v[24:27]
	v_mfma_f32_16x16x32_bf16 v[20:23], v[204:207], v[238:241], v[20:23]
	v_mfma_f32_16x16x32_bf16 v[16:19], v[208:211], v[238:241], v[16:19]
	s_waitcnt lgkmcnt(6)
	v_mfma_f32_16x16x32_bf16 v[12:15], v[196:199], v[242:245], v[12:15]
	v_mfma_f32_16x16x32_bf16 v[8:11], v[200:203], v[242:245], v[8:11]
	v_mfma_f32_16x16x32_bf16 v[4:7], v[204:207], v[242:245], v[4:7]
	v_mfma_f32_16x16x32_bf16 v[0:3], v[208:211], v[242:245], v[0:3]
	s_setprio 0
	s_add_i32 s1, s1, 2
	s_cmp_lt_u32 s1, 30
	s_mov_b32 s10, s11
	s_waitcnt lgkmcnt(0)
	s_barrier
	s_cbranch_scc1 .LBB0_706
	s_waitcnt vmcnt(4)
	v_mov_b32_e32 v116, v220
	s_nop 0
	v_and_b32_e32 v112, 0xffffff80, v116
	v_add_u32_e32 v117, s0, v112
	v_and_or_b32 v114, v116, 15, v117
	v_ashrrev_i32_e32 v115, 31, v114
	v_lshl_add_u64 v[112:113], v[114:115], 2, s[14:15]
	global_load_dword v122, v[112:113], off
	v_and_b32_e32 v112, 64, v116
	v_lshrrev_b32_e32 v115, 1, v116
	v_ashrrev_i32_e32 v116, 14, v117
	v_ashrrev_i32_e32 v117, 31, v116
	v_lshlrev_b32_e32 v152, 1, v112
	v_or_b32_e32 v118, 16, v114
	v_lshlrev_b64 v[116:117], 16, v[116:117]
	v_lshl_add_u64 v[112:113], s[38:39], 0, v[152:153]
	v_and_b32_e32 v152, 24, v115
	v_ashrrev_i32_e32 v119, 31, v118
	v_lshl_or_b32 v115, s12, 14, v116
	s_waitcnt vmcnt(4)
	v_lshl_add_u64 v[120:121], v[118:119], 2, s[14:15]
	v_lshl_add_u64 v[112:113], v[112:113], 0, v[152:153]
	s_waitcnt vmcnt(0)
	v_fmamk_f32 v116, v122, 0x3a800000, v166
	v_mul_f32_e32 v119, 0x4b800000, v116
	v_cmp_gt_f32_e32 vcc, s40, v116
	s_nop 1
	v_cndmask_b32_e32 v116, v116, v119, vcc
	v_rsq_f32_e32 v119, v116
	v_and_or_b32 v116, v114, s41, v115
	v_lshlrev_b64 v[122:123], 8, v[116:117]
	v_lshl_add_u64 v[122:123], v[112:113], 0, v[122:123]
	v_mul_f32_e32 v116, 0x45800000, v119
	v_cndmask_b32_e32 v116, v119, v116, vcc
	v_mul_f32_e32 v124, v149, v116
	v_mul_f32_e32 v125, v150, v116
	v_mul_f32_e32 v119, v148, v116
	v_mul_f32_e32 v126, v151, v116
	v_mul_f32_e32 v127, v144, v116
	v_mul_f32_e32 v128, v145, v116
	v_mul_f32_e32 v129, v146, v116
	v_mul_f32_e32 v130, v147, v116
	v_mul_f32_e32 v131, v140, v116
	v_cvt_pk_bf16_f32 v124, v119, v124
	v_cvt_pk_bf16_f32 v125, v125, v126
	v_mul_f32_e32 v132, v141, v116
	v_mul_f32_e32 v133, v142, v116
	v_mul_f32_e32 v134, v143, v116
	v_mul_f32_e32 v135, v136, v116
	v_mul_f32_e32 v136, v137, v116
	v_mul_f32_e32 v137, v138, v116
	v_mul_f32_e32 v116, v139, v116
	v_cvt_pk_bf16_f32 v126, v127, v128
	v_cvt_pk_bf16_f32 v127, v129, v130
	v_cvt_pk_bf16_f32 v128, v131, v132
	v_cvt_pk_bf16_f32 v129, v133, v134
	v_cvt_pk_bf16_f32 v130, v135, v136
	v_cvt_pk_bf16_f32 v131, v137, v116
	global_store_dwordx2 v[122:123], v[124:125], off
	global_store_dwordx2 v[122:123], v[126:127], off offset:32
	global_store_dwordx2 v[122:123], v[128:129], off offset:64
	global_store_dwordx2 v[122:123], v[130:131], off offset:96
	global_load_dword v116, v[120:121], off
	v_or_b32_e32 v120, 32, v114
	v_ashrrev_i32_e32 v121, 31, v120
	v_lshl_add_u64 v[122:123], v[120:121], 2, s[14:15]
	s_waitcnt vmcnt(0)
	v_fmamk_f32 v116, v116, 0x3a800000, v166
	v_mul_f32_e32 v119, 0x4b800000, v116
	v_cmp_gt_f32_e32 vcc, s40, v116
	s_nop 1
	v_cndmask_b32_e32 v116, v116, v119, vcc
	v_rsq_f32_e32 v121, v116
	v_and_or_b32 v116, v118, s42, v115
	v_lshlrev_b64 v[118:119], 8, v[116:117]
	v_lshl_add_u64 v[118:119], v[112:113], 0, v[118:119]
	v_mul_f32_e32 v116, 0x45800000, v121
	v_cndmask_b32_e32 v116, v121, v116, vcc
	v_mul_f32_e32 v108, v108, v116
	v_mul_f32_e32 v109, v109, v116
	v_mul_f32_e32 v110, v110, v116
	v_mul_f32_e32 v111, v111, v116
	v_mul_f32_e32 v100, v100, v116
	v_mul_f32_e32 v101, v101, v116
	v_mul_f32_e32 v102, v102, v116
	v_mul_f32_e32 v103, v103, v116
	v_mul_f32_e32 v121, v96, v116
	v_mul_f32_e32 v124, v97, v116
	v_cvt_pk_bf16_f32 v96, v108, v109
	v_cvt_pk_bf16_f32 v97, v110, v111
	v_mul_f32_e32 v104, v104, v116
	v_mul_f32_e32 v105, v105, v116
	v_mul_f32_e32 v106, v106, v116
	v_mul_f32_e32 v107, v107, v116
	v_mul_f32_e32 v125, v98, v116
	v_mul_f32_e32 v116, v99, v116
	v_cvt_pk_bf16_f32 v98, v104, v105
	v_cvt_pk_bf16_f32 v99, v106, v107
	v_cvt_pk_bf16_f32 v100, v100, v101
	v_cvt_pk_bf16_f32 v101, v102, v103
	v_cvt_pk_bf16_f32 v102, v121, v124
	v_cvt_pk_bf16_f32 v103, v125, v116
	global_store_dwordx2 v[118:119], v[96:97], off
	global_store_dwordx2 v[118:119], v[98:99], off offset:32
	global_store_dwordx2 v[118:119], v[100:101], off offset:64
	global_store_dwordx2 v[118:119], v[102:103], off offset:96
	global_load_dword v100, v[122:123], off
	v_or_b32_e32 v96, 48, v114
	v_ashrrev_i32_e32 v97, 31, v96
	v_lshl_add_u64 v[98:99], v[96:97], 2, s[14:15]
	v_and_or_b32 v116, v120, s43, v115
	s_waitcnt vmcnt(0)
	v_fmamk_f32 v97, v100, 0x3a800000, v166
	v_mul_f32_e32 v100, 0x4b800000, v97
	v_cmp_gt_f32_e32 vcc, s40, v97
	s_nop 1
	v_cndmask_b32_e32 v97, v97, v100, vcc
	v_rsq_f32_e32 v97, v97
	v_lshlrev_b64 v[100:101], 8, v[116:117]
	v_lshl_add_u64 v[100:101], v[112:113], 0, v[100:101]
	v_and_or_b32 v116, v96, s44, v115
	v_mul_f32_e32 v102, 0x45800000, v97
	v_cndmask_b32_e32 v97, v97, v102, vcc
	v_mul_f32_e32 v92, v92, v97
	v_mul_f32_e32 v93, v93, v97
	v_mul_f32_e32 v94, v94, v97
	v_mul_f32_e32 v95, v95, v97
	v_mul_f32_e32 v84, v84, v97
	v_mul_f32_e32 v85, v85, v97
	v_mul_f32_e32 v86, v86, v97
	v_mul_f32_e32 v87, v87, v97
	v_mul_f32_e32 v102, v80, v97
	v_mul_f32_e32 v103, v81, v97
	v_cvt_pk_bf16_f32 v80, v92, v93
	v_cvt_pk_bf16_f32 v81, v94, v95
	v_mul_f32_e32 v88, v88, v97
	v_mul_f32_e32 v89, v89, v97
	v_mul_f32_e32 v90, v90, v97
	v_mul_f32_e32 v91, v91, v97
	v_mul_f32_e32 v104, v82, v97
	v_mul_f32_e32 v97, v83, v97
	v_cvt_pk_bf16_f32 v82, v88, v89
	v_cvt_pk_bf16_f32 v83, v90, v91
	v_cvt_pk_bf16_f32 v84, v84, v85
	v_cvt_pk_bf16_f32 v85, v86, v87
	v_cvt_pk_bf16_f32 v86, v102, v103
	v_cvt_pk_bf16_f32 v87, v104, v97
	global_store_dwordx2 v[100:101], v[80:81], off
	global_store_dwordx2 v[100:101], v[82:83], off offset:32
	global_store_dwordx2 v[100:101], v[84:85], off offset:64
	global_store_dwordx2 v[100:101], v[86:87], off offset:96
	global_load_dword v84, v[98:99], off
	v_or_b32_e32 v80, 64, v114
	v_ashrrev_i32_e32 v81, 31, v80
	v_lshl_add_u64 v[82:83], v[80:81], 2, s[14:15]
	s_waitcnt vmcnt(0)
	v_fmamk_f32 v81, v84, 0x3a800000, v166
	v_mul_f32_e32 v84, 0x4b800000, v81
	v_cmp_gt_f32_e32 vcc, s40, v81
	s_nop 1
	v_cndmask_b32_e32 v81, v81, v84, vcc
	v_rsq_f32_e32 v81, v81
	v_lshlrev_b64 v[84:85], 8, v[116:117]
	v_lshl_add_u64 v[84:85], v[112:113], 0, v[84:85]
	v_and_or_b32 v116, v80, s45, v115
	v_mul_f32_e32 v86, 0x45800000, v81
	v_cndmask_b32_e32 v81, v81, v86, vcc
	v_mul_f32_e32 v76, v76, v81
	v_mul_f32_e32 v77, v77, v81
	v_mul_f32_e32 v78, v78, v81
	v_mul_f32_e32 v79, v79, v81
	v_mul_f32_e32 v68, v68, v81
	v_mul_f32_e32 v69, v69, v81
	v_mul_f32_e32 v70, v70, v81
	v_mul_f32_e32 v71, v71, v81
	v_mul_f32_e32 v86, v64, v81
	v_mul_f32_e32 v87, v65, v81
	v_cvt_pk_bf16_f32 v64, v76, v77
	v_cvt_pk_bf16_f32 v65, v78, v79
	v_mul_f32_e32 v72, v72, v81
	v_mul_f32_e32 v73, v73, v81
	v_mul_f32_e32 v74, v74, v81
	v_mul_f32_e32 v75, v75, v81
	v_mul_f32_e32 v88, v66, v81
	v_mul_f32_e32 v81, v67, v81
	v_cvt_pk_bf16_f32 v66, v72, v73
	v_cvt_pk_bf16_f32 v67, v74, v75
	v_cvt_pk_bf16_f32 v68, v68, v69
	v_cvt_pk_bf16_f32 v69, v70, v71
	v_cvt_pk_bf16_f32 v70, v86, v87
	v_cvt_pk_bf16_f32 v71, v88, v81
	global_store_dwordx2 v[84:85], v[64:65], off
	global_store_dwordx2 v[84:85], v[66:67], off offset:32
	global_store_dwordx2 v[84:85], v[68:69], off offset:64
	global_store_dwordx2 v[84:85], v[70:71], off offset:96
	global_load_dword v68, v[82:83], off
	v_or_b32_e32 v64, 0x50, v114
	v_ashrrev_i32_e32 v65, 31, v64
	v_lshl_add_u64 v[66:67], v[64:65], 2, s[14:15]
	s_waitcnt vmcnt(0)
	v_fmamk_f32 v65, v68, 0x3a800000, v166
	v_mul_f32_e32 v68, 0x4b800000, v65
	v_cmp_gt_f32_e32 vcc, s40, v65
	s_nop 1
	v_cndmask_b32_e32 v65, v65, v68, vcc
	v_rsq_f32_e32 v65, v65
	v_lshlrev_b64 v[68:69], 8, v[116:117]
	v_lshl_add_u64 v[68:69], v[112:113], 0, v[68:69]
	v_and_or_b32 v116, v64, s46, v115
	v_mul_f32_e32 v70, 0x45800000, v65
	v_cndmask_b32_e32 v65, v65, v70, vcc
	v_mul_f32_e32 v60, v60, v65
	v_mul_f32_e32 v61, v61, v65
	v_mul_f32_e32 v62, v62, v65
	v_mul_f32_e32 v63, v63, v65
	v_mul_f32_e32 v52, v52, v65
	v_mul_f32_e32 v53, v53, v65
	v_mul_f32_e32 v54, v54, v65
	v_mul_f32_e32 v55, v55, v65
	v_mul_f32_e32 v70, v48, v65
	v_mul_f32_e32 v71, v49, v65
	v_cvt_pk_bf16_f32 v48, v60, v61
	v_cvt_pk_bf16_f32 v49, v62, v63
	v_mul_f32_e32 v56, v56, v65
	v_mul_f32_e32 v57, v57, v65
	v_mul_f32_e32 v58, v58, v65
	v_mul_f32_e32 v59, v59, v65
	v_mul_f32_e32 v72, v50, v65
	v_mul_f32_e32 v65, v51, v65
	v_cvt_pk_bf16_f32 v50, v56, v57
	v_cvt_pk_bf16_f32 v51, v58, v59
	v_cvt_pk_bf16_f32 v52, v52, v53
	v_cvt_pk_bf16_f32 v53, v54, v55
	v_cvt_pk_bf16_f32 v54, v70, v71
	v_cvt_pk_bf16_f32 v55, v72, v65
	global_store_dwordx2 v[68:69], v[48:49], off
	global_store_dwordx2 v[68:69], v[50:51], off offset:32
	global_store_dwordx2 v[68:69], v[52:53], off offset:64
	global_store_dwordx2 v[68:69], v[54:55], off offset:96
	global_load_dword v52, v[66:67], off
	v_or_b32_e32 v48, 0x60, v114
	v_ashrrev_i32_e32 v49, 31, v48
	v_lshl_add_u64 v[50:51], v[48:49], 2, s[14:15]
	s_waitcnt vmcnt(0)
	v_fmamk_f32 v49, v52, 0x3a800000, v166
	v_mul_f32_e32 v52, 0x4b800000, v49
	v_cmp_gt_f32_e32 vcc, s40, v49
	s_nop 1
	v_cndmask_b32_e32 v49, v49, v52, vcc
	v_rsq_f32_e32 v49, v49
	v_lshlrev_b64 v[52:53], 8, v[116:117]
	v_lshl_add_u64 v[52:53], v[112:113], 0, v[52:53]
	v_and_or_b32 v116, v48, s47, v115
	v_mul_f32_e32 v54, 0x45800000, v49
	v_cndmask_b32_e32 v49, v49, v54, vcc
	v_mul_f32_e32 v44, v44, v49
	v_mul_f32_e32 v45, v45, v49
	v_mul_f32_e32 v46, v46, v49
	v_mul_f32_e32 v47, v47, v49
	v_mul_f32_e32 v36, v36, v49
	v_mul_f32_e32 v37, v37, v49
	v_mul_f32_e32 v38, v38, v49
	v_mul_f32_e32 v39, v39, v49
	v_mul_f32_e32 v54, v32, v49
	v_mul_f32_e32 v55, v33, v49
	v_cvt_pk_bf16_f32 v32, v44, v45
	v_cvt_pk_bf16_f32 v33, v46, v47
	v_mul_f32_e32 v40, v40, v49
	v_mul_f32_e32 v41, v41, v49
	v_mul_f32_e32 v42, v42, v49
	v_mul_f32_e32 v43, v43, v49
	v_mul_f32_e32 v56, v34, v49
	v_mul_f32_e32 v49, v35, v49
	v_cvt_pk_bf16_f32 v34, v40, v41
	v_cvt_pk_bf16_f32 v35, v42, v43
	v_cvt_pk_bf16_f32 v36, v36, v37
	v_cvt_pk_bf16_f32 v37, v38, v39
	v_cvt_pk_bf16_f32 v38, v54, v55
	v_cvt_pk_bf16_f32 v39, v56, v49
	global_store_dwordx2 v[52:53], v[32:33], off
	global_store_dwordx2 v[52:53], v[34:35], off offset:32
	global_store_dwordx2 v[52:53], v[36:37], off offset:64
	global_store_dwordx2 v[52:53], v[38:39], off offset:96
	global_load_dword v36, v[50:51], off
	v_or_b32_e32 v32, 0x70, v114
	v_ashrrev_i32_e32 v33, 31, v32
	v_lshl_add_u64 v[34:35], v[32:33], 2, s[14:15]
	s_waitcnt vmcnt(0)
	v_fmamk_f32 v33, v36, 0x3a800000, v166
	v_mul_f32_e32 v36, 0x4b800000, v33
	v_cmp_gt_f32_e32 vcc, s40, v33
	s_nop 1
	v_cndmask_b32_e32 v33, v33, v36, vcc
	v_rsq_f32_e32 v33, v33
	v_lshlrev_b64 v[36:37], 8, v[116:117]
	v_lshl_add_u64 v[36:37], v[112:113], 0, v[36:37]
	v_and_or_b32 v116, v32, s48, v115
	v_mul_f32_e32 v38, 0x45800000, v33
	v_cndmask_b32_e32 v33, v33, v38, vcc
	v_mul_f32_e32 v28, v28, v33
	v_mul_f32_e32 v29, v29, v33
	v_mul_f32_e32 v30, v30, v33
	v_mul_f32_e32 v31, v31, v33
	v_mul_f32_e32 v20, v20, v33
	v_mul_f32_e32 v21, v21, v33
	v_mul_f32_e32 v22, v22, v33
	v_mul_f32_e32 v23, v23, v33
	v_mul_f32_e32 v38, v16, v33
	v_mul_f32_e32 v39, v17, v33
	v_cvt_pk_bf16_f32 v16, v28, v29
	v_cvt_pk_bf16_f32 v17, v30, v31
	v_mul_f32_e32 v24, v24, v33
	v_mul_f32_e32 v25, v25, v33
	v_mul_f32_e32 v26, v26, v33
	v_mul_f32_e32 v27, v27, v33
	v_mul_f32_e32 v40, v18, v33
	v_mul_f32_e32 v33, v19, v33
	v_cvt_pk_bf16_f32 v18, v24, v25
	v_cvt_pk_bf16_f32 v19, v26, v27
	v_cvt_pk_bf16_f32 v20, v20, v21
	v_cvt_pk_bf16_f32 v21, v22, v23
	v_cvt_pk_bf16_f32 v22, v38, v39
	v_cvt_pk_bf16_f32 v23, v40, v33
	global_store_dwordx2 v[36:37], v[16:17], off
	global_store_dwordx2 v[36:37], v[18:19], off offset:32
	global_store_dwordx2 v[36:37], v[20:21], off offset:64
	global_store_dwordx2 v[36:37], v[22:23], off offset:96
	global_load_dword v16, v[34:35], off
	s_waitcnt vmcnt(0)
	v_fmamk_f32 v16, v16, 0x3a800000, v166
	v_mul_f32_e32 v17, 0x4b800000, v16
	v_cmp_gt_f32_e32 vcc, s40, v16
	s_nop 1
	v_cndmask_b32_e32 v16, v16, v17, vcc
	v_rsq_f32_e32 v18, v16
	v_lshlrev_b64 v[16:17], 8, v[116:117]
	v_lshl_add_u64 v[16:17], v[112:113], 0, v[16:17]
	v_mul_f32_e32 v19, 0x45800000, v18
	v_cndmask_b32_e32 v18, v18, v19, vcc
	v_mul_f32_e32 v12, v12, v18
	v_mul_f32_e32 v13, v13, v18
	v_mul_f32_e32 v14, v14, v18
	v_mul_f32_e32 v15, v15, v18
	v_mul_f32_e32 v4, v4, v18
	v_mul_f32_e32 v5, v5, v18
	v_mul_f32_e32 v6, v6, v18
	v_mul_f32_e32 v7, v7, v18
	v_mul_f32_e32 v19, v0, v18
	v_mul_f32_e32 v20, v1, v18
	v_cvt_pk_bf16_f32 v0, v12, v13
	v_cvt_pk_bf16_f32 v1, v14, v15
	v_mul_f32_e32 v8, v8, v18
	v_mul_f32_e32 v9, v9, v18
	v_mul_f32_e32 v10, v10, v18
	v_mul_f32_e32 v11, v11, v18
	v_mul_f32_e32 v21, v2, v18
	v_mul_f32_e32 v18, v3, v18
	v_cvt_pk_bf16_f32 v2, v8, v9
	v_cvt_pk_bf16_f32 v3, v10, v11
	v_cvt_pk_bf16_f32 v4, v4, v5
	v_cvt_pk_bf16_f32 v5, v6, v7
	v_cvt_pk_bf16_f32 v6, v19, v20
	v_cvt_pk_bf16_f32 v7, v21, v18
	global_store_dwordx2 v[16:17], v[0:1], off
	global_store_dwordx2 v[16:17], v[2:3], off offset:32
	global_store_dwordx2 v[16:17], v[4:5], off offset:64
	global_store_dwordx2 v[16:17], v[6:7], off offset:96
	s_branch .LBB0_699

.LBB0_710:
	s_add_i32 s11, s10, 64
	s_min_u32 s13, s11, 0x3e0
	s_lshl_b32 s16, s13, 1
	v_lshl_add_u64 v[172:173], v[154:155], 0, s[16:17]
	v_lshl_add_u64 v[176:177], v[158:159], 0, s[16:17]
	v_lshl_add_u64 v[180:181], v[160:161], 0, s[16:17]
	v_lshl_add_u64 v[184:185], v[162:163], 0, s[16:17]
	v_lshl_add_u64 v[188:189], v[156:157], 0, s[16:17]
	v_lshl_add_u64 v[192:193], v[164:165], 0, s[16:17]
	global_load_dwordx4 v[172:175], v[172:173], off
	ds_read_b128 v[196:199], v171 offset:32768
	global_load_dwordx4 v[176:179], v[176:177], off
	ds_read_b128 v[200:203], v171 offset:33792
	global_load_dwordx4 v[180:183], v[180:181], off
	ds_read_b128 v[204:207], v171 offset:34816
	global_load_dwordx4 v[184:187], v[184:185], off
	ds_read_b128 v[208:211], v171 offset:35840
	global_load_dwordx4 v[188:191], v[188:189], off
	ds_read_b128 v[212:215], v169
	global_load_dwordx4 v[192:195], v[192:193], off
	ds_read_b128 v[216:219], v169 offset:1024
	ds_read_b128 v[222:225], v169 offset:2048
	ds_read_b128 v[226:229], v169 offset:3072
	ds_read_b128 v[230:233], v169 offset:4096
	ds_read_b128 v[234:237], v169 offset:5120
	ds_read_b128 v[238:241], v169 offset:6144
	ds_read_b128 v[242:245], v169 offset:7168
	s_setprio 1
	s_waitcnt lgkmcnt(7)
	v_mfma_f32_16x16x32_bf16 v[148:151], v[212:215], v[196:199], v[148:151]
	v_mfma_f32_16x16x32_bf16 v[144:147], v[212:215], v[200:203], v[144:147]
	v_mfma_f32_16x16x32_bf16 v[140:143], v[212:215], v[204:207], v[140:143]
	v_mfma_f32_16x16x32_bf16 v[128:131], v[212:215], v[208:211], v[128:131]
	s_waitcnt vmcnt(11)
	ds_write_b128 v152, v[112:115] offset:16384
	s_waitcnt lgkmcnt(7)
	v_mfma_f32_16x16x32_bf16 v[108:111], v[216:219], v[196:199], v[108:111]
	v_mfma_f32_16x16x32_bf16 v[104:107], v[216:219], v[200:203], v[104:107]
	v_mfma_f32_16x16x32_bf16 v[100:103], v[216:219], v[204:207], v[100:103]
	v_mfma_f32_16x16x32_bf16 v[96:99], v[216:219], v[208:211], v[96:99]
	s_waitcnt vmcnt(9)
	ds_write_b128 v152, v[120:123] offset:20480
	s_waitcnt lgkmcnt(7)
	v_mfma_f32_16x16x32_bf16 v[92:95], v[222:225], v[196:199], v[92:95]
	v_mfma_f32_16x16x32_bf16 v[88:91], v[222:225], v[200:203], v[88:91]
	v_mfma_f32_16x16x32_bf16 v[84:87], v[222:225], v[204:207], v[84:87]
	v_mfma_f32_16x16x32_bf16 v[80:83], v[222:225], v[208:211], v[80:83]
	s_waitcnt vmcnt(8)
	ds_write_b128 v152, v[124:127] offset:24576
	s_waitcnt lgkmcnt(7)
	v_mfma_f32_16x16x32_bf16 v[76:79], v[226:229], v[196:199], v[76:79]
	v_mfma_f32_16x16x32_bf16 v[72:75], v[226:229], v[200:203], v[72:75]
	v_mfma_f32_16x16x32_bf16 v[68:71], v[226:229], v[204:207], v[68:71]
	v_mfma_f32_16x16x32_bf16 v[64:67], v[226:229], v[208:211], v[64:67]
	s_waitcnt vmcnt(7)
	ds_write_b128 v152, v[132:135] offset:28672
	s_waitcnt lgkmcnt(7)
	v_mfma_f32_16x16x32_bf16 v[60:63], v[230:233], v[196:199], v[60:63]
	v_mfma_f32_16x16x32_bf16 v[56:59], v[230:233], v[200:203], v[56:59]
	v_mfma_f32_16x16x32_bf16 v[52:55], v[230:233], v[204:207], v[52:55]
	v_mfma_f32_16x16x32_bf16 v[48:51], v[230:233], v[208:211], v[48:51]
	s_waitcnt vmcnt(7)
	ds_write_b128 v152, v[116:119] offset:40960
	s_waitcnt lgkmcnt(7)
	v_mfma_f32_16x16x32_bf16 v[44:47], v[234:237], v[196:199], v[44:47]
	v_mfma_f32_16x16x32_bf16 v[40:43], v[234:237], v[200:203], v[40:43]
	v_mfma_f32_16x16x32_bf16 v[36:39], v[234:237], v[204:207], v[36:39]
	v_mfma_f32_16x16x32_bf16 v[32:35], v[234:237], v[208:211], v[32:35]
	s_waitcnt vmcnt(6)
	ds_write_b128 v152, v[136:139] offset:45056
	s_waitcnt lgkmcnt(7)
	v_mfma_f32_16x16x32_bf16 v[28:31], v[238:241], v[196:199], v[28:31]
	v_mfma_f32_16x16x32_bf16 v[24:27], v[238:241], v[200:203], v[24:27]
	v_mfma_f32_16x16x32_bf16 v[20:23], v[238:241], v[204:207], v[20:23]
	v_mfma_f32_16x16x32_bf16 v[16:19], v[238:241], v[208:211], v[16:19]
	s_waitcnt lgkmcnt(6)
	v_mfma_f32_16x16x32_bf16 v[12:15], v[242:245], v[196:199], v[12:15]
	v_mfma_f32_16x16x32_bf16 v[8:11], v[242:245], v[200:203], v[8:11]
	v_mfma_f32_16x16x32_bf16 v[4:7], v[242:245], v[204:207], v[4:7]
	v_mfma_f32_16x16x32_bf16 v[0:3], v[242:245], v[208:211], v[0:3]
	s_setprio 0
	s_min_u32 s10, s10, 0x380
	s_lshl_b32 s16, s10, 1
	s_mov_b32 s27, s17
	s_add_i32 s26, s16, 0xc0
	v_lshl_add_u64 v[112:113], v[154:155], 0, s[16:17]
	v_lshl_add_u64 v[116:117], v[156:157], 0, s[16:17]
	v_lshl_add_u64 v[120:121], v[158:159], 0, s[26:27]
	v_lshl_add_u64 v[124:125], v[160:161], 0, s[26:27]
	v_lshl_add_u64 v[132:133], v[162:163], 0, s[26:27]
	v_lshl_add_u64 v[136:137], v[164:165], 0, s[26:27]
	s_waitcnt lgkmcnt(0)
	s_barrier
	global_load_dwordx4 v[112:115], v[112:113], off offset:192
	ds_read_b128 v[196:199], v168 offset:40960
	global_load_dwordx4 v[116:119], v[116:117], off offset:192
	ds_read_b128 v[200:203], v168 offset:41984
	global_load_dwordx4 v[120:123], v[120:121], off
	ds_read_b128 v[204:207], v168 offset:43008
	global_load_dwordx4 v[124:127], v[124:125], off
	ds_read_b128 v[208:211], v168 offset:44032
	global_load_dwordx4 v[132:135], v[132:133], off
	ds_read_b128 v[212:215], v170
	global_load_dwordx4 v[136:139], v[136:137], off
	ds_read_b128 v[216:219], v170 offset:1024
	ds_read_b128 v[222:225], v170 offset:2048
	ds_read_b128 v[226:229], v170 offset:3072
	ds_read_b128 v[230:233], v170 offset:4096
	ds_read_b128 v[234:237], v170 offset:5120
	ds_read_b128 v[238:241], v170 offset:6144
	ds_read_b128 v[242:245], v170 offset:7168
	s_setprio 1
	s_waitcnt lgkmcnt(7)
	v_mfma_f32_16x16x32_bf16 v[148:151], v[212:215], v[196:199], v[148:151]
	v_mfma_f32_16x16x32_bf16 v[144:147], v[212:215], v[200:203], v[144:147]
	v_mfma_f32_16x16x32_bf16 v[140:143], v[212:215], v[204:207], v[140:143]
	v_mfma_f32_16x16x32_bf16 v[128:131], v[212:215], v[208:211], v[128:131]
	s_waitcnt vmcnt(11)
	ds_write_b128 v152, v[172:175]
	s_waitcnt lgkmcnt(7)
	v_mfma_f32_16x16x32_bf16 v[108:111], v[216:219], v[196:199], v[108:111]
	v_mfma_f32_16x16x32_bf16 v[104:107], v[216:219], v[200:203], v[104:107]
	v_mfma_f32_16x16x32_bf16 v[100:103], v[216:219], v[204:207], v[100:103]
	v_mfma_f32_16x16x32_bf16 v[96:99], v[216:219], v[208:211], v[96:99]
	s_waitcnt vmcnt(10)
	ds_write_b128 v152, v[176:179] offset:4096
	s_waitcnt lgkmcnt(7)
	v_mfma_f32_16x16x32_bf16 v[92:95], v[222:225], v[196:199], v[92:95]
	v_mfma_f32_16x16x32_bf16 v[88:91], v[222:225], v[200:203], v[88:91]
	v_mfma_f32_16x16x32_bf16 v[84:87], v[222:225], v[204:207], v[84:87]
	v_mfma_f32_16x16x32_bf16 v[80:83], v[222:225], v[208:211], v[80:83]
	s_waitcnt vmcnt(9)
	ds_write_b128 v152, v[180:183] offset:8192
	s_waitcnt lgkmcnt(7)
	v_mfma_f32_16x16x32_bf16 v[76:79], v[226:229], v[196:199], v[76:79]
	v_mfma_f32_16x16x32_bf16 v[72:75], v[226:229], v[200:203], v[72:75]
	v_mfma_f32_16x16x32_bf16 v[68:71], v[226:229], v[204:207], v[68:71]
	v_mfma_f32_16x16x32_bf16 v[64:67], v[226:229], v[208:211], v[64:67]
	s_waitcnt vmcnt(8)
	ds_write_b128 v152, v[184:187] offset:12288
	s_waitcnt lgkmcnt(7)
	v_mfma_f32_16x16x32_bf16 v[60:63], v[230:233], v[196:199], v[60:63]
	v_mfma_f32_16x16x32_bf16 v[56:59], v[230:233], v[200:203], v[56:59]
	v_mfma_f32_16x16x32_bf16 v[52:55], v[230:233], v[204:207], v[52:55]
	v_mfma_f32_16x16x32_bf16 v[48:51], v[230:233], v[208:211], v[48:51]
	s_waitcnt vmcnt(7)
	ds_write_b128 v152, v[188:191] offset:32768
	s_waitcnt lgkmcnt(7)
	v_mfma_f32_16x16x32_bf16 v[44:47], v[234:237], v[196:199], v[44:47]
	v_mfma_f32_16x16x32_bf16 v[40:43], v[234:237], v[200:203], v[40:43]
	v_mfma_f32_16x16x32_bf16 v[36:39], v[234:237], v[204:207], v[36:39]
	v_mfma_f32_16x16x32_bf16 v[32:35], v[234:237], v[208:211], v[32:35]
	s_waitcnt vmcnt(6)
	ds_write_b128 v152, v[192:195] offset:36864
	s_waitcnt lgkmcnt(7)
	v_mfma_f32_16x16x32_bf16 v[28:31], v[238:241], v[196:199], v[28:31]
	v_mfma_f32_16x16x32_bf16 v[24:27], v[238:241], v[200:203], v[24:27]
	v_mfma_f32_16x16x32_bf16 v[20:23], v[238:241], v[204:207], v[20:23]
	v_mfma_f32_16x16x32_bf16 v[16:19], v[238:241], v[208:211], v[16:19]
	s_waitcnt lgkmcnt(6)
	v_mfma_f32_16x16x32_bf16 v[12:15], v[242:245], v[196:199], v[12:15]
	v_mfma_f32_16x16x32_bf16 v[8:11], v[242:245], v[200:203], v[8:11]
	v_mfma_f32_16x16x32_bf16 v[4:7], v[242:245], v[204:207], v[4:7]
	v_mfma_f32_16x16x32_bf16 v[0:3], v[242:245], v[208:211], v[0:3]
	s_setprio 0
	s_add_i32 s1, s1, 2
	s_cmp_lt_u32 s1, 30
	s_mov_b32 s10, s11
	s_waitcnt lgkmcnt(0)
	s_barrier
	s_cbranch_scc1 .LBB0_710
	s_waitcnt vmcnt(5)
	v_mov_b32_e32 v114, v220
	v_mov_b32_e32 v115, v153
	v_and_b32_e32 v112, 0xffffff80, v114
	s_waitcnt vmcnt(4)
	v_add_u32_e32 v116, s0, v112
	v_lshrrev_b32_e32 v112, 2, v114
	v_and_b32_e32 v118, 12, v112
	s_waitcnt vmcnt(3)
	v_or_b32_e32 v120, v118, v116
	v_ashrrev_i32_e32 v121, 31, v120
	v_lshl_add_u64 v[112:113], v[120:121], 2, s[14:15]
	global_load_dwordx4 v[132:135], v[112:113], off
	v_ashrrev_i32_e32 v122, 14, v116
	v_ashrrev_i32_e32 v123, 31, v122
	v_lshlrev_b64 v[122:123], 10, v[122:123]
	v_mov_b64_e32 v[112:113], s[34:35]
	s_waitcnt vmcnt(3)
	v_lshrrev_b32_e32 v126, 6, v116
	v_or_b32_e32 v124, 16, v120
	v_lshl_or_b32 v121, s12, 8, v122
	v_ashrrev_i32_e32 v125, 31, v124
	v_and_or_b32 v122, v126, s49, v121
	s_waitcnt vmcnt(1)
	v_lshl_add_u64 v[136:137], v[124:125], 2, s[14:15]
	v_lshlrev_b64 v[124:125], 14, v[122:123]
	v_lshlrev_b32_e32 v114, 7, v114
	v_lshlrev_b32_e32 v152, 1, v118
	v_lshl_add_u64 v[124:125], s[38:39], 0, v[124:125]
	v_and_b32_e32 v114, 0x2780, v114
	v_lshl_add_u64 v[126:127], v[124:125], 0, v[152:153]
	v_mov_b32_e32 v117, v153
	v_mov_b32_e32 v119, v153
	v_or_b32_e32 v116, 0x1000, v114
	v_or_b32_e32 v118, 0x1800, v114
	v_lshl_add_u64 v[124:125], v[126:127], 0, v[114:115]
	v_lshl_add_u64 v[138:139], v[126:127], 0, v[116:117]
	v_lshl_add_u64 v[154:155], v[126:127], 0, v[118:119]
	s_waitcnt vmcnt(0)
	v_pk_fma_f32 v[132:133], v[132:133], s[30:31], v[112:113] op_sel_hi:[1,0,0]
	v_pk_fma_f32 v[134:135], v[134:135], s[30:31], v[112:113] op_sel_hi:[1,0,0]
	v_mul_f32_e32 v122, 0x4b800000, v132
	v_mul_f32_e32 v156, 0x4b800000, v133
	v_mul_f32_e32 v157, 0x4b800000, v134
	v_mul_f32_e32 v158, 0x4b800000, v135
	v_cmp_gt_f32_e32 vcc, s40, v132
	v_cmp_gt_f32_e64 s[0:1], s40, v133
	v_cmp_gt_f32_e64 s[10:11], s40, v134
	v_cmp_gt_f32_e64 s[12:13], s40, v135
	v_cndmask_b32_e32 v122, v132, v122, vcc
	v_cndmask_b32_e64 v132, v133, v156, s[0:1]
	v_cndmask_b32_e64 v133, v134, v157, s[10:11]
	v_cndmask_b32_e64 v134, v135, v158, s[12:13]
	v_rsq_f32_e32 v122, v122
	v_rsq_f32_e32 v132, v132
	v_rsq_f32_e32 v133, v133
	v_rsq_f32_e32 v134, v134
	v_mul_f32_e32 v135, 0x45800000, v122
	v_mul_f32_e32 v156, 0x45800000, v132
	v_mul_f32_e32 v157, 0x45800000, v133
	v_mul_f32_e32 v158, 0x45800000, v134
	v_cndmask_b32_e32 v122, v122, v135, vcc
	v_cndmask_b32_e64 v132, v132, v156, s[0:1]
	v_cndmask_b32_e64 v133, v133, v157, s[10:11]
	v_cndmask_b32_e64 v134, v134, v158, s[12:13]
	v_mul_f32_e32 v135, v148, v122
	v_mul_f32_e32 v148, v149, v132
	v_mul_f32_e32 v149, v150, v133
	v_mul_f32_e32 v150, v151, v134
	v_mul_f32_e32 v144, v144, v122
	v_mul_f32_e32 v140, v140, v122
	v_mul_f32_e32 v122, v128, v122
	v_mul_f32_e32 v151, v129, v132
	v_cvt_pk_bf16_f32 v128, v135, v148
	v_cvt_pk_bf16_f32 v129, v149, v150
	v_mul_f32_e32 v145, v145, v132
	v_mul_f32_e32 v146, v146, v133
	v_mul_f32_e32 v147, v147, v134
	v_mul_f32_e32 v141, v141, v132
	v_mul_f32_e32 v142, v142, v133
	v_mul_f32_e32 v143, v143, v134
	v_mul_f32_e32 v156, v130, v133
	v_mul_f32_e32 v157, v131, v134
	v_cvt_pk_bf16_f32 v130, v144, v145
	v_cvt_pk_bf16_f32 v131, v146, v147
	v_cvt_pk_bf16_f32 v132, v140, v141
	v_cvt_pk_bf16_f32 v133, v142, v143
	v_cvt_pk_bf16_f32 v134, v122, v151
	v_cvt_pk_bf16_f32 v135, v156, v157
	global_store_dwordx2 v[124:125], v[128:129], off
	global_store_dwordx2 v[124:125], v[130:131], off offset:2048
	global_store_dwordx2 v[138:139], v[132:133], off
	global_store_dwordx2 v[154:155], v[134:135], off
	global_load_dwordx4 v[128:131], v[136:137], off
	v_or_b32_e32 v132, 32, v120
	v_ashrrev_i32_e32 v133, 31, v132
	v_lshl_add_u64 v[134:135], v[126:127], 0, 32
	v_lshl_add_u64 v[132:133], v[132:133], 2, s[14:15]
	v_lshl_add_u64 v[136:137], v[134:135], 0, v[116:117]
	v_lshl_add_u64 v[134:135], v[134:135], 0, v[118:119]
	s_waitcnt vmcnt(0)
	v_pk_fma_f32 v[128:129], v[128:129], s[30:31], v[112:113] op_sel_hi:[1,0,0]
	v_pk_fma_f32 v[130:131], v[130:131], s[30:31], v[112:113] op_sel_hi:[1,0,0]
	v_mul_f32_e32 v122, 0x4b800000, v128
	v_mul_f32_e32 v138, 0x4b800000, v129
	v_mul_f32_e32 v139, 0x4b800000, v130
	v_mul_f32_e32 v140, 0x4b800000, v131
	v_cmp_gt_f32_e32 vcc, s40, v128
	v_cmp_gt_f32_e64 s[0:1], s40, v129
	v_cmp_gt_f32_e64 s[10:11], s40, v130
	v_cmp_gt_f32_e64 s[12:13], s40, v131
	v_cndmask_b32_e32 v122, v128, v122, vcc
	v_cndmask_b32_e64 v128, v129, v138, s[0:1]
	v_cndmask_b32_e64 v129, v130, v139, s[10:11]
	v_cndmask_b32_e64 v130, v131, v140, s[12:13]
	v_rsq_f32_e32 v122, v122
	v_rsq_f32_e32 v128, v128
	v_rsq_f32_e32 v129, v129
	v_rsq_f32_e32 v130, v130
	v_mul_f32_e32 v131, 0x45800000, v122
	v_mul_f32_e32 v138, 0x45800000, v128
	v_mul_f32_e32 v139, 0x45800000, v129
	v_mul_f32_e32 v140, 0x45800000, v130
	v_cndmask_b32_e32 v122, v122, v131, vcc
	v_cndmask_b32_e64 v128, v128, v138, s[0:1]
	v_cndmask_b32_e64 v129, v129, v139, s[10:11]
	v_cndmask_b32_e64 v130, v130, v140, s[12:13]
	v_mul_f32_e32 v108, v108, v122
	v_mul_f32_e32 v109, v109, v128
	v_mul_f32_e32 v110, v110, v129
	v_mul_f32_e32 v111, v111, v130
	v_mul_f32_e32 v104, v104, v122
	v_mul_f32_e32 v105, v105, v128
	v_mul_f32_e32 v100, v100, v122
	v_mul_f32_e32 v101, v101, v128
	v_mul_f32_e32 v102, v102, v129
	v_mul_f32_e32 v103, v103, v130
	v_mul_f32_e32 v122, v96, v122
	v_mul_f32_e32 v128, v97, v128
	v_cvt_pk_bf16_f32 v96, v108, v109
	v_cvt_pk_bf16_f32 v97, v110, v111
	v_mul_f32_e32 v106, v106, v129
	v_mul_f32_e32 v107, v107, v130
	v_mul_f32_e32 v129, v98, v129
	v_mul_f32_e32 v130, v99, v130
	v_cvt_pk_bf16_f32 v98, v104, v105
	v_cvt_pk_bf16_f32 v99, v106, v107
	v_cvt_pk_bf16_f32 v100, v100, v101
	v_cvt_pk_bf16_f32 v101, v102, v103
	v_cvt_pk_bf16_f32 v102, v122, v128
	v_cvt_pk_bf16_f32 v103, v129, v130
	global_store_dwordx2 v[124:125], v[96:97], off offset:32
	global_store_dwordx2 v[124:125], v[98:99], off offset:2080
	global_store_dwordx2 v[136:137], v[100:101], off
	global_store_dwordx2 v[134:135], v[102:103], off
	global_load_dwordx4 v[96:99], v[132:133], off
	v_or_b32_e32 v100, 48, v120
	v_ashrrev_i32_e32 v101, 31, v100
	v_lshl_add_u64 v[102:103], v[126:127], 0, 64
	v_lshl_add_u64 v[100:101], v[100:101], 2, s[14:15]
	v_lshl_add_u64 v[104:105], v[102:103], 0, v[116:117]
	v_lshl_add_u64 v[102:103], v[102:103], 0, v[118:119]
	s_waitcnt vmcnt(0)
	v_pk_fma_f32 v[96:97], v[96:97], s[30:31], v[112:113] op_sel_hi:[1,0,0]
	v_pk_fma_f32 v[98:99], v[98:99], s[30:31], v[112:113] op_sel_hi:[1,0,0]
	v_mul_f32_e32 v106, 0x4b800000, v96
	v_mul_f32_e32 v107, 0x4b800000, v97
	v_mul_f32_e32 v108, 0x4b800000, v98
	v_mul_f32_e32 v109, 0x4b800000, v99
	v_cmp_gt_f32_e32 vcc, s40, v96
	v_cmp_gt_f32_e64 s[0:1], s40, v97
	v_cmp_gt_f32_e64 s[10:11], s40, v98
	v_cmp_gt_f32_e64 s[12:13], s40, v99
	v_cndmask_b32_e32 v96, v96, v106, vcc
	v_cndmask_b32_e64 v97, v97, v107, s[0:1]
	v_cndmask_b32_e64 v98, v98, v108, s[10:11]
	v_cndmask_b32_e64 v99, v99, v109, s[12:13]
	v_rsq_f32_e32 v96, v96
	v_rsq_f32_e32 v97, v97
	v_rsq_f32_e32 v98, v98
	v_rsq_f32_e32 v99, v99
	v_mul_f32_e32 v106, 0x45800000, v96
	v_mul_f32_e32 v107, 0x45800000, v97
	v_mul_f32_e32 v108, 0x45800000, v98
	v_mul_f32_e32 v109, 0x45800000, v99
	v_cndmask_b32_e32 v96, v96, v106, vcc
	v_cndmask_b32_e64 v97, v97, v107, s[0:1]
	v_cndmask_b32_e64 v98, v98, v108, s[10:11]
	v_cndmask_b32_e64 v99, v99, v109, s[12:13]
	v_mul_f32_e32 v92, v92, v96
	v_mul_f32_e32 v93, v93, v97
	v_mul_f32_e32 v94, v94, v98
	v_mul_f32_e32 v95, v95, v99
	v_mul_f32_e32 v88, v88, v96
	v_mul_f32_e32 v89, v89, v97
	v_mul_f32_e32 v84, v84, v96
	v_mul_f32_e32 v85, v85, v97
	v_mul_f32_e32 v86, v86, v98
	v_mul_f32_e32 v87, v87, v99
	v_mul_f32_e32 v96, v80, v96
	v_mul_f32_e32 v97, v81, v97
	v_cvt_pk_bf16_f32 v80, v92, v93
	v_cvt_pk_bf16_f32 v81, v94, v95
	v_mul_f32_e32 v90, v90, v98
	v_mul_f32_e32 v91, v91, v99
	v_mul_f32_e32 v98, v82, v98
	v_mul_f32_e32 v99, v83, v99
	v_cvt_pk_bf16_f32 v82, v88, v89
	v_cvt_pk_bf16_f32 v83, v90, v91
	v_cvt_pk_bf16_f32 v84, v84, v85
	v_cvt_pk_bf16_f32 v85, v86, v87
	v_cvt_pk_bf16_f32 v86, v96, v97
	v_cvt_pk_bf16_f32 v87, v98, v99
	global_store_dwordx2 v[124:125], v[80:81], off offset:64
	global_store_dwordx2 v[124:125], v[82:83], off offset:2112
	global_store_dwordx2 v[104:105], v[84:85], off
	global_store_dwordx2 v[102:103], v[86:87], off
	global_load_dwordx4 v[80:83], v[100:101], off
	v_or_b32_e32 v84, 64, v120
	v_ashrrev_i32_e32 v85, 31, v84
	v_lshl_add_u64 v[86:87], v[84:85], 2, s[14:15]
	v_lshl_add_u64 v[88:89], v[126:127], 0, s[36:37]
	v_lshl_add_u64 v[90:91], v[88:89], 0, v[116:117]
	v_lshl_add_u64 v[88:89], v[88:89], 0, v[118:119]
	s_waitcnt vmcnt(0)
	v_pk_fma_f32 v[80:81], v[80:81], s[30:31], v[112:113] op_sel_hi:[1,0,0]
	v_pk_fma_f32 v[82:83], v[82:83], s[30:31], v[112:113] op_sel_hi:[1,0,0]
	v_mul_f32_e32 v85, 0x4b800000, v80
	v_mul_f32_e32 v92, 0x4b800000, v81
	v_mul_f32_e32 v93, 0x4b800000, v82
	v_mul_f32_e32 v94, 0x4b800000, v83
	v_cmp_gt_f32_e32 vcc, s40, v80
	v_cmp_gt_f32_e64 s[0:1], s40, v81
	v_cmp_gt_f32_e64 s[10:11], s40, v82
	v_cmp_gt_f32_e64 s[12:13], s40, v83
	v_cndmask_b32_e32 v80, v80, v85, vcc
	v_cndmask_b32_e64 v81, v81, v92, s[0:1]
	v_cndmask_b32_e64 v82, v82, v93, s[10:11]
	v_cndmask_b32_e64 v83, v83, v94, s[12:13]
	v_rsq_f32_e32 v80, v80
	v_rsq_f32_e32 v81, v81
	v_rsq_f32_e32 v82, v82
	v_rsq_f32_e32 v83, v83
	v_mul_f32_e32 v85, 0x45800000, v80
	v_mul_f32_e32 v92, 0x45800000, v81
	v_mul_f32_e32 v93, 0x45800000, v82
	v_mul_f32_e32 v94, 0x45800000, v83
	v_cndmask_b32_e32 v80, v80, v85, vcc
	v_cndmask_b32_e64 v81, v81, v92, s[0:1]
	v_cndmask_b32_e64 v82, v82, v93, s[10:11]
	v_cndmask_b32_e64 v83, v83, v94, s[12:13]
	v_mul_f32_e32 v76, v76, v80
	v_mul_f32_e32 v77, v77, v81
	v_mul_f32_e32 v78, v78, v82
	v_mul_f32_e32 v79, v79, v83
	v_mul_f32_e32 v72, v72, v80
	v_mul_f32_e32 v73, v73, v81
	v_mul_f32_e32 v68, v68, v80
	v_mul_f32_e32 v69, v69, v81
	v_mul_f32_e32 v70, v70, v82
	v_mul_f32_e32 v71, v71, v83
	v_mul_f32_e32 v80, v64, v80
	v_mul_f32_e32 v81, v65, v81
	v_cvt_pk_bf16_f32 v64, v76, v77
	v_cvt_pk_bf16_f32 v65, v78, v79
	v_mul_f32_e32 v74, v74, v82
	v_mul_f32_e32 v75, v75, v83
	v_mul_f32_e32 v82, v66, v82
	v_mul_f32_e32 v83, v67, v83
	v_cvt_pk_bf16_f32 v66, v72, v73
	v_cvt_pk_bf16_f32 v67, v74, v75
	v_cvt_pk_bf16_f32 v68, v68, v69
	v_cvt_pk_bf16_f32 v69, v70, v71
	v_cvt_pk_bf16_f32 v70, v80, v81
	v_cvt_pk_bf16_f32 v71, v82, v83
	global_store_dwordx2 v[124:125], v[64:65], off offset:96
	global_store_dwordx2 v[124:125], v[66:67], off offset:2144
	global_store_dwordx2 v[90:91], v[68:69], off
	global_store_dwordx2 v[88:89], v[70:71], off
	global_load_dwordx4 v[64:67], v[86:87], off
	v_or_b32_e32 v68, 0x50, v120
	v_ashrrev_i32_e32 v69, 31, v68
	v_lshl_add_u64 v[70:71], v[68:69], 2, s[14:15]
	v_lshrrev_b32_e32 v72, 6, v84
	v_and_or_b32 v122, v72, s50, v121
	v_lshlrev_b64 v[72:73], 14, v[122:123]
	v_lshl_add_u64 v[72:73], s[38:39], 0, v[72:73]
	v_lshl_add_u64 v[72:73], v[72:73], 0, v[152:153]
	v_lshl_add_u64 v[74:75], v[72:73], 0, v[114:115]
	v_lshl_add_u64 v[76:77], v[72:73], 0, v[116:117]
	v_lshl_add_u64 v[72:73], v[72:73], 0, v[118:119]
	s_waitcnt vmcnt(0)
	v_pk_fma_f32 v[64:65], v[64:65], s[30:31], v[112:113] op_sel_hi:[1,0,0]
	v_pk_fma_f32 v[66:67], v[66:67], s[30:31], v[112:113] op_sel_hi:[1,0,0]
	v_mul_f32_e32 v69, 0x4b800000, v64
	v_mul_f32_e32 v78, 0x4b800000, v65
	v_mul_f32_e32 v79, 0x4b800000, v66
	v_mul_f32_e32 v80, 0x4b800000, v67
	v_cmp_gt_f32_e32 vcc, s40, v64
	v_cmp_gt_f32_e64 s[0:1], s40, v65
	v_cmp_gt_f32_e64 s[10:11], s40, v66
	v_cmp_gt_f32_e64 s[12:13], s40, v67
	v_cndmask_b32_e32 v64, v64, v69, vcc
	v_cndmask_b32_e64 v65, v65, v78, s[0:1]
	v_cndmask_b32_e64 v66, v66, v79, s[10:11]
	v_cndmask_b32_e64 v67, v67, v80, s[12:13]
	v_rsq_f32_e32 v64, v64
	v_rsq_f32_e32 v65, v65
	v_rsq_f32_e32 v66, v66
	v_rsq_f32_e32 v67, v67
	v_mul_f32_e32 v69, 0x45800000, v64
	v_mul_f32_e32 v78, 0x45800000, v65
	v_mul_f32_e32 v79, 0x45800000, v66
	v_mul_f32_e32 v80, 0x45800000, v67
	v_cndmask_b32_e32 v64, v64, v69, vcc
	v_cndmask_b32_e64 v65, v65, v78, s[0:1]
	v_cndmask_b32_e64 v66, v66, v79, s[10:11]
	v_cndmask_b32_e64 v67, v67, v80, s[12:13]
	v_mul_f32_e32 v60, v60, v64
	v_mul_f32_e32 v61, v61, v65
	v_mul_f32_e32 v62, v62, v66
	v_mul_f32_e32 v63, v63, v67
	v_mul_f32_e32 v56, v56, v64
	v_mul_f32_e32 v57, v57, v65
	v_mul_f32_e32 v52, v52, v64
	v_mul_f32_e32 v53, v53, v65
	v_mul_f32_e32 v54, v54, v66
	v_mul_f32_e32 v55, v55, v67
	v_mul_f32_e32 v64, v48, v64
	v_mul_f32_e32 v65, v49, v65
	v_cvt_pk_bf16_f32 v48, v60, v61
	v_cvt_pk_bf16_f32 v49, v62, v63
	v_mul_f32_e32 v58, v58, v66
	v_mul_f32_e32 v59, v59, v67
	v_mul_f32_e32 v66, v50, v66
	v_mul_f32_e32 v67, v51, v67
	v_cvt_pk_bf16_f32 v50, v56, v57
	v_cvt_pk_bf16_f32 v51, v58, v59
	v_cvt_pk_bf16_f32 v52, v52, v53
	v_cvt_pk_bf16_f32 v53, v54, v55
	v_cvt_pk_bf16_f32 v54, v64, v65
	v_cvt_pk_bf16_f32 v55, v66, v67
	global_store_dwordx2 v[74:75], v[48:49], off
	global_store_dwordx2 v[74:75], v[50:51], off offset:2048
	global_store_dwordx2 v[76:77], v[52:53], off
	global_store_dwordx2 v[72:73], v[54:55], off
	global_load_dwordx4 v[48:51], v[70:71], off
	v_or_b32_e32 v52, 0x60, v120
	v_ashrrev_i32_e32 v53, 31, v52
	v_lshl_add_u64 v[54:55], v[52:53], 2, s[14:15]
	v_lshrrev_b32_e32 v56, 6, v68
	v_and_or_b32 v122, v56, s50, v121
	v_lshlrev_b64 v[56:57], 14, v[122:123]
	v_lshl_add_u64 v[56:57], s[38:39], 0, v[56:57]
	v_lshl_add_u64 v[56:57], v[56:57], 0, v[152:153]
	v_lshl_add_u64 v[58:59], v[56:57], 0, 32
	v_lshl_add_u64 v[56:57], v[56:57], 0, v[114:115]
	v_lshl_add_u64 v[60:61], v[58:59], 0, v[116:117]
	v_lshl_add_u64 v[58:59], v[58:59], 0, v[118:119]
	s_waitcnt vmcnt(0)
	v_pk_fma_f32 v[48:49], v[48:49], s[30:31], v[112:113] op_sel_hi:[1,0,0]
	v_pk_fma_f32 v[50:51], v[50:51], s[30:31], v[112:113] op_sel_hi:[1,0,0]
	v_mul_f32_e32 v53, 0x4b800000, v48
	v_mul_f32_e32 v62, 0x4b800000, v49
	v_mul_f32_e32 v63, 0x4b800000, v50
	v_mul_f32_e32 v64, 0x4b800000, v51
	v_cmp_gt_f32_e32 vcc, s40, v48
	v_cmp_gt_f32_e64 s[0:1], s40, v49
	v_cmp_gt_f32_e64 s[10:11], s40, v50
	v_cmp_gt_f32_e64 s[12:13], s40, v51
	v_cndmask_b32_e32 v48, v48, v53, vcc
	v_cndmask_b32_e64 v49, v49, v62, s[0:1]
	v_cndmask_b32_e64 v50, v50, v63, s[10:11]
	v_cndmask_b32_e64 v51, v51, v64, s[12:13]
	v_rsq_f32_e32 v48, v48
	v_rsq_f32_e32 v49, v49
	v_rsq_f32_e32 v50, v50
	v_rsq_f32_e32 v51, v51
	v_mul_f32_e32 v53, 0x45800000, v48
	v_mul_f32_e32 v62, 0x45800000, v49
	v_mul_f32_e32 v63, 0x45800000, v50
	v_mul_f32_e32 v64, 0x45800000, v51
	v_cndmask_b32_e32 v48, v48, v53, vcc
	v_cndmask_b32_e64 v49, v49, v62, s[0:1]
	v_cndmask_b32_e64 v50, v50, v63, s[10:11]
	v_cndmask_b32_e64 v51, v51, v64, s[12:13]
	v_mul_f32_e32 v44, v44, v48
	v_mul_f32_e32 v45, v45, v49
	v_mul_f32_e32 v46, v46, v50
	v_mul_f32_e32 v47, v47, v51
	v_mul_f32_e32 v40, v40, v48
	v_mul_f32_e32 v41, v41, v49
	v_mul_f32_e32 v36, v36, v48
	v_mul_f32_e32 v37, v37, v49
	v_mul_f32_e32 v38, v38, v50
	v_mul_f32_e32 v39, v39, v51
	v_mul_f32_e32 v48, v32, v48
	v_mul_f32_e32 v49, v33, v49
	v_cvt_pk_bf16_f32 v32, v44, v45
	v_cvt_pk_bf16_f32 v33, v46, v47
	v_mul_f32_e32 v42, v42, v50
	v_mul_f32_e32 v43, v43, v51
	v_mul_f32_e32 v50, v34, v50
	v_mul_f32_e32 v51, v35, v51
	v_cvt_pk_bf16_f32 v34, v40, v41
	v_cvt_pk_bf16_f32 v35, v42, v43
	v_cvt_pk_bf16_f32 v36, v36, v37
	v_cvt_pk_bf16_f32 v37, v38, v39
	v_cvt_pk_bf16_f32 v38, v48, v49
	v_cvt_pk_bf16_f32 v39, v50, v51
	global_store_dwordx2 v[56:57], v[32:33], off offset:32
	global_store_dwordx2 v[56:57], v[34:35], off offset:2080
	global_store_dwordx2 v[60:61], v[36:37], off
	global_store_dwordx2 v[58:59], v[38:39], off
	global_load_dwordx4 v[32:35], v[54:55], off
	v_or_b32_e32 v36, 0x70, v120
	v_ashrrev_i32_e32 v37, 31, v36
	v_lshl_add_u64 v[38:39], v[36:37], 2, s[14:15]
	v_lshrrev_b32_e32 v40, 6, v52
	v_and_or_b32 v122, v40, s50, v121
	v_lshlrev_b64 v[40:41], 14, v[122:123]
	v_lshl_add_u64 v[40:41], s[38:39], 0, v[40:41]
	v_lshl_add_u64 v[40:41], v[40:41], 0, v[152:153]
	v_lshl_add_u64 v[42:43], v[40:41], 0, 64
	v_lshl_add_u64 v[40:41], v[40:41], 0, v[114:115]
	v_lshl_add_u64 v[44:45], v[42:43], 0, v[116:117]
	v_lshl_add_u64 v[42:43], v[42:43], 0, v[118:119]
	s_waitcnt vmcnt(0)
	v_pk_fma_f32 v[32:33], v[32:33], s[30:31], v[112:113] op_sel_hi:[1,0,0]
	v_pk_fma_f32 v[34:35], v[34:35], s[30:31], v[112:113] op_sel_hi:[1,0,0]
	v_mul_f32_e32 v37, 0x4b800000, v32
	v_mul_f32_e32 v46, 0x4b800000, v33
	v_mul_f32_e32 v47, 0x4b800000, v34
	v_mul_f32_e32 v48, 0x4b800000, v35
	v_cmp_gt_f32_e32 vcc, s40, v32
	v_cmp_gt_f32_e64 s[0:1], s40, v33
	v_cmp_gt_f32_e64 s[10:11], s40, v34
	v_cmp_gt_f32_e64 s[12:13], s40, v35
	v_cndmask_b32_e32 v32, v32, v37, vcc
	v_cndmask_b32_e64 v33, v33, v46, s[0:1]
	v_cndmask_b32_e64 v34, v34, v47, s[10:11]
	v_cndmask_b32_e64 v35, v35, v48, s[12:13]
	v_rsq_f32_e32 v32, v32
	v_rsq_f32_e32 v33, v33
	v_rsq_f32_e32 v34, v34
	v_rsq_f32_e32 v35, v35
	v_mul_f32_e32 v37, 0x45800000, v32
	v_mul_f32_e32 v46, 0x45800000, v33
	v_mul_f32_e32 v47, 0x45800000, v34
	v_mul_f32_e32 v48, 0x45800000, v35
	v_cndmask_b32_e32 v32, v32, v37, vcc
	v_cndmask_b32_e64 v33, v33, v46, s[0:1]
	v_cndmask_b32_e64 v34, v34, v47, s[10:11]
	v_cndmask_b32_e64 v35, v35, v48, s[12:13]
	v_mul_f32_e32 v28, v28, v32
	v_mul_f32_e32 v29, v29, v33
	v_mul_f32_e32 v30, v30, v34
	v_mul_f32_e32 v31, v31, v35
	v_mul_f32_e32 v24, v24, v32
	v_mul_f32_e32 v25, v25, v33
	v_mul_f32_e32 v20, v20, v32
	v_mul_f32_e32 v21, v21, v33
	v_mul_f32_e32 v22, v22, v34
	v_mul_f32_e32 v23, v23, v35
	v_mul_f32_e32 v32, v16, v32
	v_mul_f32_e32 v33, v17, v33
	v_cvt_pk_bf16_f32 v16, v28, v29
	v_cvt_pk_bf16_f32 v17, v30, v31
	v_mul_f32_e32 v26, v26, v34
	v_mul_f32_e32 v27, v27, v35
	v_mul_f32_e32 v34, v18, v34
	v_mul_f32_e32 v35, v19, v35
	v_cvt_pk_bf16_f32 v18, v24, v25
	v_cvt_pk_bf16_f32 v19, v26, v27
	v_cvt_pk_bf16_f32 v20, v20, v21
	v_cvt_pk_bf16_f32 v21, v22, v23
	v_cvt_pk_bf16_f32 v22, v32, v33
	v_cvt_pk_bf16_f32 v23, v34, v35
	global_store_dwordx2 v[40:41], v[16:17], off offset:64
	global_store_dwordx2 v[40:41], v[18:19], off offset:2112
	global_store_dwordx2 v[44:45], v[20:21], off
	global_store_dwordx2 v[42:43], v[22:23], off
	global_load_dwordx4 v[16:19], v[38:39], off
	v_lshrrev_b32_e32 v20, 6, v36
	v_and_or_b32 v122, v20, s50, v121
	v_lshlrev_b64 v[20:21], 14, v[122:123]
	v_lshl_add_u64 v[20:21], s[38:39], 0, v[20:21]
	v_lshl_add_u64 v[20:21], v[20:21], 0, v[152:153]
	v_lshl_add_u64 v[22:23], v[20:21], 0, s[36:37]
	v_lshl_add_u64 v[20:21], v[20:21], 0, v[114:115]
	v_lshl_add_u64 v[24:25], v[22:23], 0, v[116:117]
	v_lshl_add_u64 v[22:23], v[22:23], 0, v[118:119]
	s_waitcnt vmcnt(0)
	v_pk_fma_f32 v[16:17], v[16:17], s[30:31], v[112:113] op_sel_hi:[1,0,0]
	v_pk_fma_f32 v[18:19], v[18:19], s[30:31], v[112:113] op_sel_hi:[1,0,0]
	v_mul_f32_e32 v26, 0x4b800000, v16
	v_mul_f32_e32 v27, 0x4b800000, v17
	v_mul_f32_e32 v28, 0x4b800000, v18
	v_mul_f32_e32 v29, 0x4b800000, v19
	v_cmp_gt_f32_e32 vcc, s40, v16
	v_cmp_gt_f32_e64 s[0:1], s40, v17
	v_cmp_gt_f32_e64 s[10:11], s40, v18
	v_cmp_gt_f32_e64 s[12:13], s40, v19
	v_cndmask_b32_e32 v16, v16, v26, vcc
	v_cndmask_b32_e64 v17, v17, v27, s[0:1]
	v_cndmask_b32_e64 v18, v18, v28, s[10:11]
	v_cndmask_b32_e64 v19, v19, v29, s[12:13]
	v_rsq_f32_e32 v16, v16
	v_rsq_f32_e32 v17, v17
	v_rsq_f32_e32 v18, v18
	v_rsq_f32_e32 v19, v19
	v_mul_f32_e32 v26, 0x45800000, v16
	v_mul_f32_e32 v27, 0x45800000, v17
	v_mul_f32_e32 v28, 0x45800000, v18
	v_mul_f32_e32 v29, 0x45800000, v19
	v_cndmask_b32_e32 v16, v16, v26, vcc
	v_cndmask_b32_e64 v17, v17, v27, s[0:1]
	v_cndmask_b32_e64 v18, v18, v28, s[10:11]
	v_cndmask_b32_e64 v19, v19, v29, s[12:13]
	v_mul_f32_e32 v12, v12, v16
	v_mul_f32_e32 v13, v13, v17
	v_mul_f32_e32 v14, v14, v18
	v_mul_f32_e32 v15, v15, v19
	v_mul_f32_e32 v8, v8, v16
	v_mul_f32_e32 v9, v9, v17
	v_mul_f32_e32 v4, v4, v16
	v_mul_f32_e32 v5, v5, v17
	v_mul_f32_e32 v6, v6, v18
	v_mul_f32_e32 v7, v7, v19
	v_mul_f32_e32 v16, v0, v16
	v_mul_f32_e32 v17, v1, v17
	v_cvt_pk_bf16_f32 v0, v12, v13
	v_cvt_pk_bf16_f32 v1, v14, v15
	v_mul_f32_e32 v10, v10, v18
	v_mul_f32_e32 v11, v11, v19
	v_mul_f32_e32 v18, v2, v18
	v_mul_f32_e32 v19, v3, v19
	v_cvt_pk_bf16_f32 v2, v8, v9
	v_cvt_pk_bf16_f32 v3, v10, v11
	v_cvt_pk_bf16_f32 v4, v4, v5
	v_cvt_pk_bf16_f32 v5, v6, v7
	v_cvt_pk_bf16_f32 v6, v16, v17
	v_cvt_pk_bf16_f32 v7, v18, v19
	global_store_dwordx2 v[20:21], v[0:1], off offset:96
	global_store_dwordx2 v[20:21], v[2:3], off offset:2144
	global_store_dwordx2 v[24:25], v[4:5], off
	global_store_dwordx2 v[22:23], v[6:7], off
	s_branch .LBB0_699

.LBB0_769:
	s_add_i32 s14, s13, 64
	s_min_u32 s15, s14, 0x3e0
	s_lshl_b32 s34, s15, 1
	v_lshl_add_u64 v[172:173], v[154:155], 0, s[34:35]
	v_lshl_add_u64 v[176:177], v[158:159], 0, s[34:35]
	v_lshl_add_u64 v[180:181], v[160:161], 0, s[34:35]
	v_lshl_add_u64 v[184:185], v[162:163], 0, s[34:35]
	v_lshl_add_u64 v[188:189], v[156:157], 0, s[34:35]
	v_lshl_add_u64 v[192:193], v[164:165], 0, s[34:35]
	global_load_dwordx4 v[172:175], v[172:173], off
	ds_read_b128 v[196:199], v171 offset:32768
	global_load_dwordx4 v[176:179], v[176:177], off
	ds_read_b128 v[200:203], v171 offset:33792
	global_load_dwordx4 v[180:183], v[180:181], off
	ds_read_b128 v[204:207], v171 offset:34816
	global_load_dwordx4 v[184:187], v[184:185], off
	ds_read_b128 v[208:211], v171 offset:35840
	global_load_dwordx4 v[188:191], v[188:189], off
	ds_read_b128 v[212:215], v169
	global_load_dwordx4 v[192:195], v[192:193], off
	ds_read_b128 v[216:219], v169 offset:1024
	ds_read_b128 v[222:225], v169 offset:2048
	ds_read_b128 v[226:229], v169 offset:3072
	ds_read_b128 v[230:233], v169 offset:4096
	ds_read_b128 v[234:237], v169 offset:5120
	ds_read_b128 v[238:241], v169 offset:6144
	ds_read_b128 v[242:245], v169 offset:7168
	s_setprio 1
	s_waitcnt lgkmcnt(7)
	v_mfma_f32_16x16x32_bf16 v[148:151], v[196:199], v[212:215], v[148:151]
	v_mfma_f32_16x16x32_bf16 v[144:147], v[200:203], v[212:215], v[144:147]
	v_mfma_f32_16x16x32_bf16 v[116:119], v[204:207], v[212:215], v[116:119]
	v_mfma_f32_16x16x32_bf16 v[112:115], v[208:211], v[212:215], v[112:115]
	s_waitcnt vmcnt(11)
	ds_write_b128 v152, v[120:123] offset:16384
	s_waitcnt lgkmcnt(7)
	v_mfma_f32_16x16x32_bf16 v[108:111], v[196:199], v[216:219], v[108:111]
	v_mfma_f32_16x16x32_bf16 v[104:107], v[200:203], v[216:219], v[104:107]
	v_mfma_f32_16x16x32_bf16 v[100:103], v[204:207], v[216:219], v[100:103]
	v_mfma_f32_16x16x32_bf16 v[96:99], v[208:211], v[216:219], v[96:99]
	s_waitcnt vmcnt(9)
	ds_write_b128 v152, v[128:131] offset:20480
	s_waitcnt lgkmcnt(7)
	v_mfma_f32_16x16x32_bf16 v[92:95], v[196:199], v[222:225], v[92:95]
	v_mfma_f32_16x16x32_bf16 v[88:91], v[200:203], v[222:225], v[88:91]
	v_mfma_f32_16x16x32_bf16 v[84:87], v[204:207], v[222:225], v[84:87]
	v_mfma_f32_16x16x32_bf16 v[80:83], v[208:211], v[222:225], v[80:83]
	s_waitcnt vmcnt(8)
	ds_write_b128 v152, v[132:135] offset:24576
	s_waitcnt lgkmcnt(7)
	v_mfma_f32_16x16x32_bf16 v[76:79], v[196:199], v[226:229], v[76:79]
	v_mfma_f32_16x16x32_bf16 v[72:75], v[200:203], v[226:229], v[72:75]
	v_mfma_f32_16x16x32_bf16 v[68:71], v[204:207], v[226:229], v[68:71]
	v_mfma_f32_16x16x32_bf16 v[64:67], v[208:211], v[226:229], v[64:67]
	s_waitcnt vmcnt(7)
	ds_write_b128 v152, v[136:139] offset:28672
	s_waitcnt lgkmcnt(7)
	v_mfma_f32_16x16x32_bf16 v[60:63], v[196:199], v[230:233], v[60:63]
	v_mfma_f32_16x16x32_bf16 v[56:59], v[200:203], v[230:233], v[56:59]
	v_mfma_f32_16x16x32_bf16 v[52:55], v[204:207], v[230:233], v[52:55]
	v_mfma_f32_16x16x32_bf16 v[48:51], v[208:211], v[230:233], v[48:51]
	s_waitcnt vmcnt(7)
	ds_write_b128 v152, v[124:127] offset:40960
	s_waitcnt lgkmcnt(7)
	v_mfma_f32_16x16x32_bf16 v[44:47], v[196:199], v[234:237], v[44:47]
	v_mfma_f32_16x16x32_bf16 v[40:43], v[200:203], v[234:237], v[40:43]
	v_mfma_f32_16x16x32_bf16 v[36:39], v[204:207], v[234:237], v[36:39]
	v_mfma_f32_16x16x32_bf16 v[32:35], v[208:211], v[234:237], v[32:35]
	s_waitcnt vmcnt(6)
	ds_write_b128 v152, v[140:143] offset:45056
	s_waitcnt lgkmcnt(7)
	v_mfma_f32_16x16x32_bf16 v[28:31], v[196:199], v[238:241], v[28:31]
	v_mfma_f32_16x16x32_bf16 v[24:27], v[200:203], v[238:241], v[24:27]
	v_mfma_f32_16x16x32_bf16 v[20:23], v[204:207], v[238:241], v[20:23]
	v_mfma_f32_16x16x32_bf16 v[16:19], v[208:211], v[238:241], v[16:19]
	s_waitcnt lgkmcnt(6)
	v_mfma_f32_16x16x32_bf16 v[12:15], v[196:199], v[242:245], v[12:15]
	v_mfma_f32_16x16x32_bf16 v[8:11], v[200:203], v[242:245], v[8:11]
	v_mfma_f32_16x16x32_bf16 v[4:7], v[204:207], v[242:245], v[4:7]
	v_mfma_f32_16x16x32_bf16 v[0:3], v[208:211], v[242:245], v[0:3]
	s_setprio 0
	s_min_u32 s13, s13, 0x380
	s_lshl_b32 s34, s13, 1
	s_mov_b32 s17, s35
	s_add_i32 s16, s34, 0xc0
	v_lshl_add_u64 v[120:121], v[154:155], 0, s[34:35]
	v_lshl_add_u64 v[124:125], v[156:157], 0, s[34:35]
	v_lshl_add_u64 v[128:129], v[158:159], 0, s[16:17]
	v_lshl_add_u64 v[132:133], v[160:161], 0, s[16:17]
	v_lshl_add_u64 v[136:137], v[162:163], 0, s[16:17]
	v_lshl_add_u64 v[140:141], v[164:165], 0, s[16:17]
	s_waitcnt lgkmcnt(0)
	s_barrier
	global_load_dwordx4 v[120:123], v[120:121], off offset:192
	ds_read_b128 v[196:199], v168 offset:40960
	global_load_dwordx4 v[124:127], v[124:125], off offset:192
	ds_read_b128 v[200:203], v168 offset:41984
	global_load_dwordx4 v[128:131], v[128:129], off
	ds_read_b128 v[204:207], v168 offset:43008
	global_load_dwordx4 v[132:135], v[132:133], off
	ds_read_b128 v[208:211], v168 offset:44032
	global_load_dwordx4 v[136:139], v[136:137], off
	ds_read_b128 v[212:215], v170
	global_load_dwordx4 v[140:143], v[140:141], off
	ds_read_b128 v[216:219], v170 offset:1024
	ds_read_b128 v[222:225], v170 offset:2048
	ds_read_b128 v[226:229], v170 offset:3072
	ds_read_b128 v[230:233], v170 offset:4096
	ds_read_b128 v[234:237], v170 offset:5120
	ds_read_b128 v[238:241], v170 offset:6144
	ds_read_b128 v[242:245], v170 offset:7168
	s_setprio 1
	s_waitcnt lgkmcnt(7)
	v_mfma_f32_16x16x32_bf16 v[148:151], v[196:199], v[212:215], v[148:151]
	v_mfma_f32_16x16x32_bf16 v[144:147], v[200:203], v[212:215], v[144:147]
	v_mfma_f32_16x16x32_bf16 v[116:119], v[204:207], v[212:215], v[116:119]
	v_mfma_f32_16x16x32_bf16 v[112:115], v[208:211], v[212:215], v[112:115]
	s_waitcnt vmcnt(11)
	ds_write_b128 v152, v[172:175]
	s_waitcnt lgkmcnt(7)
	v_mfma_f32_16x16x32_bf16 v[108:111], v[196:199], v[216:219], v[108:111]
	v_mfma_f32_16x16x32_bf16 v[104:107], v[200:203], v[216:219], v[104:107]
	v_mfma_f32_16x16x32_bf16 v[100:103], v[204:207], v[216:219], v[100:103]
	v_mfma_f32_16x16x32_bf16 v[96:99], v[208:211], v[216:219], v[96:99]
	s_waitcnt vmcnt(10)
	ds_write_b128 v152, v[176:179] offset:4096
	s_waitcnt lgkmcnt(7)
	v_mfma_f32_16x16x32_bf16 v[92:95], v[196:199], v[222:225], v[92:95]
	v_mfma_f32_16x16x32_bf16 v[88:91], v[200:203], v[222:225], v[88:91]
	v_mfma_f32_16x16x32_bf16 v[84:87], v[204:207], v[222:225], v[84:87]
	v_mfma_f32_16x16x32_bf16 v[80:83], v[208:211], v[222:225], v[80:83]
	s_waitcnt vmcnt(9)
	ds_write_b128 v152, v[180:183] offset:8192
	s_waitcnt lgkmcnt(7)
	v_mfma_f32_16x16x32_bf16 v[76:79], v[196:199], v[226:229], v[76:79]
	v_mfma_f32_16x16x32_bf16 v[72:75], v[200:203], v[226:229], v[72:75]
	v_mfma_f32_16x16x32_bf16 v[68:71], v[204:207], v[226:229], v[68:71]
	v_mfma_f32_16x16x32_bf16 v[64:67], v[208:211], v[226:229], v[64:67]
	s_waitcnt vmcnt(8)
	ds_write_b128 v152, v[184:187] offset:12288
	s_waitcnt lgkmcnt(7)
	v_mfma_f32_16x16x32_bf16 v[60:63], v[196:199], v[230:233], v[60:63]
	v_mfma_f32_16x16x32_bf16 v[56:59], v[200:203], v[230:233], v[56:59]
	v_mfma_f32_16x16x32_bf16 v[52:55], v[204:207], v[230:233], v[52:55]
	v_mfma_f32_16x16x32_bf16 v[48:51], v[208:211], v[230:233], v[48:51]
	s_waitcnt vmcnt(7)
	ds_write_b128 v152, v[188:191] offset:32768
	s_waitcnt lgkmcnt(7)
	v_mfma_f32_16x16x32_bf16 v[44:47], v[196:199], v[234:237], v[44:47]
	v_mfma_f32_16x16x32_bf16 v[40:43], v[200:203], v[234:237], v[40:43]
	v_mfma_f32_16x16x32_bf16 v[36:39], v[204:207], v[234:237], v[36:39]
	v_mfma_f32_16x16x32_bf16 v[32:35], v[208:211], v[234:237], v[32:35]
	s_waitcnt vmcnt(6)
	ds_write_b128 v152, v[192:195] offset:36864
	s_waitcnt lgkmcnt(7)
	v_mfma_f32_16x16x32_bf16 v[28:31], v[196:199], v[238:241], v[28:31]
	v_mfma_f32_16x16x32_bf16 v[24:27], v[200:203], v[238:241], v[24:27]
	v_mfma_f32_16x16x32_bf16 v[20:23], v[204:207], v[238:241], v[20:23]
	v_mfma_f32_16x16x32_bf16 v[16:19], v[208:211], v[238:241], v[16:19]
	s_waitcnt lgkmcnt(6)
	v_mfma_f32_16x16x32_bf16 v[12:15], v[196:199], v[242:245], v[12:15]
	v_mfma_f32_16x16x32_bf16 v[8:11], v[200:203], v[242:245], v[8:11]
	v_mfma_f32_16x16x32_bf16 v[4:7], v[204:207], v[242:245], v[4:7]
	v_mfma_f32_16x16x32_bf16 v[0:3], v[208:211], v[242:245], v[0:3]
	s_setprio 0
	s_add_i32 s11, s11, 2
	s_cmp_lt_u32 s11, 30
	s_mov_b32 s13, s14
	s_waitcnt lgkmcnt(0)
	s_barrier
	s_cbranch_scc1 .LBB0_769
	s_waitcnt vmcnt(4)
	v_mov_b32_e32 v126, v220
	v_mov_b64_e32 v[124:125], s[72:73]
	v_and_b32_e32 v120, 0xffffff80, v126
	v_add_u32_e32 v120, s12, v120
	v_and_or_b32 v122, v126, 15, v120
	v_ashrrev_i32_e32 v123, 31, v122
	v_lshl_add_u64 v[120:121], v[122:123], 2, s[0:1]
	global_load_dword v120, v[120:121], off
	v_and_b32_e32 v121, 64, v126
	v_lshrrev_b32_e32 v126, 2, v126
	v_and_b32_e32 v126, 12, v126
	s_waitcnt vmcnt(0)
	v_fmamk_f32 v120, v120, 0x3a800000, v167
	v_mul_f32_e32 v127, 0x4b800000, v120
	v_cmp_gt_f32_e32 vcc, s42, v120
	s_nop 1
	v_cndmask_b32_e32 v120, v120, v127, vcc
	v_rsq_f32_e32 v127, v120
	v_or3_b32 v120, v121, v126, s10
	v_mad_i64_i32 v[124:125], s[10:11], v122, s41, v[124:125]
	v_mul_f32_e32 v121, 0x45800000, v127
	v_cndmask_b32_e32 v129, v127, v121, vcc
	v_mul_f32_e32 v132, v148, v129
	v_mul_f32_e32 v131, v149, v129
	v_mul_f32_e32 v130, v150, v129
	v_mul_f32_e32 v128, v151, v129
	v_cmp_lt_i32_e64 s[10:11], s43, v120
	s_and_saveexec_b64 s[12:13], s[10:11]
	s_xor_b64 s[12:13], exec, s[12:13]
	s_cbranch_execz .LBB0_774
	v_cmp_gt_u32_e32 vcc, s44, v120
	s_and_saveexec_b64 s[14:15], vcc
	s_cbranch_execz .LBB0_773
	v_mul_f32_e32 v121, 0xbfb8aa3b, v132
	v_exp_f32_e32 v121, v121
	v_mul_f32_e32 v126, 0xbfb8aa3b, v131
	v_mul_f32_e32 v127, 0xbfb8aa3b, v128
	v_exp_f32_e32 v126, v126
	v_add_f32_e32 v121, 1.0, v121
	v_rcp_f32_e32 v132, v121
	v_mul_f32_e32 v121, 0xbfb8aa3b, v130
	v_exp_f32_e32 v121, v121
	v_exp_f32_e32 v127, v127
	v_add_f32_e32 v126, 1.0, v126
	v_rcp_f32_e32 v133, v126
	v_add_f32_e32 v121, 1.0, v121
	v_rcp_f32_e32 v134, v121
	v_add_f32_e32 v121, 1.0, v127
	v_rcp_f32_e32 v135, v121
	v_mov_b32_e32 v121, v153
	v_lshl_add_u64 v[126:127], v[120:121], 2, v[124:125]
	v_add_co_u32_e32 v126, vcc, 0x2ffe000, v126
	s_nop 1
	v_addc_co_u32_e32 v127, vcc, 0, v127, vcc
	global_store_dwordx4 v[126:127], v[132:135], off

.LBB0_1737:
	s_add_i32 s26, s25, 64
	s_min_u32 s12, s26, 0x3e0
	s_lshl_b32 s12, s12, 1
	v_lshl_add_u64 v[172:173], v[154:155], 0, s[12:13]
	v_lshl_add_u64 v[176:177], v[158:159], 0, s[12:13]
	v_lshl_add_u64 v[180:181], v[160:161], 0, s[12:13]
	v_lshl_add_u64 v[184:185], v[162:163], 0, s[12:13]
	v_lshl_add_u64 v[188:189], v[156:157], 0, s[12:13]
	v_lshl_add_u64 v[192:193], v[164:165], 0, s[12:13]
	global_load_dwordx4 v[172:175], v[172:173], off
	ds_read_b128 v[196:199], v171 offset:32768
	global_load_dwordx4 v[176:179], v[176:177], off
	ds_read_b128 v[200:203], v171 offset:33792
	global_load_dwordx4 v[180:183], v[180:181], off
	ds_read_b128 v[204:207], v171 offset:34816
	global_load_dwordx4 v[184:187], v[184:185], off
	ds_read_b128 v[208:211], v171 offset:35840
	global_load_dwordx4 v[188:191], v[188:189], off
	ds_read_b128 v[212:215], v169
	global_load_dwordx4 v[192:195], v[192:193], off
	ds_read_b128 v[216:219], v169 offset:1024
	ds_read_b128 v[222:225], v169 offset:2048
	ds_read_b128 v[226:229], v169 offset:3072
	ds_read_b128 v[230:233], v169 offset:4096
	ds_read_b128 v[234:237], v169 offset:5120
	ds_read_b128 v[238:241], v169 offset:6144
	ds_read_b128 v[242:245], v169 offset:7168
	s_setprio 1
	s_waitcnt lgkmcnt(7)
	v_mfma_f32_16x16x32_bf16 v[148:151], v[196:199], v[212:215], v[148:151]
	v_mfma_f32_16x16x32_bf16 v[144:147], v[200:203], v[212:215], v[144:147]
	v_mfma_f32_16x16x32_bf16 v[116:119], v[204:207], v[212:215], v[116:119]
	v_mfma_f32_16x16x32_bf16 v[112:115], v[208:211], v[212:215], v[112:115]
	s_waitcnt vmcnt(11)
	ds_write_b128 v152, v[120:123] offset:16384
	s_waitcnt lgkmcnt(7)
	v_mfma_f32_16x16x32_bf16 v[108:111], v[196:199], v[216:219], v[108:111]
	v_mfma_f32_16x16x32_bf16 v[104:107], v[200:203], v[216:219], v[104:107]
	v_mfma_f32_16x16x32_bf16 v[100:103], v[204:207], v[216:219], v[100:103]
	v_mfma_f32_16x16x32_bf16 v[96:99], v[208:211], v[216:219], v[96:99]
	s_waitcnt vmcnt(9)
	ds_write_b128 v152, v[124:127] offset:20480
	s_waitcnt lgkmcnt(7)
	v_mfma_f32_16x16x32_bf16 v[92:95], v[196:199], v[222:225], v[92:95]
	v_mfma_f32_16x16x32_bf16 v[88:91], v[200:203], v[222:225], v[88:91]
	v_mfma_f32_16x16x32_bf16 v[84:87], v[204:207], v[222:225], v[84:87]
	v_mfma_f32_16x16x32_bf16 v[80:83], v[208:211], v[222:225], v[80:83]
	s_waitcnt vmcnt(8)
	ds_write_b128 v152, v[128:131] offset:24576
	s_waitcnt lgkmcnt(7)
	v_mfma_f32_16x16x32_bf16 v[76:79], v[196:199], v[226:229], v[76:79]
	v_mfma_f32_16x16x32_bf16 v[72:75], v[200:203], v[226:229], v[72:75]
	v_mfma_f32_16x16x32_bf16 v[68:71], v[204:207], v[226:229], v[68:71]
	v_mfma_f32_16x16x32_bf16 v[64:67], v[208:211], v[226:229], v[64:67]
	s_waitcnt vmcnt(7)
	ds_write_b128 v152, v[136:139] offset:28672
	s_waitcnt lgkmcnt(7)
	v_mfma_f32_16x16x32_bf16 v[60:63], v[196:199], v[230:233], v[60:63]
	v_mfma_f32_16x16x32_bf16 v[56:59], v[200:203], v[230:233], v[56:59]
	v_mfma_f32_16x16x32_bf16 v[52:55], v[204:207], v[230:233], v[52:55]
	v_mfma_f32_16x16x32_bf16 v[48:51], v[208:211], v[230:233], v[48:51]
	s_waitcnt vmcnt(6)
	ds_write_b128 v152, v[140:143] offset:45056
	s_waitcnt lgkmcnt(7)
	v_mfma_f32_16x16x32_bf16 v[44:47], v[196:199], v[234:237], v[44:47]
	v_mfma_f32_16x16x32_bf16 v[40:43], v[200:203], v[234:237], v[40:43]
	v_mfma_f32_16x16x32_bf16 v[36:39], v[204:207], v[234:237], v[36:39]
	v_mfma_f32_16x16x32_bf16 v[32:35], v[208:211], v[234:237], v[32:35]
	ds_write_b128 v152, v[132:135] offset:40960
	s_waitcnt lgkmcnt(7)
	v_mfma_f32_16x16x32_bf16 v[28:31], v[196:199], v[238:241], v[28:31]
	v_mfma_f32_16x16x32_bf16 v[24:27], v[200:203], v[238:241], v[24:27]
	v_mfma_f32_16x16x32_bf16 v[20:23], v[204:207], v[238:241], v[20:23]
	v_mfma_f32_16x16x32_bf16 v[16:19], v[208:211], v[238:241], v[16:19]
	s_waitcnt lgkmcnt(6)
	v_mfma_f32_16x16x32_bf16 v[12:15], v[196:199], v[242:245], v[12:15]
	v_mfma_f32_16x16x32_bf16 v[8:11], v[200:203], v[242:245], v[8:11]
	v_mfma_f32_16x16x32_bf16 v[4:7], v[204:207], v[242:245], v[4:7]
	v_mfma_f32_16x16x32_bf16 v[0:3], v[208:211], v[242:245], v[0:3]
	s_setprio 0
	s_min_u32 s12, s25, 0x380
	s_lshl_b32 s12, s12, 1
	s_mov_b32 s29, s13
	s_add_i32 s28, s12, 0xc0
	v_lshl_add_u64 v[120:121], v[154:155], 0, s[12:13]
	v_lshl_add_u64 v[124:125], v[156:157], 0, s[12:13]
	v_lshl_add_u64 v[126:127], v[158:159], 0, s[28:29]
	v_lshl_add_u64 v[128:129], v[160:161], 0, s[28:29]
	v_lshl_add_u64 v[136:137], v[162:163], 0, s[28:29]
	v_lshl_add_u64 v[140:141], v[164:165], 0, s[28:29]
	s_waitcnt lgkmcnt(0)
	s_barrier
	global_load_dwordx4 v[120:123], v[120:121], off offset:192
	ds_read_b128 v[196:199], v168 offset:40960
	global_load_dwordx4 v[132:135], v[124:125], off offset:192
	ds_read_b128 v[200:203], v168 offset:41984
	global_load_dwordx4 v[124:127], v[126:127], off
	ds_read_b128 v[204:207], v168 offset:43008
	global_load_dwordx4 v[128:131], v[128:129], off
	ds_read_b128 v[208:211], v168 offset:44032
	global_load_dwordx4 v[136:139], v[136:137], off
	ds_read_b128 v[212:215], v170
	global_load_dwordx4 v[140:143], v[140:141], off
	ds_read_b128 v[216:219], v170 offset:1024
	ds_read_b128 v[222:225], v170 offset:2048
	ds_read_b128 v[226:229], v170 offset:3072
	ds_read_b128 v[230:233], v170 offset:4096
	ds_read_b128 v[234:237], v170 offset:5120
	ds_read_b128 v[238:241], v170 offset:6144
	ds_read_b128 v[242:245], v170 offset:7168
	s_setprio 1
	s_waitcnt lgkmcnt(7)
	v_mfma_f32_16x16x32_bf16 v[148:151], v[196:199], v[212:215], v[148:151]
	v_mfma_f32_16x16x32_bf16 v[144:147], v[200:203], v[212:215], v[144:147]
	v_mfma_f32_16x16x32_bf16 v[116:119], v[204:207], v[212:215], v[116:119]
	v_mfma_f32_16x16x32_bf16 v[112:115], v[208:211], v[212:215], v[112:115]
	s_waitcnt vmcnt(11)
	ds_write_b128 v152, v[172:175]
	s_waitcnt lgkmcnt(7)
	v_mfma_f32_16x16x32_bf16 v[108:111], v[196:199], v[216:219], v[108:111]
	v_mfma_f32_16x16x32_bf16 v[104:107], v[200:203], v[216:219], v[104:107]
	v_mfma_f32_16x16x32_bf16 v[100:103], v[204:207], v[216:219], v[100:103]
	v_mfma_f32_16x16x32_bf16 v[96:99], v[208:211], v[216:219], v[96:99]
	s_waitcnt vmcnt(10)
	ds_write_b128 v152, v[176:179] offset:4096
	s_waitcnt lgkmcnt(7)
	v_mfma_f32_16x16x32_bf16 v[92:95], v[196:199], v[222:225], v[92:95]
	v_mfma_f32_16x16x32_bf16 v[88:91], v[200:203], v[222:225], v[88:91]
	v_mfma_f32_16x16x32_bf16 v[84:87], v[204:207], v[222:225], v[84:87]
	v_mfma_f32_16x16x32_bf16 v[80:83], v[208:211], v[222:225], v[80:83]
	s_waitcnt vmcnt(9)
	ds_write_b128 v152, v[180:183] offset:8192
	s_waitcnt lgkmcnt(7)
	v_mfma_f32_16x16x32_bf16 v[76:79], v[196:199], v[226:229], v[76:79]
	v_mfma_f32_16x16x32_bf16 v[72:75], v[200:203], v[226:229], v[72:75]
	v_mfma_f32_16x16x32_bf16 v[68:71], v[204:207], v[226:229], v[68:71]
	v_mfma_f32_16x16x32_bf16 v[64:67], v[208:211], v[226:229], v[64:67]
	s_waitcnt vmcnt(8)
	ds_write_b128 v152, v[184:187] offset:12288
	s_waitcnt lgkmcnt(7)
	v_mfma_f32_16x16x32_bf16 v[60:63], v[196:199], v[230:233], v[60:63]
	v_mfma_f32_16x16x32_bf16 v[56:59], v[200:203], v[230:233], v[56:59]
	v_mfma_f32_16x16x32_bf16 v[52:55], v[204:207], v[230:233], v[52:55]
	v_mfma_f32_16x16x32_bf16 v[48:51], v[208:211], v[230:233], v[48:51]
	s_waitcnt vmcnt(7)
	ds_write_b128 v152, v[188:191] offset:32768
	s_waitcnt lgkmcnt(7)
	v_mfma_f32_16x16x32_bf16 v[44:47], v[196:199], v[234:237], v[44:47]
	v_mfma_f32_16x16x32_bf16 v[40:43], v[200:203], v[234:237], v[40:43]
	v_mfma_f32_16x16x32_bf16 v[36:39], v[204:207], v[234:237], v[36:39]
	v_mfma_f32_16x16x32_bf16 v[32:35], v[208:211], v[234:237], v[32:35]
	s_waitcnt vmcnt(6)
	ds_write_b128 v152, v[192:195] offset:36864
	s_waitcnt lgkmcnt(7)
	v_mfma_f32_16x16x32_bf16 v[28:31], v[196:199], v[238:241], v[28:31]
	v_mfma_f32_16x16x32_bf16 v[24:27], v[200:203], v[238:241], v[24:27]
	v_mfma_f32_16x16x32_bf16 v[20:23], v[204:207], v[238:241], v[20:23]
	v_mfma_f32_16x16x32_bf16 v[16:19], v[208:211], v[238:241], v[16:19]
	s_waitcnt lgkmcnt(6)
	v_mfma_f32_16x16x32_bf16 v[12:15], v[196:199], v[242:245], v[12:15]
	v_mfma_f32_16x16x32_bf16 v[8:11], v[200:203], v[242:245], v[8:11]
	v_mfma_f32_16x16x32_bf16 v[4:7], v[204:207], v[242:245], v[4:7]
	v_mfma_f32_16x16x32_bf16 v[0:3], v[208:211], v[242:245], v[0:3]
	s_setprio 0
	s_add_i32 s21, s21, 2
	s_cmp_lt_u32 s21, 30
	s_mov_b32 s25, s26
	s_waitcnt lgkmcnt(0)
	s_barrier
	s_cbranch_scc1 .LBB0_1737
	s_waitcnt vmcnt(5)
	v_mov_b32_e32 v120, v220
	s_nop 0
	v_and_b32_e32 v122, 0xffffff80, v120
	v_add_u32_e32 v122, s20, v122
	v_and_b32_e32 v121, 64, v120
	v_and_or_b32 v122, v120, 15, v122
	v_lshrrev_b32_e32 v120, 2, v120
	v_and_b32_e32 v120, 12, v120
	v_or3_b32 v120, v121, v120, s24
	v_ashrrev_i32_e32 v121, 31, v120
	v_ashrrev_i32_e32 v123, 31, v122
	v_lshl_add_u64 v[120:121], v[120:121], 1, s[10:11]
	s_waitcnt vmcnt(3)
	v_lshl_add_u64 v[124:125], v[122:123], 2, s[0:1]
	v_lshlrev_b64 v[126:127], 12, v[122:123]
	v_lshl_add_u64 v[162:163], v[120:121], 0, v[126:127]
	global_load_dword v152, v[124:125], off
	global_load_dwordx2 v[168:169], v[162:163], off
	global_load_dwordx2 v[170:171], v[162:163], off offset:32
	global_load_dwordx2 v[172:173], v[162:163], off offset:64
	v_or_b32_e32 v124, 16, v122
	v_ashrrev_i32_e32 v125, 31, v124
	v_lshl_add_u64 v[126:127], v[124:125], 2, s[0:1]
	v_lshlrev_b64 v[124:125], 12, v[124:125]
	s_waitcnt vmcnt(4)
	v_lshl_add_u64 v[142:143], v[120:121], 0, v[124:125]
	v_or_b32_e32 v124, 32, v122
	v_ashrrev_i32_e32 v125, 31, v124
	global_load_dwordx2 v[174:175], v[162:163], off offset:96
	global_load_dword v176, v[126:127], off
	global_load_dwordx2 v[164:165], v[142:143], off
	global_load_dwordx2 v[160:161], v[142:143], off offset:32
	v_lshl_add_u64 v[126:127], v[124:125], 2, s[0:1]
	v_lshlrev_b64 v[124:125], 12, v[124:125]
	v_lshl_add_u64 v[132:133], v[120:121], 0, v[124:125]
	v_or_b32_e32 v124, 48, v122
	v_ashrrev_i32_e32 v125, 31, v124
	global_load_dwordx2 v[158:159], v[142:143], off offset:64
	global_load_dwordx2 v[156:157], v[142:143], off offset:96
	global_load_dword v177, v[126:127], off
	global_load_dwordx2 v[154:155], v[132:133], off
	v_lshl_add_u64 v[126:127], v[124:125], 2, s[0:1]
	v_lshlrev_b64 v[124:125], 12, v[124:125]
	v_lshl_add_u64 v[124:125], v[120:121], 0, v[124:125]
	global_load_dwordx2 v[140:141], v[132:133], off offset:32
	global_load_dwordx2 v[138:139], v[132:133], off offset:64
	global_load_dwordx2 v[136:137], v[132:133], off offset:96
	global_load_dword v123, v[126:127], off
	global_load_dwordx2 v[134:135], v[124:125], off
	global_load_dwordx2 v[130:131], v[124:125], off offset:32
	global_load_dwordx2 v[128:129], v[124:125], off offset:64
	s_nop 0
	global_load_dwordx2 v[126:127], v[124:125], off offset:96
	s_waitcnt vmcnt(19)
	v_fmamk_f32 v152, v152, 0x3a800000, v167
	v_mul_f32_e32 v178, 0x4b800000, v152
	v_cmp_gt_f32_e32 vcc, s22, v152
	s_nop 1
	v_cndmask_b32_e32 v152, v152, v178, vcc
	v_rsq_f32_e32 v152, v152
	s_waitcnt vmcnt(18)
	v_lshlrev_b32_e32 v178, 16, v168
	v_and_b32_e32 v168, 0xffff0000, v168
	v_mul_f32_e32 v179, 0x45800000, v152
	v_cndmask_b32_e32 v152, v152, v179, vcc
	v_mul_f32_e32 v148, v148, v152
	v_mul_f32_e32 v180, 0xbfb8aa3b, v148
	v_exp_f32_e32 v180, v180
	v_mul_f32_e32 v149, v149, v152
	v_mul_f32_e32 v181, 0xbfb8aa3b, v149
	v_exp_f32_e32 v181, v181
	v_add_f32_e32 v180, 1.0, v180
	v_rcp_f32_e32 v180, v180
	v_mul_f32_e32 v150, v150, v152
	v_mul_f32_e32 v151, v151, v152
	v_lshlrev_b32_e32 v179, 16, v169
	v_mul_f32_e32 v148, v148, v180
	v_mul_f32_e32 v148, v148, v178
	v_add_f32_e32 v178, 1.0, v181
	v_mul_f32_e32 v180, 0xbfb8aa3b, v150
	v_mul_f32_e32 v181, 0xbfb8aa3b, v151
	v_rcp_f32_e32 v178, v178
	v_exp_f32_e32 v180, v180
	v_exp_f32_e32 v181, v181
	v_and_b32_e32 v169, 0xffff0000, v169
	v_mul_f32_e32 v149, v149, v178
	v_add_f32_e32 v178, 1.0, v180
	v_add_f32_e32 v180, 1.0, v181
	v_rcp_f32_e32 v180, v180
	v_rcp_f32_e32 v178, v178
	v_mul_f32_e32 v149, v149, v168
	v_mul_f32_e32 v144, v144, v152
	v_mul_f32_e32 v151, v151, v180
	v_mul_f32_e32 v150, v150, v178
	v_mul_f32_e32 v151, v151, v169
	v_mul_f32_e32 v150, v150, v179
	v_cvt_pk_bf16_f32 v148, v148, v149
	v_cvt_pk_bf16_f32 v149, v150, v151
	v_mul_f32_e32 v151, 0xbfb8aa3b, v144
	v_exp_f32_e32 v151, v151
	v_mul_f32_e32 v145, v145, v152
	v_mul_f32_e32 v169, 0xbfb8aa3b, v145
	v_exp_f32_e32 v169, v169
	v_add_f32_e32 v151, 1.0, v151
	v_rcp_f32_e32 v151, v151
	global_store_dwordx2 v[162:163], v[148:149], off
	s_waitcnt vmcnt(18)
	v_lshlrev_b32_e32 v148, 16, v170
	v_mul_f32_e32 v146, v146, v152
	v_mul_f32_e32 v147, v147, v152
	v_mul_f32_e32 v144, v144, v151
	v_mul_f32_e32 v144, v144, v148
	v_add_f32_e32 v148, 1.0, v169
	v_mul_f32_e32 v151, 0xbfb8aa3b, v146
	v_mul_f32_e32 v169, 0xbfb8aa3b, v147
	v_rcp_f32_e32 v148, v148
	v_exp_f32_e32 v151, v151
	v_exp_f32_e32 v169, v169
	v_and_b32_e32 v149, 0xffff0000, v170
	v_mul_f32_e32 v145, v145, v148
	v_add_f32_e32 v148, 1.0, v151
	v_add_f32_e32 v151, 1.0, v169
	v_rcp_f32_e32 v151, v151
	v_rcp_f32_e32 v148, v148
	v_and_b32_e32 v168, 0xffff0000, v171
	v_lshlrev_b32_e32 v150, 16, v171
	v_mul_f32_e32 v147, v147, v151
	v_mul_f32_e32 v145, v145, v149
	v_mul_f32_e32 v146, v146, v148
	v_mul_f32_e32 v147, v147, v168
	v_mul_f32_e32 v116, v116, v152
	v_mul_f32_e32 v146, v146, v150
	v_cvt_pk_bf16_f32 v144, v144, v145
	v_cvt_pk_bf16_f32 v145, v146, v147
	v_mul_f32_e32 v147, 0xbfb8aa3b, v116
	v_exp_f32_e32 v147, v147
	v_mul_f32_e32 v117, v117, v152
	v_mul_f32_e32 v149, 0xbfb8aa3b, v117
	v_exp_f32_e32 v149, v149
	v_add_f32_e32 v147, 1.0, v147
	v_rcp_f32_e32 v147, v147
	global_store_dwordx2 v[162:163], v[144:145], off offset:32
	s_waitcnt vmcnt(18)
	v_lshlrev_b32_e32 v144, 16, v172
	v_mul_f32_e32 v118, v118, v152
	v_mul_f32_e32 v119, v119, v152
	v_mul_f32_e32 v116, v116, v147
	v_mul_f32_e32 v116, v116, v144
	v_add_f32_e32 v144, 1.0, v149
	v_mul_f32_e32 v147, 0xbfb8aa3b, v118
	v_mul_f32_e32 v149, 0xbfb8aa3b, v119
	v_rcp_f32_e32 v144, v144
	v_exp_f32_e32 v147, v147
	v_exp_f32_e32 v149, v149
	v_and_b32_e32 v145, 0xffff0000, v172
	v_mul_f32_e32 v117, v117, v144
	v_add_f32_e32 v144, 1.0, v147
	v_add_f32_e32 v147, 1.0, v149
	v_rcp_f32_e32 v147, v147
	v_rcp_f32_e32 v144, v144
	v_and_b32_e32 v148, 0xffff0000, v173
	v_lshlrev_b32_e32 v146, 16, v173
	v_mul_f32_e32 v119, v119, v147
	v_mul_f32_e32 v117, v117, v145
	v_mul_f32_e32 v118, v118, v144
	v_mul_f32_e32 v119, v119, v148
	v_mul_f32_e32 v112, v112, v152
	v_mul_f32_e32 v118, v118, v146
	v_cvt_pk_bf16_f32 v116, v116, v117
	v_cvt_pk_bf16_f32 v117, v118, v119
	v_mul_f32_e32 v119, 0xbfb8aa3b, v112
	v_exp_f32_e32 v119, v119
	v_mul_f32_e32 v113, v113, v152
	v_mul_f32_e32 v145, 0xbfb8aa3b, v113
	v_exp_f32_e32 v145, v145
	v_add_f32_e32 v119, 1.0, v119
	v_rcp_f32_e32 v119, v119
	global_store_dwordx2 v[162:163], v[116:117], off offset:64
	s_waitcnt vmcnt(18)
	v_lshlrev_b32_e32 v116, 16, v174
	v_mul_f32_e32 v114, v114, v152
	v_mul_f32_e32 v112, v112, v119
	v_mul_f32_e32 v112, v112, v116
	v_add_f32_e32 v116, 1.0, v145
	v_mul_f32_e32 v119, 0xbfb8aa3b, v114
	v_rcp_f32_e32 v116, v116
	v_exp_f32_e32 v119, v119
	v_mul_f32_e32 v115, v115, v152
	v_mul_f32_e32 v145, 0xbfb8aa3b, v115
	v_mul_f32_e32 v113, v113, v116
	v_add_f32_e32 v116, 1.0, v119
	v_rcp_f32_e32 v116, v116
	v_exp_f32_e32 v145, v145
	v_and_b32_e32 v117, 0xffff0000, v174
	v_mul_f32_e32 v113, v113, v117
	v_mul_f32_e32 v114, v114, v116
	s_waitcnt vmcnt(17)
	v_fmamk_f32 v116, v176, 0x3a800000, v167
	v_add_f32_e32 v119, 1.0, v145
	v_mul_f32_e32 v117, 0x4b800000, v116
	v_cmp_gt_f32_e32 vcc, s22, v116
	v_rcp_f32_e32 v119, v119
	v_lshlrev_b32_e32 v118, 16, v175
	v_cndmask_b32_e32 v116, v116, v117, vcc
	v_rsq_f32_e32 v116, v116
	v_and_b32_e32 v144, 0xffff0000, v175
	v_mul_f32_e32 v115, v115, v119
	v_cvt_pk_bf16_f32 v112, v112, v113
	v_mul_f32_e32 v114, v114, v118
	v_mul_f32_e32 v115, v115, v144
	v_cvt_pk_bf16_f32 v113, v114, v115
	global_store_dwordx2 v[162:163], v[112:113], off offset:96
	v_mul_f32_e32 v112, 0x45800000, v116
	v_cndmask_b32_e32 v112, v116, v112, vcc
	v_mul_f32_e32 v108, v108, v112
	v_mul_f32_e32 v116, 0xbfb8aa3b, v108
	v_exp_f32_e32 v116, v116
	v_mul_f32_e32 v109, v109, v112
	v_mul_f32_e32 v118, 0xbfb8aa3b, v109
	v_exp_f32_e32 v118, v118
	v_add_f32_e32 v116, 1.0, v116
	v_rcp_f32_e32 v116, v116
	s_waitcnt vmcnt(17)
	v_lshlrev_b32_e32 v113, 16, v164
	v_mul_f32_e32 v110, v110, v112
	v_mul_f32_e32 v111, v111, v112
	v_mul_f32_e32 v108, v108, v116
	v_mul_f32_e32 v108, v108, v113
	v_add_f32_e32 v113, 1.0, v118
	v_mul_f32_e32 v116, 0xbfb8aa3b, v110
	v_mul_f32_e32 v118, 0xbfb8aa3b, v111
	v_rcp_f32_e32 v113, v113
	v_exp_f32_e32 v116, v116
	v_exp_f32_e32 v118, v118
	v_and_b32_e32 v114, 0xffff0000, v164
	v_mul_f32_e32 v109, v109, v113
	v_add_f32_e32 v113, 1.0, v116
	v_add_f32_e32 v116, 1.0, v118
	v_rcp_f32_e32 v116, v116
	v_rcp_f32_e32 v113, v113
	v_and_b32_e32 v117, 0xffff0000, v165
	v_lshlrev_b32_e32 v115, 16, v165
	v_mul_f32_e32 v111, v111, v116
	v_mul_f32_e32 v109, v109, v114
	v_mul_f32_e32 v110, v110, v113
	v_mul_f32_e32 v111, v111, v117
	v_mul_f32_e32 v104, v104, v112
	v_mul_f32_e32 v110, v110, v115
	v_cvt_pk_bf16_f32 v108, v108, v109
	v_cvt_pk_bf16_f32 v109, v110, v111
	v_mul_f32_e32 v111, 0xbfb8aa3b, v104
	v_exp_f32_e32 v111, v111
	v_mul_f32_e32 v105, v105, v112
	v_mul_f32_e32 v114, 0xbfb8aa3b, v105
	v_exp_f32_e32 v114, v114
	v_add_f32_e32 v111, 1.0, v111
	v_rcp_f32_e32 v111, v111
	global_store_dwordx2 v[142:143], v[108:109], off
	s_waitcnt vmcnt(17)
	v_lshlrev_b32_e32 v108, 16, v160
	v_mul_f32_e32 v106, v106, v112
	v_mul_f32_e32 v107, v107, v112
	v_mul_f32_e32 v104, v104, v111
	v_mul_f32_e32 v104, v104, v108
	v_add_f32_e32 v108, 1.0, v114
	v_mul_f32_e32 v111, 0xbfb8aa3b, v106
	v_mul_f32_e32 v114, 0xbfb8aa3b, v107
	v_rcp_f32_e32 v108, v108
	v_exp_f32_e32 v111, v111
	v_exp_f32_e32 v114, v114
	v_and_b32_e32 v109, 0xffff0000, v160
	v_mul_f32_e32 v105, v105, v108
	v_add_f32_e32 v108, 1.0, v111
	v_add_f32_e32 v111, 1.0, v114
	v_rcp_f32_e32 v111, v111
	v_rcp_f32_e32 v108, v108
	v_and_b32_e32 v113, 0xffff0000, v161
	v_lshlrev_b32_e32 v110, 16, v161
	v_mul_f32_e32 v107, v107, v111
	v_mul_f32_e32 v105, v105, v109
	v_mul_f32_e32 v106, v106, v108
	v_mul_f32_e32 v107, v107, v113
	v_mul_f32_e32 v100, v100, v112
	v_mul_f32_e32 v106, v106, v110
	v_cvt_pk_bf16_f32 v104, v104, v105
	v_cvt_pk_bf16_f32 v105, v106, v107
	v_mul_f32_e32 v107, 0xbfb8aa3b, v100
	v_exp_f32_e32 v107, v107
	v_mul_f32_e32 v101, v101, v112
	v_mul_f32_e32 v109, 0xbfb8aa3b, v101
	v_exp_f32_e32 v109, v109
	v_add_f32_e32 v107, 1.0, v107
	v_rcp_f32_e32 v107, v107
	global_store_dwordx2 v[142:143], v[104:105], off offset:32
	s_waitcnt vmcnt(17)
	v_lshlrev_b32_e32 v104, 16, v158
	v_mul_f32_e32 v102, v102, v112
	v_mul_f32_e32 v103, v103, v112
	v_mul_f32_e32 v100, v100, v107
	v_mul_f32_e32 v100, v100, v104
	v_add_f32_e32 v104, 1.0, v109
	v_mul_f32_e32 v107, 0xbfb8aa3b, v102
	v_mul_f32_e32 v109, 0xbfb8aa3b, v103
	v_rcp_f32_e32 v104, v104
	v_exp_f32_e32 v107, v107
	v_exp_f32_e32 v109, v109
	v_and_b32_e32 v105, 0xffff0000, v158
	v_mul_f32_e32 v101, v101, v104
	v_add_f32_e32 v104, 1.0, v107
	v_add_f32_e32 v107, 1.0, v109
	v_rcp_f32_e32 v107, v107
	v_rcp_f32_e32 v104, v104
	v_and_b32_e32 v108, 0xffff0000, v159
	v_lshlrev_b32_e32 v106, 16, v159
	v_mul_f32_e32 v103, v103, v107
	v_mul_f32_e32 v101, v101, v105
	v_mul_f32_e32 v102, v102, v104
	v_mul_f32_e32 v103, v103, v108
	v_mul_f32_e32 v96, v96, v112
	v_mul_f32_e32 v102, v102, v106
	v_cvt_pk_bf16_f32 v100, v100, v101
	v_cvt_pk_bf16_f32 v101, v102, v103
	v_mul_f32_e32 v103, 0xbfb8aa3b, v96
	v_exp_f32_e32 v103, v103
	v_mul_f32_e32 v97, v97, v112
	v_mul_f32_e32 v105, 0xbfb8aa3b, v97
	v_exp_f32_e32 v105, v105
	v_add_f32_e32 v103, 1.0, v103
	v_rcp_f32_e32 v103, v103
	global_store_dwordx2 v[142:143], v[100:101], off offset:64
	s_waitcnt vmcnt(17)
	v_lshlrev_b32_e32 v100, 16, v156
	v_mul_f32_e32 v98, v98, v112
	v_mul_f32_e32 v96, v96, v103
	v_mul_f32_e32 v96, v96, v100
	v_add_f32_e32 v100, 1.0, v105
	v_mul_f32_e32 v103, 0xbfb8aa3b, v98
	v_rcp_f32_e32 v100, v100
	v_exp_f32_e32 v103, v103
	v_mul_f32_e32 v99, v99, v112
	v_mul_f32_e32 v105, 0xbfb8aa3b, v99
	v_mul_f32_e32 v97, v97, v100
	v_add_f32_e32 v100, 1.0, v103
	v_rcp_f32_e32 v100, v100
	v_exp_f32_e32 v105, v105
	v_and_b32_e32 v101, 0xffff0000, v156
	v_mul_f32_e32 v97, v97, v101
	v_mul_f32_e32 v98, v98, v100
	s_waitcnt vmcnt(16)
	v_fmamk_f32 v100, v177, 0x3a800000, v167
	v_add_f32_e32 v103, 1.0, v105
	v_mul_f32_e32 v101, 0x4b800000, v100
	v_cmp_gt_f32_e32 vcc, s22, v100
	v_rcp_f32_e32 v103, v103
	v_lshlrev_b32_e32 v102, 16, v157
	v_cndmask_b32_e32 v100, v100, v101, vcc
	v_rsq_f32_e32 v100, v100
	v_and_b32_e32 v104, 0xffff0000, v157
	v_mul_f32_e32 v99, v99, v103
	v_cvt_pk_bf16_f32 v96, v96, v97
	v_mul_f32_e32 v98, v98, v102
	v_mul_f32_e32 v99, v99, v104
	v_cvt_pk_bf16_f32 v97, v98, v99
	global_store_dwordx2 v[142:143], v[96:97], off offset:96
	v_mul_f32_e32 v96, 0x45800000, v100
	v_cndmask_b32_e32 v96, v100, v96, vcc
	v_mul_f32_e32 v92, v92, v96
	v_mul_f32_e32 v100, 0xbfb8aa3b, v92
	v_exp_f32_e32 v100, v100
	v_mul_f32_e32 v93, v93, v96
	v_mul_f32_e32 v102, 0xbfb8aa3b, v93
	v_exp_f32_e32 v102, v102
	v_add_f32_e32 v100, 1.0, v100
	v_rcp_f32_e32 v100, v100
	s_waitcnt vmcnt(16)
	v_lshlrev_b32_e32 v97, 16, v154
	v_mul_f32_e32 v94, v94, v96
	v_mul_f32_e32 v95, v95, v96
	v_mul_f32_e32 v92, v92, v100
	v_mul_f32_e32 v92, v92, v97
	v_add_f32_e32 v97, 1.0, v102
	v_mul_f32_e32 v100, 0xbfb8aa3b, v94
	v_mul_f32_e32 v102, 0xbfb8aa3b, v95
	v_rcp_f32_e32 v97, v97
	v_exp_f32_e32 v100, v100
	v_exp_f32_e32 v102, v102
	v_and_b32_e32 v98, 0xffff0000, v154
	v_mul_f32_e32 v93, v93, v97
	v_add_f32_e32 v97, 1.0, v100
	v_add_f32_e32 v100, 1.0, v102
	v_rcp_f32_e32 v100, v100
	v_rcp_f32_e32 v97, v97
	v_and_b32_e32 v101, 0xffff0000, v155
	v_lshlrev_b32_e32 v99, 16, v155
	v_mul_f32_e32 v95, v95, v100
	v_mul_f32_e32 v93, v93, v98
	v_mul_f32_e32 v94, v94, v97
	v_mul_f32_e32 v95, v95, v101
	v_mul_f32_e32 v88, v88, v96
	v_mul_f32_e32 v94, v94, v99
	v_cvt_pk_bf16_f32 v92, v92, v93
	v_cvt_pk_bf16_f32 v93, v94, v95
	v_mul_f32_e32 v95, 0xbfb8aa3b, v88
	v_exp_f32_e32 v95, v95
	v_mul_f32_e32 v89, v89, v96
	v_mul_f32_e32 v98, 0xbfb8aa3b, v89
	v_exp_f32_e32 v98, v98
	v_add_f32_e32 v95, 1.0, v95
	v_rcp_f32_e32 v95, v95
	global_store_dwordx2 v[132:133], v[92:93], off
	s_waitcnt vmcnt(16)
	v_lshlrev_b32_e32 v92, 16, v140
	v_mul_f32_e32 v90, v90, v96
	v_mul_f32_e32 v91, v91, v96
	v_mul_f32_e32 v88, v88, v95
	v_mul_f32_e32 v88, v88, v92
	v_add_f32_e32 v92, 1.0, v98
	v_mul_f32_e32 v95, 0xbfb8aa3b, v90
	v_mul_f32_e32 v98, 0xbfb8aa3b, v91
	v_rcp_f32_e32 v92, v92
	v_exp_f32_e32 v95, v95
	v_exp_f32_e32 v98, v98
	v_and_b32_e32 v93, 0xffff0000, v140
	v_mul_f32_e32 v89, v89, v92
	v_add_f32_e32 v92, 1.0, v95
	v_add_f32_e32 v95, 1.0, v98
	v_rcp_f32_e32 v95, v95
	v_rcp_f32_e32 v92, v92
	v_and_b32_e32 v97, 0xffff0000, v141
	v_lshlrev_b32_e32 v94, 16, v141
	v_mul_f32_e32 v91, v91, v95
	v_mul_f32_e32 v89, v89, v93
	v_mul_f32_e32 v90, v90, v92
	v_mul_f32_e32 v91, v91, v97
	v_mul_f32_e32 v84, v84, v96
	v_mul_f32_e32 v90, v90, v94
	v_cvt_pk_bf16_f32 v88, v88, v89
	v_cvt_pk_bf16_f32 v89, v90, v91
	v_mul_f32_e32 v91, 0xbfb8aa3b, v84
	v_exp_f32_e32 v91, v91
	v_mul_f32_e32 v85, v85, v96
	v_mul_f32_e32 v93, 0xbfb8aa3b, v85
	v_exp_f32_e32 v93, v93
	v_add_f32_e32 v91, 1.0, v91
	v_rcp_f32_e32 v91, v91
	global_store_dwordx2 v[132:133], v[88:89], off offset:32
	s_waitcnt vmcnt(16)
	v_lshlrev_b32_e32 v88, 16, v138
	v_mul_f32_e32 v86, v86, v96
	v_mul_f32_e32 v87, v87, v96
	v_mul_f32_e32 v84, v84, v91
	v_mul_f32_e32 v84, v84, v88
	v_add_f32_e32 v88, 1.0, v93
	v_mul_f32_e32 v91, 0xbfb8aa3b, v86
	v_mul_f32_e32 v93, 0xbfb8aa3b, v87
	v_rcp_f32_e32 v88, v88
	v_exp_f32_e32 v91, v91
	v_exp_f32_e32 v93, v93
	v_and_b32_e32 v89, 0xffff0000, v138
	v_mul_f32_e32 v85, v85, v88
	v_add_f32_e32 v88, 1.0, v91
	v_add_f32_e32 v91, 1.0, v93
	v_rcp_f32_e32 v91, v91
	v_rcp_f32_e32 v88, v88
	v_and_b32_e32 v92, 0xffff0000, v139
	v_lshlrev_b32_e32 v90, 16, v139
	v_mul_f32_e32 v87, v87, v91
	v_mul_f32_e32 v85, v85, v89
	v_mul_f32_e32 v86, v86, v88
	v_mul_f32_e32 v87, v87, v92
	v_mul_f32_e32 v80, v80, v96
	v_mul_f32_e32 v86, v86, v90
	v_cvt_pk_bf16_f32 v84, v84, v85
	v_cvt_pk_bf16_f32 v85, v86, v87
	v_mul_f32_e32 v87, 0xbfb8aa3b, v80
	v_exp_f32_e32 v87, v87
	v_mul_f32_e32 v81, v81, v96
	v_mul_f32_e32 v89, 0xbfb8aa3b, v81
	v_exp_f32_e32 v89, v89
	v_add_f32_e32 v87, 1.0, v87
	v_rcp_f32_e32 v87, v87
	global_store_dwordx2 v[132:133], v[84:85], off offset:64
	s_waitcnt vmcnt(16)
	v_lshlrev_b32_e32 v84, 16, v136
	v_mul_f32_e32 v82, v82, v96
	v_mul_f32_e32 v80, v80, v87
	v_mul_f32_e32 v80, v80, v84
	v_add_f32_e32 v84, 1.0, v89
	v_mul_f32_e32 v87, 0xbfb8aa3b, v82
	v_rcp_f32_e32 v84, v84
	v_exp_f32_e32 v87, v87
	v_mul_f32_e32 v83, v83, v96
	v_mul_f32_e32 v89, 0xbfb8aa3b, v83
	v_mul_f32_e32 v81, v81, v84
	v_add_f32_e32 v84, 1.0, v87
	v_rcp_f32_e32 v84, v84
	v_exp_f32_e32 v89, v89
	v_and_b32_e32 v85, 0xffff0000, v136
	v_mul_f32_e32 v81, v81, v85
	v_mul_f32_e32 v82, v82, v84
	s_waitcnt vmcnt(15)
	v_fmamk_f32 v84, v123, 0x3a800000, v167
	v_add_f32_e32 v87, 1.0, v89
	v_mul_f32_e32 v85, 0x4b800000, v84
	v_cmp_gt_f32_e32 vcc, s22, v84
	v_rcp_f32_e32 v87, v87
	v_lshlrev_b32_e32 v86, 16, v137
	v_cndmask_b32_e32 v84, v84, v85, vcc
	v_rsq_f32_e32 v84, v84
	v_and_b32_e32 v88, 0xffff0000, v137
	v_mul_f32_e32 v83, v83, v87
	v_cvt_pk_bf16_f32 v80, v80, v81
	v_mul_f32_e32 v82, v82, v86
	v_mul_f32_e32 v83, v83, v88
	v_cvt_pk_bf16_f32 v81, v82, v83
	global_store_dwordx2 v[132:133], v[80:81], off offset:96
	v_mul_f32_e32 v80, 0x45800000, v84
	v_cndmask_b32_e32 v80, v84, v80, vcc
	v_mul_f32_e32 v76, v76, v80
	v_mul_f32_e32 v84, 0xbfb8aa3b, v76
	v_exp_f32_e32 v84, v84
	v_mul_f32_e32 v77, v77, v80
	v_mul_f32_e32 v86, 0xbfb8aa3b, v77
	v_exp_f32_e32 v86, v86
	v_add_f32_e32 v84, 1.0, v84
	v_rcp_f32_e32 v84, v84
	s_waitcnt vmcnt(15)
	v_lshlrev_b32_e32 v81, 16, v134
	v_mul_f32_e32 v78, v78, v80
	v_mul_f32_e32 v79, v79, v80
	v_mul_f32_e32 v76, v76, v84
	v_mul_f32_e32 v76, v76, v81
	v_add_f32_e32 v81, 1.0, v86
	v_mul_f32_e32 v84, 0xbfb8aa3b, v78
	v_mul_f32_e32 v86, 0xbfb8aa3b, v79
	v_rcp_f32_e32 v81, v81
	v_exp_f32_e32 v84, v84
	v_exp_f32_e32 v86, v86
	v_and_b32_e32 v82, 0xffff0000, v134
	v_mul_f32_e32 v77, v77, v81
	v_add_f32_e32 v81, 1.0, v84
	v_add_f32_e32 v84, 1.0, v86
	v_rcp_f32_e32 v84, v84
	v_rcp_f32_e32 v81, v81
	v_and_b32_e32 v85, 0xffff0000, v135
	v_lshlrev_b32_e32 v83, 16, v135
	v_mul_f32_e32 v79, v79, v84
	v_mul_f32_e32 v77, v77, v82
	v_mul_f32_e32 v78, v78, v81
	v_mul_f32_e32 v79, v79, v85
	v_mul_f32_e32 v72, v72, v80
	v_mul_f32_e32 v78, v78, v83
	v_cvt_pk_bf16_f32 v76, v76, v77
	v_cvt_pk_bf16_f32 v77, v78, v79
	v_mul_f32_e32 v79, 0xbfb8aa3b, v72
	v_exp_f32_e32 v79, v79
	v_mul_f32_e32 v73, v73, v80
	v_mul_f32_e32 v82, 0xbfb8aa3b, v73
	v_exp_f32_e32 v82, v82
	v_add_f32_e32 v79, 1.0, v79
	v_rcp_f32_e32 v79, v79
	global_store_dwordx2 v[124:125], v[76:77], off
	s_waitcnt vmcnt(15)
	v_lshlrev_b32_e32 v76, 16, v130
	v_mul_f32_e32 v74, v74, v80
	v_mul_f32_e32 v75, v75, v80
	v_mul_f32_e32 v72, v72, v79
	v_mul_f32_e32 v72, v72, v76
	v_add_f32_e32 v76, 1.0, v82
	v_mul_f32_e32 v79, 0xbfb8aa3b, v74
	v_mul_f32_e32 v82, 0xbfb8aa3b, v75
	v_rcp_f32_e32 v76, v76
	v_exp_f32_e32 v79, v79
	v_exp_f32_e32 v82, v82
	v_and_b32_e32 v77, 0xffff0000, v130
	v_mul_f32_e32 v73, v73, v76
	v_add_f32_e32 v76, 1.0, v79
	v_add_f32_e32 v79, 1.0, v82
	v_rcp_f32_e32 v79, v79
	v_rcp_f32_e32 v76, v76
	v_and_b32_e32 v81, 0xffff0000, v131
	v_lshlrev_b32_e32 v78, 16, v131
	v_mul_f32_e32 v75, v75, v79
	v_mul_f32_e32 v73, v73, v77
	v_mul_f32_e32 v74, v74, v76
	v_mul_f32_e32 v75, v75, v81
	v_mul_f32_e32 v68, v68, v80
	v_mul_f32_e32 v74, v74, v78
	v_cvt_pk_bf16_f32 v72, v72, v73
	v_cvt_pk_bf16_f32 v73, v74, v75
	v_mul_f32_e32 v75, 0xbfb8aa3b, v68
	v_exp_f32_e32 v75, v75
	v_mul_f32_e32 v69, v69, v80
	v_mul_f32_e32 v77, 0xbfb8aa3b, v69
	v_exp_f32_e32 v77, v77
	v_add_f32_e32 v75, 1.0, v75
	v_rcp_f32_e32 v75, v75
	global_store_dwordx2 v[124:125], v[72:73], off offset:32
	s_waitcnt vmcnt(15)
	v_lshlrev_b32_e32 v72, 16, v128
	v_mul_f32_e32 v70, v70, v80
	v_mul_f32_e32 v71, v71, v80
	v_mul_f32_e32 v68, v68, v75
	v_mul_f32_e32 v68, v68, v72
	v_add_f32_e32 v72, 1.0, v77
	v_mul_f32_e32 v75, 0xbfb8aa3b, v70
	v_mul_f32_e32 v77, 0xbfb8aa3b, v71
	v_rcp_f32_e32 v72, v72
	v_exp_f32_e32 v75, v75
	v_exp_f32_e32 v77, v77
	v_and_b32_e32 v73, 0xffff0000, v128
	v_mul_f32_e32 v69, v69, v72
	v_add_f32_e32 v72, 1.0, v75
	v_add_f32_e32 v75, 1.0, v77
	v_rcp_f32_e32 v75, v75
	v_rcp_f32_e32 v72, v72
	v_and_b32_e32 v76, 0xffff0000, v129
	v_lshlrev_b32_e32 v74, 16, v129
	v_mul_f32_e32 v71, v71, v75
	v_mul_f32_e32 v69, v69, v73
	v_mul_f32_e32 v70, v70, v72
	v_mul_f32_e32 v71, v71, v76
	v_mul_f32_e32 v64, v64, v80
	v_mul_f32_e32 v70, v70, v74
	v_cvt_pk_bf16_f32 v68, v68, v69
	v_cvt_pk_bf16_f32 v69, v70, v71
	v_mul_f32_e32 v71, 0xbfb8aa3b, v64
	v_exp_f32_e32 v71, v71
	v_mul_f32_e32 v65, v65, v80
	v_mul_f32_e32 v73, 0xbfb8aa3b, v65
	v_exp_f32_e32 v73, v73
	v_add_f32_e32 v71, 1.0, v71
	v_rcp_f32_e32 v71, v71
	global_store_dwordx2 v[124:125], v[68:69], off offset:64
	s_waitcnt vmcnt(15)
	v_lshlrev_b32_e32 v68, 16, v126
	v_mul_f32_e32 v66, v66, v80
	v_mul_f32_e32 v67, v67, v80
	v_mul_f32_e32 v64, v64, v71
	v_mul_f32_e32 v64, v64, v68
	v_add_f32_e32 v68, 1.0, v73
	v_mul_f32_e32 v71, 0xbfb8aa3b, v66
	v_mul_f32_e32 v73, 0xbfb8aa3b, v67
	v_rcp_f32_e32 v68, v68
	v_exp_f32_e32 v71, v71
	v_exp_f32_e32 v73, v73
	v_and_b32_e32 v69, 0xffff0000, v126
	v_mul_f32_e32 v65, v65, v68
	v_add_f32_e32 v68, 1.0, v71
	v_add_f32_e32 v71, 1.0, v73
	v_rcp_f32_e32 v68, v68
	v_rcp_f32_e32 v71, v71
	v_lshlrev_b32_e32 v70, 16, v127
	v_and_b32_e32 v72, 0xffff0000, v127
	v_mul_f32_e32 v65, v65, v69
	v_mul_f32_e32 v66, v66, v68
	v_mul_f32_e32 v67, v67, v71
	v_mul_f32_e32 v66, v66, v70
	v_mul_f32_e32 v67, v67, v72
	v_cvt_pk_bf16_f32 v64, v64, v65
	v_cvt_pk_bf16_f32 v65, v66, v67
	global_store_dwordx2 v[124:125], v[64:65], off offset:96
	v_or_b32_e32 v64, 64, v122
	v_ashrrev_i32_e32 v65, 31, v64
	v_lshl_add_u64 v[66:67], v[64:65], 2, s[0:1]
	v_lshlrev_b64 v[64:65], 12, v[64:65]
	v_lshl_add_u64 v[92:93], v[120:121], 0, v[64:65]
	v_or_b32_e32 v64, 0x50, v122
	v_ashrrev_i32_e32 v65, 31, v64
	global_load_dword v97, v[66:67], off
	global_load_dwordx2 v[98:99], v[92:93], off
	global_load_dwordx2 v[100:101], v[92:93], off offset:32
	global_load_dwordx2 v[102:103], v[92:93], off offset:64
	v_lshl_add_u64 v[66:67], v[64:65], 2, s[0:1]
	v_lshlrev_b64 v[64:65], 12, v[64:65]
	v_lshl_add_u64 v[82:83], v[120:121], 0, v[64:65]
	v_or_b32_e32 v64, 0x60, v122
	v_ashrrev_i32_e32 v65, 31, v64
	global_load_dwordx2 v[104:105], v[92:93], off offset:96
	global_load_dword v106, v[66:67], off
	global_load_dwordx2 v[94:95], v[82:83], off
	global_load_dwordx2 v[90:91], v[82:83], off offset:32
	v_lshl_add_u64 v[66:67], v[64:65], 2, s[0:1]
	v_lshlrev_b64 v[64:65], 12, v[64:65]
	v_lshl_add_u64 v[72:73], v[120:121], 0, v[64:65]
	v_or_b32_e32 v64, 0x70, v122
	v_ashrrev_i32_e32 v65, 31, v64
	global_load_dwordx2 v[88:89], v[82:83], off offset:64
	global_load_dwordx2 v[86:87], v[82:83], off offset:96
	global_load_dword v107, v[66:67], off
	global_load_dwordx2 v[84:85], v[72:73], off
	v_lshl_add_u64 v[66:67], v[64:65], 2, s[0:1]
	v_lshlrev_b64 v[64:65], 12, v[64:65]
	v_lshl_add_u64 v[64:65], v[120:121], 0, v[64:65]
	global_load_dwordx2 v[80:81], v[72:73], off offset:32
	global_load_dwordx2 v[78:79], v[72:73], off offset:64
	global_load_dwordx2 v[76:77], v[72:73], off offset:96
	global_load_dword v96, v[66:67], off
	global_load_dwordx2 v[74:75], v[64:65], off
	global_load_dwordx2 v[70:71], v[64:65], off offset:32
	global_load_dwordx2 v[68:69], v[64:65], off offset:64
	s_nop 0
	global_load_dwordx2 v[66:67], v[64:65], off offset:96
	s_waitcnt vmcnt(19)
	v_fmamk_f32 v97, v97, 0x3a800000, v167
	v_mul_f32_e32 v108, 0x4b800000, v97
	v_cmp_gt_f32_e32 vcc, s22, v97
	s_nop 1
	v_cndmask_b32_e32 v97, v97, v108, vcc
	v_rsq_f32_e32 v97, v97
	s_waitcnt vmcnt(18)
	v_lshlrev_b32_e32 v108, 16, v98
	v_and_b32_e32 v98, 0xffff0000, v98
	v_mul_f32_e32 v109, 0x45800000, v97
	v_cndmask_b32_e32 v97, v97, v109, vcc
	v_mul_f32_e32 v60, v60, v97
	v_mul_f32_e32 v110, 0xbfb8aa3b, v60
	v_exp_f32_e32 v110, v110
	v_mul_f32_e32 v61, v61, v97
	v_mul_f32_e32 v111, 0xbfb8aa3b, v61
	v_exp_f32_e32 v111, v111
	v_add_f32_e32 v110, 1.0, v110
	v_rcp_f32_e32 v110, v110
	v_mul_f32_e32 v62, v62, v97
	v_mul_f32_e32 v63, v63, v97
	v_lshlrev_b32_e32 v109, 16, v99
	v_mul_f32_e32 v60, v60, v110
	v_mul_f32_e32 v60, v60, v108
	v_add_f32_e32 v108, 1.0, v111
	v_mul_f32_e32 v110, 0xbfb8aa3b, v62
	v_mul_f32_e32 v111, 0xbfb8aa3b, v63
	v_rcp_f32_e32 v108, v108
	v_exp_f32_e32 v110, v110
	v_exp_f32_e32 v111, v111
	v_and_b32_e32 v99, 0xffff0000, v99
	v_mul_f32_e32 v61, v61, v108
	v_add_f32_e32 v108, 1.0, v110
	v_add_f32_e32 v110, 1.0, v111
	v_rcp_f32_e32 v110, v110
	v_rcp_f32_e32 v108, v108
	v_mul_f32_e32 v61, v61, v98
	v_mul_f32_e32 v56, v56, v97
	v_mul_f32_e32 v63, v63, v110
	v_mul_f32_e32 v62, v62, v108
	v_mul_f32_e32 v63, v63, v99
	v_mul_f32_e32 v62, v62, v109
	v_cvt_pk_bf16_f32 v60, v60, v61
	v_cvt_pk_bf16_f32 v61, v62, v63
	v_mul_f32_e32 v63, 0xbfb8aa3b, v56
	v_exp_f32_e32 v63, v63
	v_mul_f32_e32 v57, v57, v97
	v_mul_f32_e32 v99, 0xbfb8aa3b, v57
	v_exp_f32_e32 v99, v99
	v_add_f32_e32 v63, 1.0, v63
	v_rcp_f32_e32 v63, v63
	global_store_dwordx2 v[92:93], v[60:61], off
	s_waitcnt vmcnt(18)
	v_lshlrev_b32_e32 v60, 16, v100
	v_mul_f32_e32 v58, v58, v97
	v_mul_f32_e32 v59, v59, v97
	v_mul_f32_e32 v56, v56, v63
	v_mul_f32_e32 v56, v56, v60
	v_add_f32_e32 v60, 1.0, v99
	v_mul_f32_e32 v63, 0xbfb8aa3b, v58
	v_mul_f32_e32 v99, 0xbfb8aa3b, v59
	v_rcp_f32_e32 v60, v60
	v_exp_f32_e32 v63, v63
	v_exp_f32_e32 v99, v99
	v_and_b32_e32 v61, 0xffff0000, v100
	v_mul_f32_e32 v57, v57, v60
	v_add_f32_e32 v60, 1.0, v63
	v_add_f32_e32 v63, 1.0, v99
	v_rcp_f32_e32 v63, v63
	v_rcp_f32_e32 v60, v60
	v_and_b32_e32 v98, 0xffff0000, v101
	v_lshlrev_b32_e32 v62, 16, v101
	v_mul_f32_e32 v59, v59, v63
	v_mul_f32_e32 v57, v57, v61
	v_mul_f32_e32 v58, v58, v60
	v_mul_f32_e32 v59, v59, v98
	v_mul_f32_e32 v52, v52, v97
	v_mul_f32_e32 v58, v58, v62
	v_cvt_pk_bf16_f32 v56, v56, v57
	v_cvt_pk_bf16_f32 v57, v58, v59
	v_mul_f32_e32 v59, 0xbfb8aa3b, v52
	v_exp_f32_e32 v59, v59
	v_mul_f32_e32 v53, v53, v97
	v_mul_f32_e32 v61, 0xbfb8aa3b, v53
	v_exp_f32_e32 v61, v61
	v_add_f32_e32 v59, 1.0, v59
	v_rcp_f32_e32 v59, v59
	global_store_dwordx2 v[92:93], v[56:57], off offset:32
	s_waitcnt vmcnt(18)
	v_lshlrev_b32_e32 v56, 16, v102
	v_mul_f32_e32 v54, v54, v97
	v_mul_f32_e32 v55, v55, v97
	v_mul_f32_e32 v52, v52, v59
	v_mul_f32_e32 v52, v52, v56
	v_add_f32_e32 v56, 1.0, v61
	v_mul_f32_e32 v59, 0xbfb8aa3b, v54
	v_mul_f32_e32 v61, 0xbfb8aa3b, v55
	v_rcp_f32_e32 v56, v56
	v_exp_f32_e32 v59, v59
	v_exp_f32_e32 v61, v61
	v_and_b32_e32 v57, 0xffff0000, v102
	v_mul_f32_e32 v53, v53, v56
	v_add_f32_e32 v56, 1.0, v59
	v_add_f32_e32 v59, 1.0, v61
	v_rcp_f32_e32 v59, v59
	v_rcp_f32_e32 v56, v56
	v_and_b32_e32 v60, 0xffff0000, v103
	v_lshlrev_b32_e32 v58, 16, v103
	v_mul_f32_e32 v55, v55, v59
	v_mul_f32_e32 v53, v53, v57
	v_mul_f32_e32 v54, v54, v56
	v_mul_f32_e32 v55, v55, v60
	v_mul_f32_e32 v48, v48, v97
	v_mul_f32_e32 v54, v54, v58
	v_cvt_pk_bf16_f32 v52, v52, v53
	v_cvt_pk_bf16_f32 v53, v54, v55
	v_mul_f32_e32 v55, 0xbfb8aa3b, v48
	v_exp_f32_e32 v55, v55
	v_mul_f32_e32 v49, v49, v97
	v_mul_f32_e32 v57, 0xbfb8aa3b, v49
	v_exp_f32_e32 v57, v57
	v_add_f32_e32 v55, 1.0, v55
	v_rcp_f32_e32 v55, v55
	global_store_dwordx2 v[92:93], v[52:53], off offset:64
	s_waitcnt vmcnt(18)
	v_lshlrev_b32_e32 v52, 16, v104
	v_mul_f32_e32 v50, v50, v97
	v_mul_f32_e32 v48, v48, v55
	v_mul_f32_e32 v48, v48, v52
	v_add_f32_e32 v52, 1.0, v57
	v_mul_f32_e32 v55, 0xbfb8aa3b, v50
	v_rcp_f32_e32 v52, v52
	v_exp_f32_e32 v55, v55
	v_mul_f32_e32 v51, v51, v97
	v_mul_f32_e32 v57, 0xbfb8aa3b, v51
	v_mul_f32_e32 v49, v49, v52
	v_add_f32_e32 v52, 1.0, v55
	v_rcp_f32_e32 v52, v52
	v_exp_f32_e32 v57, v57
	v_and_b32_e32 v53, 0xffff0000, v104
	v_mul_f32_e32 v49, v49, v53
	v_mul_f32_e32 v50, v50, v52
	s_waitcnt vmcnt(17)
	v_fmamk_f32 v52, v106, 0x3a800000, v167
	v_add_f32_e32 v55, 1.0, v57
	v_mul_f32_e32 v53, 0x4b800000, v52
	v_cmp_gt_f32_e32 vcc, s22, v52
	v_rcp_f32_e32 v55, v55
	v_lshlrev_b32_e32 v54, 16, v105
	v_cndmask_b32_e32 v52, v52, v53, vcc
	v_rsq_f32_e32 v52, v52
	v_and_b32_e32 v56, 0xffff0000, v105
	v_mul_f32_e32 v51, v51, v55
	v_cvt_pk_bf16_f32 v48, v48, v49
	v_mul_f32_e32 v50, v50, v54
	v_mul_f32_e32 v51, v51, v56
	v_cvt_pk_bf16_f32 v49, v50, v51
	global_store_dwordx2 v[92:93], v[48:49], off offset:96
	v_mul_f32_e32 v48, 0x45800000, v52
	v_cndmask_b32_e32 v48, v52, v48, vcc
	v_mul_f32_e32 v44, v44, v48
	v_mul_f32_e32 v52, 0xbfb8aa3b, v44
	v_exp_f32_e32 v52, v52
	v_mul_f32_e32 v45, v45, v48
	v_mul_f32_e32 v54, 0xbfb8aa3b, v45
	v_exp_f32_e32 v54, v54
	v_add_f32_e32 v52, 1.0, v52
	v_rcp_f32_e32 v52, v52
	s_waitcnt vmcnt(17)
	v_lshlrev_b32_e32 v49, 16, v94
	v_mul_f32_e32 v46, v46, v48
	v_mul_f32_e32 v47, v47, v48
	v_mul_f32_e32 v44, v44, v52
	v_mul_f32_e32 v44, v44, v49
	v_add_f32_e32 v49, 1.0, v54
	v_mul_f32_e32 v52, 0xbfb8aa3b, v46
	v_mul_f32_e32 v54, 0xbfb8aa3b, v47
	v_rcp_f32_e32 v49, v49
	v_exp_f32_e32 v52, v52
	v_exp_f32_e32 v54, v54
	v_and_b32_e32 v50, 0xffff0000, v94
	v_mul_f32_e32 v45, v45, v49
	v_add_f32_e32 v49, 1.0, v52
	v_add_f32_e32 v52, 1.0, v54
	v_rcp_f32_e32 v52, v52
	v_rcp_f32_e32 v49, v49
	v_and_b32_e32 v53, 0xffff0000, v95
	v_lshlrev_b32_e32 v51, 16, v95
	v_mul_f32_e32 v47, v47, v52
	v_mul_f32_e32 v45, v45, v50
	v_mul_f32_e32 v46, v46, v49
	v_mul_f32_e32 v47, v47, v53
	v_mul_f32_e32 v40, v40, v48
	v_mul_f32_e32 v46, v46, v51
	v_cvt_pk_bf16_f32 v44, v44, v45
	v_cvt_pk_bf16_f32 v45, v46, v47
	v_mul_f32_e32 v47, 0xbfb8aa3b, v40
	v_exp_f32_e32 v47, v47
	v_mul_f32_e32 v41, v41, v48
	v_mul_f32_e32 v50, 0xbfb8aa3b, v41
	v_exp_f32_e32 v50, v50
	v_add_f32_e32 v47, 1.0, v47
	v_rcp_f32_e32 v47, v47
	global_store_dwordx2 v[82:83], v[44:45], off
	s_waitcnt vmcnt(17)
	v_lshlrev_b32_e32 v44, 16, v90
	v_mul_f32_e32 v42, v42, v48
	v_mul_f32_e32 v43, v43, v48
	v_mul_f32_e32 v40, v40, v47
	v_mul_f32_e32 v40, v40, v44
	v_add_f32_e32 v44, 1.0, v50
	v_mul_f32_e32 v47, 0xbfb8aa3b, v42
	v_mul_f32_e32 v50, 0xbfb8aa3b, v43
	v_rcp_f32_e32 v44, v44
	v_exp_f32_e32 v47, v47
	v_exp_f32_e32 v50, v50
	v_and_b32_e32 v45, 0xffff0000, v90
	v_mul_f32_e32 v41, v41, v44
	v_add_f32_e32 v44, 1.0, v47
	v_add_f32_e32 v47, 1.0, v50
	v_rcp_f32_e32 v47, v47
	v_rcp_f32_e32 v44, v44
	v_and_b32_e32 v49, 0xffff0000, v91
	v_lshlrev_b32_e32 v46, 16, v91
	v_mul_f32_e32 v43, v43, v47
	v_mul_f32_e32 v41, v41, v45
	v_mul_f32_e32 v42, v42, v44
	v_mul_f32_e32 v43, v43, v49
	v_mul_f32_e32 v36, v36, v48
	v_mul_f32_e32 v42, v42, v46
	v_cvt_pk_bf16_f32 v40, v40, v41
	v_cvt_pk_bf16_f32 v41, v42, v43
	v_mul_f32_e32 v43, 0xbfb8aa3b, v36
	v_exp_f32_e32 v43, v43
	v_mul_f32_e32 v37, v37, v48
	v_mul_f32_e32 v45, 0xbfb8aa3b, v37
	v_exp_f32_e32 v45, v45
	v_add_f32_e32 v43, 1.0, v43
	v_rcp_f32_e32 v43, v43
	global_store_dwordx2 v[82:83], v[40:41], off offset:32
	s_waitcnt vmcnt(17)
	v_lshlrev_b32_e32 v40, 16, v88
	v_mul_f32_e32 v38, v38, v48
	v_mul_f32_e32 v39, v39, v48
	v_mul_f32_e32 v36, v36, v43
	v_mul_f32_e32 v36, v36, v40
	v_add_f32_e32 v40, 1.0, v45
	v_mul_f32_e32 v43, 0xbfb8aa3b, v38
	v_mul_f32_e32 v45, 0xbfb8aa3b, v39
	v_rcp_f32_e32 v40, v40
	v_exp_f32_e32 v43, v43
	v_exp_f32_e32 v45, v45
	v_and_b32_e32 v41, 0xffff0000, v88
	v_mul_f32_e32 v37, v37, v40
	v_add_f32_e32 v40, 1.0, v43
	v_add_f32_e32 v43, 1.0, v45
	v_rcp_f32_e32 v43, v43
	v_rcp_f32_e32 v40, v40
	v_and_b32_e32 v44, 0xffff0000, v89
	v_lshlrev_b32_e32 v42, 16, v89
	v_mul_f32_e32 v39, v39, v43
	v_mul_f32_e32 v37, v37, v41
	v_mul_f32_e32 v38, v38, v40
	v_mul_f32_e32 v39, v39, v44
	v_mul_f32_e32 v32, v32, v48
	v_mul_f32_e32 v38, v38, v42
	v_cvt_pk_bf16_f32 v36, v36, v37
	v_cvt_pk_bf16_f32 v37, v38, v39
	v_mul_f32_e32 v39, 0xbfb8aa3b, v32
	v_exp_f32_e32 v39, v39
	v_mul_f32_e32 v33, v33, v48
	v_mul_f32_e32 v41, 0xbfb8aa3b, v33
	v_exp_f32_e32 v41, v41
	v_add_f32_e32 v39, 1.0, v39
	v_rcp_f32_e32 v39, v39
	global_store_dwordx2 v[82:83], v[36:37], off offset:64
	s_waitcnt vmcnt(17)
	v_lshlrev_b32_e32 v36, 16, v86
	v_mul_f32_e32 v34, v34, v48
	v_mul_f32_e32 v32, v32, v39
	v_mul_f32_e32 v32, v32, v36
	v_add_f32_e32 v36, 1.0, v41
	v_mul_f32_e32 v39, 0xbfb8aa3b, v34
	v_rcp_f32_e32 v36, v36
	v_exp_f32_e32 v39, v39
	v_mul_f32_e32 v35, v35, v48
	v_mul_f32_e32 v41, 0xbfb8aa3b, v35
	v_mul_f32_e32 v33, v33, v36
	v_add_f32_e32 v36, 1.0, v39
	v_rcp_f32_e32 v36, v36
	v_exp_f32_e32 v41, v41
	v_and_b32_e32 v37, 0xffff0000, v86
	v_mul_f32_e32 v33, v33, v37
	v_mul_f32_e32 v34, v34, v36
	s_waitcnt vmcnt(16)
	v_fmamk_f32 v36, v107, 0x3a800000, v167
	v_add_f32_e32 v39, 1.0, v41
	v_mul_f32_e32 v37, 0x4b800000, v36
	v_cmp_gt_f32_e32 vcc, s22, v36
	v_rcp_f32_e32 v39, v39
	v_lshlrev_b32_e32 v38, 16, v87
	v_cndmask_b32_e32 v36, v36, v37, vcc
	v_rsq_f32_e32 v36, v36
	v_and_b32_e32 v40, 0xffff0000, v87
	v_mul_f32_e32 v35, v35, v39
	v_cvt_pk_bf16_f32 v32, v32, v33
	v_mul_f32_e32 v34, v34, v38
	v_mul_f32_e32 v35, v35, v40
	v_cvt_pk_bf16_f32 v33, v34, v35
	global_store_dwordx2 v[82:83], v[32:33], off offset:96
	v_mul_f32_e32 v32, 0x45800000, v36
	v_cndmask_b32_e32 v32, v36, v32, vcc
	v_mul_f32_e32 v28, v28, v32
	v_mul_f32_e32 v36, 0xbfb8aa3b, v28
	v_exp_f32_e32 v36, v36
	v_mul_f32_e32 v29, v29, v32
	v_mul_f32_e32 v38, 0xbfb8aa3b, v29
	v_exp_f32_e32 v38, v38
	v_add_f32_e32 v36, 1.0, v36
	v_rcp_f32_e32 v36, v36
	s_waitcnt vmcnt(16)
	v_lshlrev_b32_e32 v33, 16, v84
	v_mul_f32_e32 v30, v30, v32
	v_mul_f32_e32 v31, v31, v32
	v_mul_f32_e32 v28, v28, v36
	v_mul_f32_e32 v28, v28, v33
	v_add_f32_e32 v33, 1.0, v38
	v_mul_f32_e32 v36, 0xbfb8aa3b, v30
	v_mul_f32_e32 v38, 0xbfb8aa3b, v31
	v_rcp_f32_e32 v33, v33
	v_exp_f32_e32 v36, v36
	v_exp_f32_e32 v38, v38
	v_and_b32_e32 v34, 0xffff0000, v84
	v_mul_f32_e32 v29, v29, v33
	v_add_f32_e32 v33, 1.0, v36
	v_add_f32_e32 v36, 1.0, v38
	v_rcp_f32_e32 v36, v36
	v_rcp_f32_e32 v33, v33
	v_and_b32_e32 v37, 0xffff0000, v85
	v_lshlrev_b32_e32 v35, 16, v85
	v_mul_f32_e32 v31, v31, v36
	v_mul_f32_e32 v29, v29, v34
	v_mul_f32_e32 v30, v30, v33
	v_mul_f32_e32 v31, v31, v37
	v_mul_f32_e32 v24, v24, v32
	v_mul_f32_e32 v30, v30, v35
	v_cvt_pk_bf16_f32 v28, v28, v29
	v_cvt_pk_bf16_f32 v29, v30, v31
	v_mul_f32_e32 v31, 0xbfb8aa3b, v24
	v_exp_f32_e32 v31, v31
	v_mul_f32_e32 v25, v25, v32
	v_mul_f32_e32 v34, 0xbfb8aa3b, v25
	v_exp_f32_e32 v34, v34
	v_add_f32_e32 v31, 1.0, v31
	v_rcp_f32_e32 v31, v31
	global_store_dwordx2 v[72:73], v[28:29], off
	s_waitcnt vmcnt(16)
	v_lshlrev_b32_e32 v28, 16, v80
	v_mul_f32_e32 v26, v26, v32
	v_mul_f32_e32 v27, v27, v32
	v_mul_f32_e32 v24, v24, v31
	v_mul_f32_e32 v24, v24, v28
	v_add_f32_e32 v28, 1.0, v34
	v_mul_f32_e32 v31, 0xbfb8aa3b, v26
	v_mul_f32_e32 v34, 0xbfb8aa3b, v27
	v_rcp_f32_e32 v28, v28
	v_exp_f32_e32 v31, v31
	v_exp_f32_e32 v34, v34
	v_and_b32_e32 v29, 0xffff0000, v80
	v_mul_f32_e32 v25, v25, v28
	v_add_f32_e32 v28, 1.0, v31
	v_add_f32_e32 v31, 1.0, v34
	v_rcp_f32_e32 v31, v31
	v_rcp_f32_e32 v28, v28
	v_and_b32_e32 v33, 0xffff0000, v81
	v_lshlrev_b32_e32 v30, 16, v81
	v_mul_f32_e32 v27, v27, v31
	v_mul_f32_e32 v25, v25, v29
	v_mul_f32_e32 v26, v26, v28
	v_mul_f32_e32 v27, v27, v33
	v_mul_f32_e32 v20, v20, v32
	v_mul_f32_e32 v26, v26, v30
	v_cvt_pk_bf16_f32 v24, v24, v25
	v_cvt_pk_bf16_f32 v25, v26, v27
	v_mul_f32_e32 v27, 0xbfb8aa3b, v20
	v_exp_f32_e32 v27, v27
	v_mul_f32_e32 v21, v21, v32
	v_mul_f32_e32 v29, 0xbfb8aa3b, v21
	v_exp_f32_e32 v29, v29
	v_add_f32_e32 v27, 1.0, v27
	v_rcp_f32_e32 v27, v27
	global_store_dwordx2 v[72:73], v[24:25], off offset:32
	s_waitcnt vmcnt(16)
	v_lshlrev_b32_e32 v24, 16, v78
	v_mul_f32_e32 v22, v22, v32
	v_mul_f32_e32 v23, v23, v32
	v_mul_f32_e32 v20, v20, v27
	v_mul_f32_e32 v20, v20, v24
	v_add_f32_e32 v24, 1.0, v29
	v_mul_f32_e32 v27, 0xbfb8aa3b, v22
	v_mul_f32_e32 v29, 0xbfb8aa3b, v23
	v_rcp_f32_e32 v24, v24
	v_exp_f32_e32 v27, v27
	v_exp_f32_e32 v29, v29
	v_and_b32_e32 v25, 0xffff0000, v78
	v_mul_f32_e32 v21, v21, v24
	v_add_f32_e32 v24, 1.0, v27
	v_add_f32_e32 v27, 1.0, v29
	v_rcp_f32_e32 v27, v27
	v_rcp_f32_e32 v24, v24
	v_and_b32_e32 v28, 0xffff0000, v79
	v_lshlrev_b32_e32 v26, 16, v79
	v_mul_f32_e32 v23, v23, v27
	v_mul_f32_e32 v21, v21, v25
	v_mul_f32_e32 v22, v22, v24
	v_mul_f32_e32 v23, v23, v28
	v_mul_f32_e32 v16, v16, v32
	v_mul_f32_e32 v22, v22, v26
	v_cvt_pk_bf16_f32 v20, v20, v21
	v_cvt_pk_bf16_f32 v21, v22, v23
	v_mul_f32_e32 v23, 0xbfb8aa3b, v16
	v_exp_f32_e32 v23, v23
	v_mul_f32_e32 v17, v17, v32
	v_mul_f32_e32 v25, 0xbfb8aa3b, v17
	v_exp_f32_e32 v25, v25
	v_add_f32_e32 v23, 1.0, v23
	v_rcp_f32_e32 v23, v23
	global_store_dwordx2 v[72:73], v[20:21], off offset:64
	s_waitcnt vmcnt(16)
	v_lshlrev_b32_e32 v20, 16, v76
	v_mul_f32_e32 v18, v18, v32
	v_mul_f32_e32 v16, v16, v23
	v_mul_f32_e32 v16, v16, v20
	v_add_f32_e32 v20, 1.0, v25
	v_mul_f32_e32 v23, 0xbfb8aa3b, v18
	v_rcp_f32_e32 v20, v20
	v_exp_f32_e32 v23, v23
	v_mul_f32_e32 v19, v19, v32
	v_mul_f32_e32 v25, 0xbfb8aa3b, v19
	v_mul_f32_e32 v17, v17, v20
	v_add_f32_e32 v20, 1.0, v23
	v_rcp_f32_e32 v20, v20
	v_exp_f32_e32 v25, v25
	v_and_b32_e32 v21, 0xffff0000, v76
	v_mul_f32_e32 v17, v17, v21
	v_mul_f32_e32 v18, v18, v20
	s_waitcnt vmcnt(15)
	v_fmamk_f32 v20, v96, 0x3a800000, v167
	v_add_f32_e32 v23, 1.0, v25
	v_mul_f32_e32 v21, 0x4b800000, v20
	v_cmp_gt_f32_e32 vcc, s22, v20
	v_rcp_f32_e32 v23, v23
	v_lshlrev_b32_e32 v22, 16, v77
	v_cndmask_b32_e32 v20, v20, v21, vcc
	v_rsq_f32_e32 v20, v20
	v_and_b32_e32 v24, 0xffff0000, v77
	v_mul_f32_e32 v19, v19, v23
	v_cvt_pk_bf16_f32 v16, v16, v17
	v_mul_f32_e32 v18, v18, v22
	v_mul_f32_e32 v19, v19, v24
	v_cvt_pk_bf16_f32 v17, v18, v19
	global_store_dwordx2 v[72:73], v[16:17], off offset:96
	v_mul_f32_e32 v16, 0x45800000, v20
	v_cndmask_b32_e32 v16, v20, v16, vcc
	v_mul_f32_e32 v12, v12, v16
	v_mul_f32_e32 v20, 0xbfb8aa3b, v12
	v_exp_f32_e32 v20, v20
	v_mul_f32_e32 v13, v13, v16
	v_mul_f32_e32 v22, 0xbfb8aa3b, v13
	v_exp_f32_e32 v22, v22
	v_add_f32_e32 v20, 1.0, v20
	v_rcp_f32_e32 v20, v20
	s_waitcnt vmcnt(15)
	v_lshlrev_b32_e32 v17, 16, v74
	v_mul_f32_e32 v14, v14, v16
	v_mul_f32_e32 v15, v15, v16
	v_mul_f32_e32 v12, v12, v20
	v_mul_f32_e32 v12, v12, v17
	v_add_f32_e32 v17, 1.0, v22
	v_mul_f32_e32 v20, 0xbfb8aa3b, v14
	v_mul_f32_e32 v22, 0xbfb8aa3b, v15
	v_rcp_f32_e32 v17, v17
	v_exp_f32_e32 v20, v20
	v_exp_f32_e32 v22, v22
	v_and_b32_e32 v18, 0xffff0000, v74
	v_mul_f32_e32 v13, v13, v17
	v_add_f32_e32 v17, 1.0, v20
	v_add_f32_e32 v20, 1.0, v22
	v_rcp_f32_e32 v20, v20
	v_rcp_f32_e32 v17, v17
	v_and_b32_e32 v21, 0xffff0000, v75
	v_lshlrev_b32_e32 v19, 16, v75
	v_mul_f32_e32 v15, v15, v20
	v_mul_f32_e32 v13, v13, v18
	v_mul_f32_e32 v14, v14, v17
	v_mul_f32_e32 v15, v15, v21
	v_mul_f32_e32 v8, v8, v16
	v_mul_f32_e32 v14, v14, v19
	v_cvt_pk_bf16_f32 v12, v12, v13
	v_cvt_pk_bf16_f32 v13, v14, v15
	v_mul_f32_e32 v15, 0xbfb8aa3b, v8
	v_exp_f32_e32 v15, v15
	v_mul_f32_e32 v9, v9, v16
	v_mul_f32_e32 v18, 0xbfb8aa3b, v9
	v_exp_f32_e32 v18, v18
	v_add_f32_e32 v15, 1.0, v15
	v_rcp_f32_e32 v15, v15
	global_store_dwordx2 v[64:65], v[12:13], off
	s_waitcnt vmcnt(15)
	v_lshlrev_b32_e32 v12, 16, v70
	v_mul_f32_e32 v10, v10, v16
	v_mul_f32_e32 v11, v11, v16
	v_mul_f32_e32 v8, v8, v15
	v_mul_f32_e32 v8, v8, v12
	v_add_f32_e32 v12, 1.0, v18
	v_mul_f32_e32 v15, 0xbfb8aa3b, v10
	v_mul_f32_e32 v18, 0xbfb8aa3b, v11
	v_rcp_f32_e32 v12, v12
	v_exp_f32_e32 v15, v15
	v_exp_f32_e32 v18, v18
	v_and_b32_e32 v13, 0xffff0000, v70
	v_mul_f32_e32 v9, v9, v12
	v_add_f32_e32 v12, 1.0, v15
	v_add_f32_e32 v15, 1.0, v18
	v_rcp_f32_e32 v15, v15
	v_rcp_f32_e32 v12, v12
	v_and_b32_e32 v17, 0xffff0000, v71
	v_lshlrev_b32_e32 v14, 16, v71
	v_mul_f32_e32 v11, v11, v15
	v_mul_f32_e32 v9, v9, v13
	v_mul_f32_e32 v10, v10, v12
	v_mul_f32_e32 v11, v11, v17
	v_mul_f32_e32 v4, v4, v16
	v_mul_f32_e32 v10, v10, v14
	v_cvt_pk_bf16_f32 v8, v8, v9
	v_cvt_pk_bf16_f32 v9, v10, v11
	v_mul_f32_e32 v11, 0xbfb8aa3b, v4
	v_exp_f32_e32 v11, v11
	v_mul_f32_e32 v5, v5, v16
	v_mul_f32_e32 v13, 0xbfb8aa3b, v5
	v_exp_f32_e32 v13, v13
	v_add_f32_e32 v11, 1.0, v11
	v_rcp_f32_e32 v11, v11
	global_store_dwordx2 v[64:65], v[8:9], off offset:32
	s_waitcnt vmcnt(15)
	v_lshlrev_b32_e32 v8, 16, v68
	v_mul_f32_e32 v6, v6, v16
	v_mul_f32_e32 v7, v7, v16
	v_mul_f32_e32 v4, v4, v11
	v_mul_f32_e32 v4, v4, v8
	v_add_f32_e32 v8, 1.0, v13
	v_mul_f32_e32 v11, 0xbfb8aa3b, v6
	v_mul_f32_e32 v13, 0xbfb8aa3b, v7
	v_rcp_f32_e32 v8, v8
	v_exp_f32_e32 v11, v11
	v_exp_f32_e32 v13, v13
	v_and_b32_e32 v9, 0xffff0000, v68
	v_mul_f32_e32 v5, v5, v8
	v_add_f32_e32 v8, 1.0, v11
	v_add_f32_e32 v11, 1.0, v13
	v_rcp_f32_e32 v11, v11
	v_rcp_f32_e32 v8, v8
	v_and_b32_e32 v12, 0xffff0000, v69
	v_lshlrev_b32_e32 v10, 16, v69
	v_mul_f32_e32 v7, v7, v11
	v_mul_f32_e32 v5, v5, v9
	v_mul_f32_e32 v6, v6, v8
	v_mul_f32_e32 v7, v7, v12
	v_mul_f32_e32 v0, v0, v16
	v_mul_f32_e32 v6, v6, v10
	v_cvt_pk_bf16_f32 v4, v4, v5
	v_cvt_pk_bf16_f32 v5, v6, v7
	v_mul_f32_e32 v7, 0xbfb8aa3b, v0
	v_exp_f32_e32 v7, v7
	v_mul_f32_e32 v1, v1, v16
	v_mul_f32_e32 v9, 0xbfb8aa3b, v1
	v_exp_f32_e32 v9, v9
	v_add_f32_e32 v7, 1.0, v7
	v_rcp_f32_e32 v7, v7
	global_store_dwordx2 v[64:65], v[4:5], off offset:64
	s_waitcnt vmcnt(15)
	v_lshlrev_b32_e32 v4, 16, v66
	v_mul_f32_e32 v2, v2, v16
	v_mul_f32_e32 v3, v3, v16
	v_mul_f32_e32 v0, v0, v7
	v_mul_f32_e32 v0, v0, v4
	v_add_f32_e32 v4, 1.0, v9
	v_mul_f32_e32 v7, 0xbfb8aa3b, v2
	v_mul_f32_e32 v9, 0xbfb8aa3b, v3
	v_rcp_f32_e32 v4, v4
	v_exp_f32_e32 v7, v7
	v_exp_f32_e32 v9, v9
	v_and_b32_e32 v5, 0xffff0000, v66
	v_mul_f32_e32 v1, v1, v4
	v_add_f32_e32 v4, 1.0, v7
	v_add_f32_e32 v7, 1.0, v9
	v_rcp_f32_e32 v4, v4
	v_rcp_f32_e32 v7, v7
	v_lshlrev_b32_e32 v6, 16, v67
	v_and_b32_e32 v8, 0xffff0000, v67
	v_mul_f32_e32 v1, v1, v5
	v_mul_f32_e32 v2, v2, v4
	v_mul_f32_e32 v3, v3, v7
	v_mul_f32_e32 v2, v2, v6
	v_mul_f32_e32 v3, v3, v8
	v_cvt_pk_bf16_f32 v0, v0, v1
	v_cvt_pk_bf16_f32 v1, v2, v3
	global_store_dwordx2 v[64:65], v[0:1], off offset:96
	s_add_i32 s23, s23, s74
	s_cmpk_lt_i32 s23, 0x800
	s_cbranch_scc1 .LBB0_1736

.LBB0_1795:
	s_add_i32 s26, s21, 64
	s_min_u32 s18, s26, 0x7e0
	s_lshl_b32 s18, s18, 1
	v_lshl_add_u64 v[174:175], v[156:157], 0, s[18:19]
	global_load_dwordx4 v[178:181], v[174:175], off
	v_lshl_add_u64 v[174:175], v[158:159], 0, s[18:19]
	v_lshl_add_u64 v[170:171], v[152:153], 0, s[18:19]
	v_lshl_add_u64 v[186:187], v[160:161], 0, s[18:19]
	global_load_dwordx4 v[182:185], v[174:175], off
	v_lshl_add_u64 v[174:175], v[154:155], 0, s[18:19]
	v_lshl_add_u64 v[194:195], v[162:163], 0, s[18:19]
	global_load_dwordx4 v[170:173], v[170:171], off
	ds_read_b128 v[200:203], v168 offset:32768
	global_load_dwordx4 v[186:189], v[186:187], off
	ds_read_b128 v[204:207], v168 offset:33792
	global_load_dwordx4 v[190:193], v[174:175], off
	ds_read_b128 v[208:211], v168 offset:34816
	global_load_dwordx4 v[194:197], v[194:195], off
	ds_read_b128 v[212:215], v168 offset:35840
	ds_read_b128 v[216:219], v166
	ds_read_b128 v[222:225], v166 offset:1024
	ds_read_b128 v[226:229], v166 offset:2048
	ds_read_b128 v[230:233], v166 offset:3072
	ds_read_b128 v[234:237], v166 offset:4096
	ds_read_b128 v[238:241], v166 offset:5120
	ds_read_b128 v[242:245], v166 offset:6144
	ds_read_b128 v[246:249], v166 offset:7168
	s_setprio 1
	s_waitcnt lgkmcnt(7)
	v_mfma_f32_16x16x32_bf16 v[148:151], v[200:203], v[216:219], v[148:151]
	v_mfma_f32_16x16x32_bf16 v[144:147], v[204:207], v[216:219], v[144:147]
	v_mfma_f32_16x16x32_bf16 v[140:143], v[208:211], v[216:219], v[140:143]
	v_mfma_f32_16x16x32_bf16 v[116:119], v[212:215], v[216:219], v[116:119]
	s_waitcnt vmcnt(11)
	ds_write_b128 v164, v[112:115] offset:16384
	s_waitcnt lgkmcnt(7)
	v_mfma_f32_16x16x32_bf16 v[108:111], v[200:203], v[222:225], v[108:111]
	v_mfma_f32_16x16x32_bf16 v[104:107], v[204:207], v[222:225], v[104:107]
	v_mfma_f32_16x16x32_bf16 v[100:103], v[208:211], v[222:225], v[100:103]
	v_mfma_f32_16x16x32_bf16 v[96:99], v[212:215], v[222:225], v[96:99]
	s_waitcnt vmcnt(9)
	ds_write_b128 v164, v[120:123] offset:20480
	s_waitcnt lgkmcnt(7)
	v_mfma_f32_16x16x32_bf16 v[92:95], v[200:203], v[226:229], v[92:95]
	v_mfma_f32_16x16x32_bf16 v[88:91], v[204:207], v[226:229], v[88:91]
	v_mfma_f32_16x16x32_bf16 v[84:87], v[208:211], v[226:229], v[84:87]
	v_mfma_f32_16x16x32_bf16 v[80:83], v[212:215], v[226:229], v[80:83]
	s_waitcnt vmcnt(8)
	ds_write_b128 v164, v[124:127] offset:24576
	s_waitcnt lgkmcnt(7)
	v_mfma_f32_16x16x32_bf16 v[76:79], v[200:203], v[230:233], v[76:79]
	v_mfma_f32_16x16x32_bf16 v[72:75], v[204:207], v[230:233], v[72:75]
	v_mfma_f32_16x16x32_bf16 v[68:71], v[208:211], v[230:233], v[68:71]
	v_mfma_f32_16x16x32_bf16 v[64:67], v[212:215], v[230:233], v[64:67]
	s_waitcnt vmcnt(7)
	ds_write_b128 v164, v[132:135] offset:28672
	s_waitcnt lgkmcnt(7)
	v_mfma_f32_16x16x32_bf16 v[60:63], v[200:203], v[234:237], v[60:63]
	v_mfma_f32_16x16x32_bf16 v[56:59], v[204:207], v[234:237], v[56:59]
	v_mfma_f32_16x16x32_bf16 v[52:55], v[208:211], v[234:237], v[52:55]
	v_mfma_f32_16x16x32_bf16 v[48:51], v[212:215], v[234:237], v[48:51]
	s_waitcnt vmcnt(6)
	ds_write_b128 v164, v[136:139] offset:45056
	s_waitcnt lgkmcnt(7)
	v_mfma_f32_16x16x32_bf16 v[44:47], v[200:203], v[238:241], v[44:47]
	v_mfma_f32_16x16x32_bf16 v[40:43], v[204:207], v[238:241], v[40:43]
	v_mfma_f32_16x16x32_bf16 v[36:39], v[208:211], v[238:241], v[36:39]
	v_mfma_f32_16x16x32_bf16 v[32:35], v[212:215], v[238:241], v[32:35]
	ds_write_b128 v164, v[128:131] offset:40960
	s_waitcnt lgkmcnt(7)
	v_mfma_f32_16x16x32_bf16 v[28:31], v[200:203], v[242:245], v[28:31]
	v_mfma_f32_16x16x32_bf16 v[24:27], v[204:207], v[242:245], v[24:27]
	v_mfma_f32_16x16x32_bf16 v[20:23], v[208:211], v[242:245], v[20:23]
	v_mfma_f32_16x16x32_bf16 v[16:19], v[212:215], v[242:245], v[16:19]
	s_waitcnt lgkmcnt(6)
	v_mfma_f32_16x16x32_bf16 v[12:15], v[200:203], v[246:249], v[12:15]
	v_mfma_f32_16x16x32_bf16 v[8:11], v[204:207], v[246:249], v[8:11]
	v_mfma_f32_16x16x32_bf16 v[4:7], v[208:211], v[246:249], v[4:7]
	v_mfma_f32_16x16x32_bf16 v[0:3], v[212:215], v[246:249], v[0:3]
	s_setprio 0
	s_min_u32 s18, s21, 0x780
	s_lshl_b32 s18, s18, 1
	s_mov_b32 s29, s19
	s_add_i32 s28, s18, 0xc0
	v_lshl_add_u64 v[112:113], v[152:153], 0, s[18:19]
	v_lshl_add_u64 v[120:121], v[154:155], 0, s[18:19]
	v_lshl_add_u64 v[122:123], v[156:157], 0, s[28:29]
	v_lshl_add_u64 v[124:125], v[158:159], 0, s[28:29]
	v_lshl_add_u64 v[132:133], v[160:161], 0, s[28:29]
	v_lshl_add_u64 v[136:137], v[162:163], 0, s[28:29]
	s_waitcnt lgkmcnt(0)
	s_barrier
	global_load_dwordx4 v[112:115], v[112:113], off offset:192
	ds_read_b128 v[200:203], v165 offset:40960
	global_load_dwordx4 v[128:131], v[120:121], off offset:192
	ds_read_b128 v[204:207], v165 offset:41984
	global_load_dwordx4 v[120:123], v[122:123], off
	ds_read_b128 v[208:211], v165 offset:43008
	global_load_dwordx4 v[124:127], v[124:125], off
	ds_read_b128 v[212:215], v165 offset:44032
	global_load_dwordx4 v[132:135], v[132:133], off
	ds_read_b128 v[216:219], v167
	global_load_dwordx4 v[136:139], v[136:137], off
	ds_read_b128 v[222:225], v167 offset:1024
	ds_read_b128 v[226:229], v167 offset:2048
	ds_read_b128 v[230:233], v167 offset:3072
	ds_read_b128 v[234:237], v167 offset:4096
	ds_read_b128 v[238:241], v167 offset:5120
	ds_read_b128 v[242:245], v167 offset:6144
	ds_read_b128 v[246:249], v167 offset:7168
	s_setprio 1
	s_waitcnt lgkmcnt(7)
	v_mfma_f32_16x16x32_bf16 v[148:151], v[200:203], v[216:219], v[148:151]
	v_mfma_f32_16x16x32_bf16 v[144:147], v[204:207], v[216:219], v[144:147]
	v_mfma_f32_16x16x32_bf16 v[140:143], v[208:211], v[216:219], v[140:143]
	v_mfma_f32_16x16x32_bf16 v[116:119], v[212:215], v[216:219], v[116:119]
	s_waitcnt vmcnt(9)
	ds_write_b128 v164, v[170:173]
	s_waitcnt lgkmcnt(7)
	v_mfma_f32_16x16x32_bf16 v[108:111], v[200:203], v[222:225], v[108:111]
	v_mfma_f32_16x16x32_bf16 v[104:107], v[204:207], v[222:225], v[104:107]
	v_mfma_f32_16x16x32_bf16 v[100:103], v[208:211], v[222:225], v[100:103]
	v_mfma_f32_16x16x32_bf16 v[96:99], v[212:215], v[222:225], v[96:99]
	ds_write_b128 v164, v[178:181] offset:4096
	s_waitcnt lgkmcnt(7)
	v_mfma_f32_16x16x32_bf16 v[92:95], v[200:203], v[226:229], v[92:95]
	v_mfma_f32_16x16x32_bf16 v[88:91], v[204:207], v[226:229], v[88:91]
	v_mfma_f32_16x16x32_bf16 v[84:87], v[208:211], v[226:229], v[84:87]
	v_mfma_f32_16x16x32_bf16 v[80:83], v[212:215], v[226:229], v[80:83]
	ds_write_b128 v164, v[182:185] offset:8192
	s_waitcnt lgkmcnt(7)
	v_mfma_f32_16x16x32_bf16 v[76:79], v[200:203], v[230:233], v[76:79]
	v_mfma_f32_16x16x32_bf16 v[72:75], v[204:207], v[230:233], v[72:75]
	v_mfma_f32_16x16x32_bf16 v[68:71], v[208:211], v[230:233], v[68:71]
	v_mfma_f32_16x16x32_bf16 v[64:67], v[212:215], v[230:233], v[64:67]
	s_waitcnt vmcnt(8)
	ds_write_b128 v164, v[186:189] offset:12288
	s_waitcnt lgkmcnt(7)
	v_mfma_f32_16x16x32_bf16 v[60:63], v[200:203], v[234:237], v[60:63]
	v_mfma_f32_16x16x32_bf16 v[56:59], v[204:207], v[234:237], v[56:59]
	v_mfma_f32_16x16x32_bf16 v[52:55], v[208:211], v[234:237], v[52:55]
	v_mfma_f32_16x16x32_bf16 v[48:51], v[212:215], v[234:237], v[48:51]
	s_waitcnt vmcnt(7)
	ds_write_b128 v164, v[190:193] offset:32768
	s_waitcnt lgkmcnt(7)
	v_mfma_f32_16x16x32_bf16 v[44:47], v[200:203], v[238:241], v[44:47]
	v_mfma_f32_16x16x32_bf16 v[40:43], v[204:207], v[238:241], v[40:43]
	v_mfma_f32_16x16x32_bf16 v[36:39], v[208:211], v[238:241], v[36:39]
	v_mfma_f32_16x16x32_bf16 v[32:35], v[212:215], v[238:241], v[32:35]
	s_waitcnt vmcnt(6)
	ds_write_b128 v164, v[194:197] offset:36864
	s_waitcnt lgkmcnt(7)
	v_mfma_f32_16x16x32_bf16 v[28:31], v[200:203], v[242:245], v[28:31]
	v_mfma_f32_16x16x32_bf16 v[24:27], v[204:207], v[242:245], v[24:27]
	v_mfma_f32_16x16x32_bf16 v[20:23], v[208:211], v[242:245], v[20:23]
	v_mfma_f32_16x16x32_bf16 v[16:19], v[212:215], v[242:245], v[16:19]
	s_waitcnt lgkmcnt(6)
	v_mfma_f32_16x16x32_bf16 v[12:15], v[200:203], v[246:249], v[12:15]
	v_mfma_f32_16x16x32_bf16 v[8:11], v[204:207], v[246:249], v[8:11]
	v_mfma_f32_16x16x32_bf16 v[4:7], v[208:211], v[246:249], v[4:7]
	v_mfma_f32_16x16x32_bf16 v[0:3], v[212:215], v[246:249], v[0:3]
	s_setprio 0
	s_add_i32 s1, s1, 2
	s_cmp_lt_u32 s1, 62
	s_mov_b32 s21, s26
	s_waitcnt lgkmcnt(0)
	s_barrier
	s_cbranch_scc1 .LBB0_1795
	s_waitcnt vmcnt(5)
	v_mov_b32_e32 v112, v220
	s_nop 0
	v_and_b32_e32 v114, 0xffffff80, v112
	v_bfe_u32 v176, v112, 4, 2
	v_add_u32_e32 v114, s20, v114
	v_and_b32_e32 v113, 64, v112
	v_and_or_b32 v184, v112, 15, v114
	v_lshlrev_b32_e32 v112, 2, v176
	v_or3_b32 v178, v112, v113, s0
	v_ashrrev_i32_e32 v179, 31, v178
	v_lshlrev_b64 v[216:217], 2, v[178:179]
	v_ashrrev_i32_e32 v185, 31, v184
	v_or_b32_e32 v194, 16, v184
	v_lshl_add_u64 v[182:183], s[70:71], 0, v[216:217]
	v_lshlrev_b64 v[218:219], 12, v[184:185]
	v_ashrrev_i32_e32 v195, 31, v194
	v_or_b32_e32 v190, 32, v184
	v_lshl_add_u64 v[112:113], v[182:183], 0, v[218:219]
	v_lshlrev_b64 v[196:197], 12, v[194:195]
	v_ashrrev_i32_e32 v191, 31, v190
	v_or_b32_e32 v186, 48, v184
	global_load_dwordx4 v[200:203], v[112:113], off
	global_load_dwordx4 v[204:207], v[112:113], off offset:64
	global_load_dwordx4 v[208:211], v[112:113], off offset:128
	global_load_dwordx4 v[212:215], v[112:113], off offset:192
	v_lshl_add_u64 v[112:113], v[182:183], 0, v[196:197]
	v_lshlrev_b64 v[192:193], 12, v[190:191]
	v_ashrrev_i32_e32 v187, 31, v186
	global_load_dwordx4 v[172:175], v[112:113], off
	global_load_dwordx4 v[168:171], v[112:113], off offset:64
	global_load_dwordx4 v[164:167], v[112:113], off offset:128
	global_load_dwordx4 v[160:163], v[112:113], off offset:192
	v_lshl_add_u64 v[112:113], v[182:183], 0, v[192:193]
	v_lshlrev_b64 v[188:189], 12, v[186:187]
	global_load_dwordx4 v[156:159], v[112:113], off
	global_load_dwordx4 v[152:155], v[112:113], off offset:64
	global_load_dwordx4 v[136:139], v[112:113], off offset:128
	global_load_dwordx4 v[132:135], v[112:113], off offset:192
	v_lshl_add_u64 v[112:113], v[182:183], 0, v[188:189]
	global_load_dwordx4 v[128:131], v[112:113], off
	global_load_dwordx4 v[124:127], v[112:113], off offset:64
	global_load_dwordx4 v[120:123], v[112:113], off offset:128
	s_nop 0
	global_load_dwordx4 v[112:115], v[112:113], off offset:192
	v_cmp_eq_u32_e32 vcc, 0, v176
	v_lshlrev_b64 v[222:223], 11, v[184:185]
	v_lshlrev_b64 v[180:181], 1, v[178:179]
	v_lshl_add_u64 v[218:219], s[70:71], 0, v[218:219]
	v_lshl_add_u64 v[224:225], s[8:9], 0, v[222:223]
	v_lshl_add_u64 v[216:217], v[218:219], 0, v[216:217]
	v_lshl_add_u64 v[218:219], v[224:225], 0, v[180:181]
	v_lshl_add_u64 v[222:223], s[72:73], 0, v[222:223]
	v_lshl_add_u64 v[222:223], v[222:223], 0, v[180:181]
	s_waitcnt vmcnt(15)
	v_pk_add_f32 v[148:149], v[148:149], v[200:201]
	s_waitcnt vmcnt(14)
	v_pk_add_f32 v[144:145], v[144:145], v[204:205]
	v_pk_add_f32 v[146:147], v[146:147], v[206:207]
	s_waitcnt vmcnt(13)
	v_pk_add_f32 v[140:141], v[140:141], v[208:209]
	v_mul_f32_e32 v176, v149, v149
	v_mul_f32_e32 v206, v145, v145
	v_pk_add_f32 v[150:151], v[150:151], v[202:203]
	s_waitcnt vmcnt(12)
	v_pk_add_f32 v[116:117], v[116:117], v[212:213]
	v_mul_f32_e32 v212, v141, v141
	v_pk_fma_f32 v[226:227], v[148:149], v[148:149], v[176:177] op_sel_hi:[1,1,0]
	v_pk_fma_f32 v[206:207], v[144:145], v[144:145], v[206:207] op_sel_hi:[1,1,0]
	v_pk_add_f32 v[142:143], v[142:143], v[210:211]
	v_mul_f32_e32 v202, v151, v151
	v_mul_f32_e32 v208, v147, v147
	v_pk_fma_f32 v[212:213], v[140:141], v[140:141], v[212:213] op_sel_hi:[1,1,0]
	v_pk_fma_f32 v[226:227], v[150:151], v[150:151], v[226:227]
	v_pk_fma_f32 v[206:207], v[146:147], v[146:147], v[206:207]
	v_mul_f32_e32 v224, v143, v143
	v_pk_fma_f32 v[212:213], v[142:143], v[142:143], v[212:213]
	v_pk_add_f32 v[202:203], v[202:203], v[226:227] op_sel_hi:[0,1]
	v_pk_add_f32 v[206:207], v[208:209], v[206:207] op_sel_hi:[0,1]
	v_pk_add_f32 v[208:209], v[224:225], v[212:213] op_sel_hi:[0,1]
	v_pk_add_f32 v[202:203], v[202:203], v[206:207]
	v_cvt_pk_bf16_f32 v200, v148, v149
	v_cvt_pk_bf16_f32 v201, v150, v151
	v_cvt_pk_bf16_f32 v204, v144, v145
	v_cvt_pk_bf16_f32 v205, v146, v147
	v_cvt_pk_bf16_f32 v210, v140, v141
	v_cvt_pk_bf16_f32 v211, v142, v143
	s_nop 0
	v_pk_add_f32 v[202:203], v[202:203], v[208:209]
	v_pk_add_f32 v[118:119], v[118:119], v[214:215]
	global_store_dwordx4 v[216:217], v[148:151], off
	global_store_dwordx2 v[218:219], v[200:201], off
	global_store_dwordx4 v[216:217], v[144:147], off offset:64
	s_nop 1
	v_add_co_u32_e64 v144, s[0:1], s24, v222
	s_nop 1
	v_addc_co_u32_e64 v145, s[0:1], 0, v223, s[0:1]
	global_store_dwordx2 v[144:145], v[204:205], off offset:32
	global_store_dwordx4 v[216:217], v[140:143], off offset:128
	global_store_dwordx2 v[144:145], v[210:211], off offset:64
	global_store_dwordx4 v[216:217], v[116:119], off offset:192
	v_cvt_pk_bf16_f32 v140, v116, v117
	v_cvt_pk_bf16_f32 v141, v118, v119
	global_store_dwordx2 v[144:145], v[140:141], off offset:96
	v_mul_f32_e32 v140, v117, v117
	v_pk_fma_f32 v[116:117], v[116:117], v[116:117], v[140:141] op_sel_hi:[1,1,0]
	s_nop 0
	v_pk_fma_f32 v[116:117], v[118:119], v[118:119], v[116:117]
	v_mul_f32_e32 v118, v119, v119
	v_pk_add_f32 v[116:117], v[118:119], v[116:117] op_sel_hi:[0,1]
	v_pk_add_f32 v[116:117], v[202:203], v[116:117]
	s_nop 0
	v_mov_b32_e32 v117, v116
	s_nop 1
	v_permlane32_swap_b32_e32 v116, v117
	v_add_f32_e32 v116, v116, v117
	v_mov_b32_e32 v117, v116
	s_nop 1
	v_permlane16_swap_b32_e32 v116, v117
	s_and_saveexec_b64 s[0:1], vcc
	s_cbranch_execz .LBB0_1798
	v_lshl_add_u64 v[118:119], v[184:185], 2, s[10:11]
	v_add_f32_e32 v116, v116, v117
	global_atomic_add_f32 v[118:119], v116, off
